# K-loops: one static s_setprio 1 for waves 4-7 at loop entry, per-phase priority flips deleted, reset at loop exit
# speedup vs baseline: 1.0129x; 1.0129x over previous
.LBB0_56:
	s_ashr_i32 s37, s36, 31
	v_cmp_lt_i64_e32 vcc, s[40:41], v[150:151]
	s_lshl_b64 s[40:41], s[36:37], 19
	s_add_u32 s40, s52, s40
	s_addc_u32 s41, s53, s41
	s_and_b64 s[44:45], vcc, exec
	s_cselect_b32 s37, s41, s1
	s_cselect_b32 s60, s40, s0
	s_ashr_i32 s35, s34, 31
	s_lshl_b64 s[44:45], s[34:35], 19
	s_add_u32 s44, s19, s44
	s_addc_u32 s45, s24, s45
	s_and_b64 s[48:49], vcc, exec
	s_cselect_b32 s35, s45, s23
	s_cselect_b32 s61, s44, s22
	s_add_u32 s0, s0, 0x40080
	s_addc_u32 s1, s1, 0
	s_add_u32 s62, s22, 0x100
	s_addc_u32 s63, s23, 0
	s_mov_b32 s64, -2
	v_mov_b64_e32 v[82:83], 0
	v_mov_b64_e32 v[84:85], 0
	s_nop 1
	v_mfma_f32_32x32x16_bf16 v[2:17], v[82:85], v[82:85], 0
	v_mov_b64_e32 v[114:115], 0
	v_mov_b64_e32 v[116:117], 0
	v_mov_b64_e32 v[118:119], 0
	v_mov_b64_e32 v[120:121], 0
	v_mov_b64_e32 v[122:123], 0
	v_mfma_f32_32x32x16_bf16 v[18:33], v[82:85], v[82:85], 0
	v_mov_b64_e32 v[124:125], 0
	v_mov_b64_e32 v[126:127], 0
	v_mov_b64_e32 v[128:129], 0
	v_mov_b64_e32 v[98:99], 0
	v_mov_b64_e32 v[100:101], 0
	v_mfma_f32_32x32x16_bf16 v[34:49], v[82:85], v[82:85], 0
	v_mov_b64_e32 v[102:103], 0
	v_mov_b64_e32 v[104:105], 0
	v_mov_b64_e32 v[106:107], 0
	v_mov_b64_e32 v[108:109], 0
	v_mov_b64_e32 v[110:111], 0
	v_mfma_f32_32x32x16_bf16 v[50:65], v[82:85], v[82:85], 0
	v_mov_b64_e32 v[112:113], 0
	v_mov_b64_e32 v[86:87], 0
	v_mov_b64_e32 v[88:89], 0
	v_mov_b64_e32 v[90:91], 0
	v_mov_b64_e32 v[92:93], 0
	v_mfma_f32_32x32x16_bf16 v[66:81], v[82:85], v[82:85], 0
	v_mov_b64_e32 v[94:95], 0
	v_mov_b64_e32 v[96:97], 0
	v_readfirstlane_b32 s98, v204
	s_lshr_b32 s98, s98, 8
	s_cmp_eq_u32 s98, 0
	s_cbranch_scc1 .Lkprio_5
	s_setprio 1
.Lkprio_5:
.LBB0_57:
	s_add_u32 s22, s0, 0xfffc0080
	s_addc_u32 s23, s1, -1
	s_add_i32 s65, 0, 0x10000
	v_add_u32_e32 v142, s65, v178
	ds_read_b128 v[130:133], v142
	ds_read_b128 v[134:137], v142 offset:1024
	ds_read_b128 v[138:141], v142 offset:2048
	ds_read_b128 v[142:145], v142 offset:3072
	s_cmp_eq_u32 s64, 12
	s_cselect_b32 s49, s37, s23
	s_cselect_b32 s48, s60, s22
	s_cselect_b32 s23, s35, s63
	s_cselect_b32 s22, s61, s62
	v_lshl_add_u64 v[186:187], s[0:1], 0, v[168:169]
	s_add_i32 m0, s47, 0xc000
	ds_read_b128 v[172:175], v180
	ds_read_b128 v[182:185], v180 offset:1024
	ds_read_b128 v[206:209], v180 offset:2048
	ds_read_b128 v[210:213], v180 offset:3072
	ds_read_b128 v[214:217], v180 offset:4096
	ds_read_b128 v[218:221], v180 offset:5120
	ds_read_b128 v[222:225], v180 offset:6144
	ds_read_b128 v[226:229], v180 offset:7168
	global_load_lds_dwordx4 v[186:187], off
	v_lshl_add_u64 v[186:187], s[0:1], 0, v[170:171]
	s_add_i32 m0, s47, 0xe000
	s_nop 0
	global_load_lds_dwordx4 v[186:187], off
	s_waitcnt lgkmcnt(8)
	s_barrier
	s_waitcnt lgkmcnt(0)
	v_mfma_f32_16x16x32_bf16 v[126:129], v[130:133], v[172:175], v[126:129]
	v_mfma_f32_16x16x32_bf16 v[122:125], v[138:141], v[172:175], v[122:125]
	v_mfma_f32_16x16x32_bf16 v[114:117], v[130:133], v[206:209], v[114:117]
	v_mfma_f32_16x16x32_bf16 v[106:109], v[138:141], v[206:209], v[106:109]
	v_mfma_f32_16x16x32_bf16 v[98:101], v[130:133], v[214:217], v[98:101]
	v_mfma_f32_16x16x32_bf16 v[90:93], v[138:141], v[214:217], v[90:93]
	v_mfma_f32_16x16x32_bf16 v[82:85], v[130:133], v[222:225], v[82:85]
	v_mfma_f32_16x16x32_bf16 v[74:77], v[138:141], v[222:225], v[74:77]
	v_mfma_f32_16x16x32_bf16 v[126:129], v[134:137], v[182:185], v[126:129]
	v_mfma_f32_16x16x32_bf16 v[122:125], v[142:145], v[182:185], v[122:125]
	v_mfma_f32_16x16x32_bf16 v[114:117], v[134:137], v[210:213], v[114:117]
	v_mfma_f32_16x16x32_bf16 v[106:109], v[142:145], v[210:213], v[106:109]
	v_mfma_f32_16x16x32_bf16 v[98:101], v[134:137], v[218:221], v[98:101]
	v_mfma_f32_16x16x32_bf16 v[90:93], v[142:145], v[218:221], v[90:93]
	v_mfma_f32_16x16x32_bf16 v[82:85], v[134:137], v[226:229], v[82:85]
	v_mfma_f32_16x16x32_bf16 v[74:77], v[142:145], v[226:229], v[74:77]
	s_barrier
	s_add_i32 s68, 0, 0x14000
	s_add_i32 s65, s65, s27
	v_add_u32_e32 v181, s68, v178
	v_lshl_add_u64 v[186:187], s[22:23], 0, v[0:1]
	s_mov_b32 m0, s65
	ds_read_b128 v[230:233], v181
	ds_read_b128 v[234:237], v181 offset:1024
	ds_read_b128 v[238:241], v181 offset:2048
	ds_read_b128 v[242:245], v181 offset:3072
	global_load_lds_dwordx4 v[186:187], off
	v_lshl_add_u64 v[246:247], s[22:23], 0, v[166:167]
	s_add_i32 m0, s65, 0x2000
	s_nop 0
	global_load_lds_dwordx4 v[246:247], off
	s_barrier
	s_waitcnt lgkmcnt(0)
	v_mfma_f32_16x16x32_bf16 v[118:121], v[230:233], v[172:175], v[118:121]
	v_mfma_f32_16x16x32_bf16 v[110:113], v[238:241], v[172:175], v[110:113]
	v_mfma_f32_16x16x32_bf16 v[102:105], v[230:233], v[206:209], v[102:105]
	v_mfma_f32_16x16x32_bf16 v[94:97], v[238:241], v[206:209], v[94:97]
	v_mfma_f32_16x16x32_bf16 v[86:89], v[230:233], v[214:217], v[86:89]
	v_mfma_f32_16x16x32_bf16 v[78:81], v[238:241], v[214:217], v[78:81]
	v_mfma_f32_16x16x32_bf16 v[70:73], v[230:233], v[222:225], v[70:73]
	v_mfma_f32_16x16x32_bf16 v[66:69], v[238:241], v[222:225], v[66:69]
	v_mfma_f32_16x16x32_bf16 v[118:121], v[234:237], v[182:185], v[118:121]
	v_mfma_f32_16x16x32_bf16 v[110:113], v[242:245], v[182:185], v[110:113]
	v_mfma_f32_16x16x32_bf16 v[102:105], v[234:237], v[210:213], v[102:105]
	v_mfma_f32_16x16x32_bf16 v[94:97], v[242:245], v[210:213], v[94:97]
	v_mfma_f32_16x16x32_bf16 v[86:89], v[234:237], v[218:221], v[86:89]
	v_mfma_f32_16x16x32_bf16 v[78:81], v[242:245], v[218:221], v[78:81]
	v_mfma_f32_16x16x32_bf16 v[70:73], v[234:237], v[226:229], v[70:73]
	v_mfma_f32_16x16x32_bf16 v[66:69], v[242:245], v[226:229], v[66:69]
	s_barrier
	s_mov_b32 m0, s47
	v_lshl_add_u64 v[248:249], s[48:49], 0, v[162:163]
	ds_read_b128 v[172:175], v180 offset:16384
	ds_read_b128 v[182:185], v180 offset:17408
	ds_read_b128 v[206:209], v180 offset:18432
	ds_read_b128 v[210:213], v180 offset:19456
	ds_read_b128 v[214:217], v180 offset:20480
	ds_read_b128 v[218:221], v180 offset:21504
	ds_read_b128 v[222:225], v180 offset:22528
	ds_read_b128 v[226:229], v180 offset:23552
	global_load_lds_dwordx4 v[248:249], off
	v_lshl_add_u64 v[250:251], s[48:49], 0, v[164:165]
	s_mov_b32 m0, s50
	s_nop 0
	global_load_lds_dwordx4 v[250:251], off
	s_barrier
	s_waitcnt lgkmcnt(0)
	v_mfma_f32_16x16x32_bf16 v[62:65], v[130:133], v[172:175], v[62:65]
	v_mfma_f32_16x16x32_bf16 v[58:61], v[138:141], v[172:175], v[58:61]
	v_mfma_f32_16x16x32_bf16 v[50:53], v[130:133], v[206:209], v[50:53]
	v_mfma_f32_16x16x32_bf16 v[42:45], v[138:141], v[206:209], v[42:45]
	v_mfma_f32_16x16x32_bf16 v[34:37], v[130:133], v[214:217], v[34:37]
	v_mfma_f32_16x16x32_bf16 v[26:29], v[138:141], v[214:217], v[26:29]
	v_mfma_f32_16x16x32_bf16 v[18:21], v[130:133], v[222:225], v[18:21]
	v_mfma_f32_16x16x32_bf16 v[10:13], v[138:141], v[222:225], v[10:13]
	v_mfma_f32_16x16x32_bf16 v[62:65], v[134:137], v[182:185], v[62:65]
	v_mfma_f32_16x16x32_bf16 v[58:61], v[142:145], v[182:185], v[58:61]
	v_mfma_f32_16x16x32_bf16 v[50:53], v[134:137], v[210:213], v[50:53]
	v_mfma_f32_16x16x32_bf16 v[42:45], v[142:145], v[210:213], v[42:45]
	v_mfma_f32_16x16x32_bf16 v[34:37], v[134:137], v[218:221], v[34:37]
	v_mfma_f32_16x16x32_bf16 v[26:29], v[142:145], v[218:221], v[26:29]
	v_mfma_f32_16x16x32_bf16 v[18:21], v[134:137], v[226:229], v[18:21]
	v_mfma_f32_16x16x32_bf16 v[10:13], v[142:145], v[226:229], v[10:13]
	s_barrier
	s_add_u32 s66, s22, 0x40000
	s_addc_u32 s67, s23, 0
	s_add_i32 s65, s68, s27
	v_lshl_add_u64 v[130:131], s[66:67], 0, v[0:1]
	s_mov_b32 m0, s65
	s_nop 0
	global_load_lds_dwordx4 v[130:131], off
	v_lshl_add_u64 v[130:131], s[66:67], 0, v[166:167]
	s_add_i32 m0, s65, 0x2000
	s_nop 0
	global_load_lds_dwordx4 v[130:131], off
	s_waitcnt vmcnt(6)
	s_barrier
	v_mfma_f32_16x16x32_bf16 v[54:57], v[230:233], v[172:175], v[54:57]
	v_mfma_f32_16x16x32_bf16 v[46:49], v[238:241], v[172:175], v[46:49]
	v_mfma_f32_16x16x32_bf16 v[38:41], v[230:233], v[206:209], v[38:41]
	v_mfma_f32_16x16x32_bf16 v[30:33], v[238:241], v[206:209], v[30:33]
	v_mfma_f32_16x16x32_bf16 v[22:25], v[230:233], v[214:217], v[22:25]
	v_mfma_f32_16x16x32_bf16 v[14:17], v[238:241], v[214:217], v[14:17]
	v_mfma_f32_16x16x32_bf16 v[6:9], v[230:233], v[222:225], v[6:9]
	v_mfma_f32_16x16x32_bf16 v[2:5], v[238:241], v[222:225], v[2:5]
	v_mfma_f32_16x16x32_bf16 v[54:57], v[234:237], v[182:185], v[54:57]
	v_mfma_f32_16x16x32_bf16 v[46:49], v[242:245], v[182:185], v[46:49]
	v_mfma_f32_16x16x32_bf16 v[38:41], v[234:237], v[210:213], v[38:41]
	v_mfma_f32_16x16x32_bf16 v[30:33], v[242:245], v[210:213], v[30:33]
	v_mfma_f32_16x16x32_bf16 v[22:25], v[234:237], v[218:221], v[22:25]
	v_mfma_f32_16x16x32_bf16 v[14:17], v[242:245], v[218:221], v[14:17]
	v_mfma_f32_16x16x32_bf16 v[6:9], v[234:237], v[226:229], v[6:9]
	v_mfma_f32_16x16x32_bf16 v[2:5], v[242:245], v[226:229], v[2:5]
	s_barrier
	s_add_i32 s65, 0, 0x18000
	v_add_u32_e32 v142, s65, v178
	ds_read_b128 v[130:133], v142
	ds_read_b128 v[134:137], v142 offset:1024
	ds_read_b128 v[138:141], v142 offset:2048
	ds_read_b128 v[142:145], v142 offset:3072
	s_add_u32 s48, s48, 0x40000
	s_addc_u32 s49, s49, 0
	s_mov_b32 m0, s51
	v_lshl_add_u64 v[230:231], s[48:49], 0, v[162:163]
	ds_read_b128 v[172:175], v180 offset:32768
	ds_read_b128 v[182:185], v180 offset:33792
	ds_read_b128 v[206:209], v180 offset:34816
	ds_read_b128 v[210:213], v180 offset:35840
	ds_read_b128 v[214:217], v180 offset:36864
	ds_read_b128 v[218:221], v180 offset:37888
	ds_read_b128 v[222:225], v180 offset:38912
	ds_read_b128 v[226:229], v180 offset:39936
	global_load_lds_dwordx4 v[230:231], off
	v_lshl_add_u64 v[230:231], s[48:49], 0, v[164:165]
	s_mov_b32 m0, s54
	s_nop 0
	global_load_lds_dwordx4 v[230:231], off
	s_waitcnt lgkmcnt(8)
	s_barrier
	s_waitcnt lgkmcnt(0)
	v_mfma_f32_16x16x32_bf16 v[126:129], v[130:133], v[172:175], v[126:129]
	v_mfma_f32_16x16x32_bf16 v[122:125], v[138:141], v[172:175], v[122:125]
	v_mfma_f32_16x16x32_bf16 v[114:117], v[130:133], v[206:209], v[114:117]
	v_mfma_f32_16x16x32_bf16 v[106:109], v[138:141], v[206:209], v[106:109]
	v_mfma_f32_16x16x32_bf16 v[98:101], v[130:133], v[214:217], v[98:101]
	v_mfma_f32_16x16x32_bf16 v[90:93], v[138:141], v[214:217], v[90:93]
	v_mfma_f32_16x16x32_bf16 v[82:85], v[130:133], v[222:225], v[82:85]
	v_mfma_f32_16x16x32_bf16 v[74:77], v[138:141], v[222:225], v[74:77]
	v_mfma_f32_16x16x32_bf16 v[126:129], v[134:137], v[182:185], v[126:129]
	v_mfma_f32_16x16x32_bf16 v[122:125], v[142:145], v[182:185], v[122:125]
	v_mfma_f32_16x16x32_bf16 v[114:117], v[134:137], v[210:213], v[114:117]
	v_mfma_f32_16x16x32_bf16 v[106:109], v[142:145], v[210:213], v[106:109]
	v_mfma_f32_16x16x32_bf16 v[98:101], v[134:137], v[218:221], v[98:101]
	v_mfma_f32_16x16x32_bf16 v[90:93], v[142:145], v[218:221], v[90:93]
	v_mfma_f32_16x16x32_bf16 v[82:85], v[134:137], v[226:229], v[82:85]
	v_mfma_f32_16x16x32_bf16 v[74:77], v[142:145], v[226:229], v[74:77]
	s_barrier
	s_add_i32 s48, 0, 0x1c000
	s_add_i32 s49, s65, s27
	v_add_u32_e32 v181, s48, v178
	v_lshl_add_u64 v[186:187], v[186:187], 0, s[94:95]
	s_mov_b32 m0, s49
	ds_read_b128 v[230:233], v181
	ds_read_b128 v[234:237], v181 offset:1024
	ds_read_b128 v[238:241], v181 offset:2048
	ds_read_b128 v[242:245], v181 offset:3072
	global_load_lds_dwordx4 v[186:187], off
	v_lshl_add_u64 v[186:187], v[246:247], 0, s[94:95]
	s_add_i32 m0, s49, 0x2000
	s_nop 0
	global_load_lds_dwordx4 v[186:187], off
	s_barrier
	s_waitcnt lgkmcnt(0)
	v_mfma_f32_16x16x32_bf16 v[118:121], v[230:233], v[172:175], v[118:121]
	v_mfma_f32_16x16x32_bf16 v[110:113], v[238:241], v[172:175], v[110:113]
	v_mfma_f32_16x16x32_bf16 v[102:105], v[230:233], v[206:209], v[102:105]
	v_mfma_f32_16x16x32_bf16 v[94:97], v[238:241], v[206:209], v[94:97]
	v_mfma_f32_16x16x32_bf16 v[86:89], v[230:233], v[214:217], v[86:89]
	v_mfma_f32_16x16x32_bf16 v[78:81], v[238:241], v[214:217], v[78:81]
	v_mfma_f32_16x16x32_bf16 v[70:73], v[230:233], v[222:225], v[70:73]
	v_mfma_f32_16x16x32_bf16 v[66:69], v[238:241], v[222:225], v[66:69]
	v_mfma_f32_16x16x32_bf16 v[118:121], v[234:237], v[182:185], v[118:121]
	v_mfma_f32_16x16x32_bf16 v[110:113], v[242:245], v[182:185], v[110:113]
	v_mfma_f32_16x16x32_bf16 v[102:105], v[234:237], v[210:213], v[102:105]
	v_mfma_f32_16x16x32_bf16 v[94:97], v[242:245], v[210:213], v[94:97]
	v_mfma_f32_16x16x32_bf16 v[86:89], v[234:237], v[218:221], v[86:89]
	v_mfma_f32_16x16x32_bf16 v[78:81], v[242:245], v[218:221], v[78:81]
	v_mfma_f32_16x16x32_bf16 v[70:73], v[234:237], v[226:229], v[70:73]
	v_mfma_f32_16x16x32_bf16 v[66:69], v[242:245], v[226:229], v[66:69]
	s_barrier
	s_mov_b32 m0, s55
	v_lshl_add_u64 v[186:187], v[248:249], 0, s[94:95]
	ds_read_b128 v[172:175], v180 offset:49152
	ds_read_b128 v[182:185], v180 offset:50176
	ds_read_b128 v[206:209], v180 offset:51200
	ds_read_b128 v[210:213], v180 offset:52224
	ds_read_b128 v[214:217], v180 offset:53248
	ds_read_b128 v[218:221], v180 offset:54272
	ds_read_b128 v[222:225], v180 offset:55296
	ds_read_b128 v[226:229], v180 offset:56320
	global_load_lds_dwordx4 v[186:187], off
	v_lshl_add_u64 v[186:187], v[250:251], 0, s[94:95]
	s_mov_b32 m0, s56
	s_nop 0
	global_load_lds_dwordx4 v[186:187], off
	s_barrier
	s_waitcnt lgkmcnt(0)
	v_mfma_f32_16x16x32_bf16 v[62:65], v[130:133], v[172:175], v[62:65]
	v_mfma_f32_16x16x32_bf16 v[58:61], v[138:141], v[172:175], v[58:61]
	v_mfma_f32_16x16x32_bf16 v[50:53], v[130:133], v[206:209], v[50:53]
	v_mfma_f32_16x16x32_bf16 v[42:45], v[138:141], v[206:209], v[42:45]
	v_mfma_f32_16x16x32_bf16 v[34:37], v[130:133], v[214:217], v[34:37]
	v_mfma_f32_16x16x32_bf16 v[26:29], v[138:141], v[214:217], v[26:29]
	v_mfma_f32_16x16x32_bf16 v[18:21], v[130:133], v[222:225], v[18:21]
	v_mfma_f32_16x16x32_bf16 v[10:13], v[138:141], v[222:225], v[10:13]
	v_mfma_f32_16x16x32_bf16 v[62:65], v[134:137], v[182:185], v[62:65]
	v_mfma_f32_16x16x32_bf16 v[58:61], v[142:145], v[182:185], v[58:61]
	v_mfma_f32_16x16x32_bf16 v[50:53], v[134:137], v[210:213], v[50:53]
	v_mfma_f32_16x16x32_bf16 v[42:45], v[142:145], v[210:213], v[42:45]
	v_mfma_f32_16x16x32_bf16 v[34:37], v[134:137], v[218:221], v[34:37]
	v_mfma_f32_16x16x32_bf16 v[26:29], v[142:145], v[218:221], v[26:29]
	v_mfma_f32_16x16x32_bf16 v[18:21], v[134:137], v[226:229], v[18:21]
	v_mfma_f32_16x16x32_bf16 v[10:13], v[142:145], v[226:229], v[10:13]
	s_barrier
	s_add_u32 s22, s22, 0x40080
	s_addc_u32 s23, s23, 0
	s_add_i32 s48, s48, s27
	v_lshl_add_u64 v[130:131], s[22:23], 0, v[0:1]
	s_mov_b32 m0, s48
	s_nop 0
	global_load_lds_dwordx4 v[130:131], off
	v_lshl_add_u64 v[130:131], s[22:23], 0, v[166:167]
	s_add_i32 m0, s48, 0x2000
	s_nop 0
	global_load_lds_dwordx4 v[130:131], off
	s_waitcnt vmcnt(6)
	s_barrier
	v_mfma_f32_16x16x32_bf16 v[54:57], v[230:233], v[172:175], v[54:57]
	v_mfma_f32_16x16x32_bf16 v[46:49], v[238:241], v[172:175], v[46:49]
	v_mfma_f32_16x16x32_bf16 v[38:41], v[230:233], v[206:209], v[38:41]
	v_mfma_f32_16x16x32_bf16 v[30:33], v[238:241], v[206:209], v[30:33]
	v_mfma_f32_16x16x32_bf16 v[22:25], v[230:233], v[214:217], v[22:25]
	v_mfma_f32_16x16x32_bf16 v[14:17], v[238:241], v[214:217], v[14:17]
	v_mfma_f32_16x16x32_bf16 v[6:9], v[230:233], v[222:225], v[6:9]
	v_mfma_f32_16x16x32_bf16 v[2:5], v[238:241], v[222:225], v[2:5]
	v_mfma_f32_16x16x32_bf16 v[54:57], v[234:237], v[182:185], v[54:57]
	v_mfma_f32_16x16x32_bf16 v[46:49], v[242:245], v[182:185], v[46:49]
	v_mfma_f32_16x16x32_bf16 v[38:41], v[234:237], v[210:213], v[38:41]
	v_mfma_f32_16x16x32_bf16 v[30:33], v[242:245], v[210:213], v[30:33]
	v_mfma_f32_16x16x32_bf16 v[22:25], v[234:237], v[218:221], v[22:25]
	v_mfma_f32_16x16x32_bf16 v[14:17], v[242:245], v[218:221], v[14:17]
	v_mfma_f32_16x16x32_bf16 v[6:9], v[234:237], v[226:229], v[6:9]
	v_mfma_f32_16x16x32_bf16 v[2:5], v[242:245], v[226:229], v[2:5]
	s_barrier
	s_add_i32 s64, s64, 2
	s_add_u32 s0, s0, 0x100
	s_addc_u32 s1, s1, 0
	s_add_u32 s62, s62, 0x100
	s_addc_u32 s63, s63, 0
	s_cmp_gt_u32 s64, 13
	s_cbranch_scc0 .LBB0_57
	s_setprio 0
	v_lshl_or_b32 v172, s59, 8, v179
	v_ashrrev_i32_e32 v173, 31, v172
	v_cndmask_b32_e64 v131, 0, 1, s[2:3]
	v_lshl_add_u64 v[174:175], v[172:173], 2, s[8:9]
	v_mov_b32_e32 v130, 0
	v_cmp_ne_u32_e64 s[0:1], 1, v131
	s_andn2_b64 vcc, exec, s[2:3]
	v_mov_b32_e32 v134, 0
	v_mov_b32_e32 v135, 0
	v_mov_b32_e32 v136, 0
	v_mov_b32_e32 v137, 0
	s_cbranch_vccnz .LBB0_60
	global_load_dwordx4 v[134:137], v[174:175], off

.LBB0_94:
	s_ashr_i32 s49, s48, 31
	s_lshl_b64 s[26:27], s[48:49], 19
	s_add_u32 s50, s14, s26
	v_cmp_lt_i64_e32 vcc, s[28:29], v[152:153]
	s_addc_u32 s51, s15, s27
	s_and_b64 s[26:27], vcc, exec
	s_cselect_b32 s25, s51, s9
	s_cselect_b32 s26, s50, s8
	s_ashr_i32 s47, s46, 31
	s_lshl_b64 s[28:29], s[46:47], 19
	s_add_u32 s54, s19, s28
	s_addc_u32 s55, s34, s29
	s_and_b64 s[28:29], vcc, exec
	s_cselect_b32 s27, s55, s23
	s_cselect_b32 s30, s54, s22
	s_add_u32 s8, s8, 0x40080
	s_addc_u32 s9, s9, 0
	s_add_u32 s31, s22, 0x100
	s_addc_u32 s47, s23, 0
	s_mov_b32 s49, -2
	v_mov_b64_e32 v[50:51], 0
	v_mov_b64_e32 v[52:53], 0
	s_nop 1
	v_mfma_f32_32x32x16_bf16 v[2:17], v[50:53], v[50:53], 0
	v_mov_b64_e32 v[54:55], 0
	v_mov_b64_e32 v[56:57], 0
	v_mov_b64_e32 v[62:63], 0
	v_mov_b64_e32 v[64:65], 0
	v_mov_b64_e32 v[70:71], 0
	v_mfma_f32_32x32x16_bf16 v[18:33], v[50:53], v[50:53], 0
	v_mov_b64_e32 v[72:73], 0
	v_mov_b64_e32 v[130:131], 0
	v_mov_b64_e32 v[132:133], 0
	v_mov_b64_e32 v[134:135], 0
	v_mov_b64_e32 v[136:137], 0
	v_mfma_f32_32x32x16_bf16 v[34:49], v[50:53], v[50:53], 0
	v_mov_b64_e32 v[138:139], 0
	v_mov_b64_e32 v[140:141], 0
	v_mov_b64_e32 v[142:143], 0
	v_mov_b64_e32 v[144:145], 0
	v_mov_b64_e32 v[114:115], 0
	v_mfma_f32_32x32x16_bf16 v[82:97], v[50:53], v[50:53], 0
	v_mov_b64_e32 v[116:117], 0
	v_mov_b64_e32 v[118:119], 0
	v_mov_b64_e32 v[120:121], 0
	v_mov_b64_e32 v[122:123], 0
	v_mov_b64_e32 v[124:125], 0
	v_mfma_f32_32x32x16_bf16 v[98:113], v[50:53], v[50:53], 0
	v_mov_b64_e32 v[126:127], 0
	v_mov_b64_e32 v[128:129], 0
	v_readfirstlane_b32 s98, v204
	s_lshr_b32 s98, s98, 8
	s_cmp_eq_u32 s98, 0
	s_cbranch_scc1 .Lkprio_4
	s_setprio 1
.Lkprio_4:
.LBB0_95:
	s_add_u32 s22, s8, 0xfffc0080
	s_addc_u32 s23, s9, -1
	s_add_i32 s63, 0, 0x10000
	v_add_u32_e32 v78, s63, v178
	ds_read_b128 v[58:61], v78
	ds_read_b128 v[66:69], v78 offset:1024
	ds_read_b128 v[74:77], v78 offset:2048
	ds_read_b128 v[78:81], v78 offset:3072
	s_cmp_eq_u32 s49, 12
	s_cselect_b32 s29, s25, s23
	s_cselect_b32 s28, s26, s22
	s_cselect_b32 s23, s27, s47
	s_cselect_b32 s22, s30, s31
	v_lshl_add_u64 v[186:187], s[8:9], 0, v[168:169]
	s_add_i32 m0, s3, 0xc000
	ds_read_b128 v[172:175], v180
	ds_read_b128 v[182:185], v180 offset:1024
	ds_read_b128 v[206:209], v180 offset:2048
	ds_read_b128 v[210:213], v180 offset:3072
	ds_read_b128 v[214:217], v180 offset:4096
	ds_read_b128 v[218:221], v180 offset:5120
	ds_read_b128 v[222:225], v180 offset:6144
	ds_read_b128 v[226:229], v180 offset:7168
	global_load_lds_dwordx4 v[186:187], off
	v_lshl_add_u64 v[186:187], s[8:9], 0, v[170:171]
	s_add_i32 m0, s3, 0xe000
	s_nop 0
	global_load_lds_dwordx4 v[186:187], off
	s_waitcnt lgkmcnt(8)
	s_barrier
	s_waitcnt lgkmcnt(0)
	v_mfma_f32_16x16x32_bf16 v[142:145], v[58:61], v[172:175], v[142:145]
	v_mfma_f32_16x16x32_bf16 v[138:141], v[74:77], v[172:175], v[138:141]
	v_mfma_f32_16x16x32_bf16 v[126:129], v[58:61], v[206:209], v[126:129]
	v_mfma_f32_16x16x32_bf16 v[118:121], v[74:77], v[206:209], v[118:121]
	v_mfma_f32_16x16x32_bf16 v[110:113], v[58:61], v[214:217], v[110:113]
	v_mfma_f32_16x16x32_bf16 v[102:105], v[74:77], v[214:217], v[102:105]
	v_mfma_f32_16x16x32_bf16 v[94:97], v[58:61], v[222:225], v[94:97]
	v_mfma_f32_16x16x32_bf16 v[86:89], v[74:77], v[222:225], v[86:89]
	v_mfma_f32_16x16x32_bf16 v[142:145], v[66:69], v[182:185], v[142:145]
	v_mfma_f32_16x16x32_bf16 v[138:141], v[78:81], v[182:185], v[138:141]
	v_mfma_f32_16x16x32_bf16 v[126:129], v[66:69], v[210:213], v[126:129]
	v_mfma_f32_16x16x32_bf16 v[118:121], v[78:81], v[210:213], v[118:121]
	v_mfma_f32_16x16x32_bf16 v[110:113], v[66:69], v[218:221], v[110:113]
	v_mfma_f32_16x16x32_bf16 v[102:105], v[78:81], v[218:221], v[102:105]
	v_mfma_f32_16x16x32_bf16 v[94:97], v[66:69], v[226:229], v[94:97]
	v_mfma_f32_16x16x32_bf16 v[86:89], v[78:81], v[226:229], v[86:89]
	s_barrier
	s_add_i32 s66, 0, 0x14000
	s_add_i32 s63, s63, s37
	v_add_u32_e32 v181, s66, v178
	v_lshl_add_u64 v[186:187], s[22:23], 0, v[0:1]
	s_mov_b32 m0, s63
	ds_read_b128 v[230:233], v181
	ds_read_b128 v[234:237], v181 offset:1024
	ds_read_b128 v[238:241], v181 offset:2048
	ds_read_b128 v[242:245], v181 offset:3072
	global_load_lds_dwordx4 v[186:187], off
	v_lshl_add_u64 v[246:247], s[22:23], 0, v[166:167]
	s_add_i32 m0, s63, 0x2000
	s_nop 0
	global_load_lds_dwordx4 v[246:247], off
	s_barrier
	s_waitcnt lgkmcnt(0)
	v_mfma_f32_16x16x32_bf16 v[134:137], v[230:233], v[172:175], v[134:137]
	v_mfma_f32_16x16x32_bf16 v[130:133], v[238:241], v[172:175], v[130:133]
	v_mfma_f32_16x16x32_bf16 v[122:125], v[230:233], v[206:209], v[122:125]
	v_mfma_f32_16x16x32_bf16 v[114:117], v[238:241], v[206:209], v[114:117]
	v_mfma_f32_16x16x32_bf16 v[106:109], v[230:233], v[214:217], v[106:109]
	v_mfma_f32_16x16x32_bf16 v[98:101], v[238:241], v[214:217], v[98:101]
	v_mfma_f32_16x16x32_bf16 v[90:93], v[230:233], v[222:225], v[90:93]
	v_mfma_f32_16x16x32_bf16 v[82:85], v[238:241], v[222:225], v[82:85]
	v_mfma_f32_16x16x32_bf16 v[134:137], v[234:237], v[182:185], v[134:137]
	v_mfma_f32_16x16x32_bf16 v[130:133], v[242:245], v[182:185], v[130:133]
	v_mfma_f32_16x16x32_bf16 v[122:125], v[234:237], v[210:213], v[122:125]
	v_mfma_f32_16x16x32_bf16 v[114:117], v[242:245], v[210:213], v[114:117]
	v_mfma_f32_16x16x32_bf16 v[106:109], v[234:237], v[218:221], v[106:109]
	v_mfma_f32_16x16x32_bf16 v[98:101], v[242:245], v[218:221], v[98:101]
	v_mfma_f32_16x16x32_bf16 v[90:93], v[234:237], v[226:229], v[90:93]
	v_mfma_f32_16x16x32_bf16 v[82:85], v[242:245], v[226:229], v[82:85]
	s_barrier
	s_mov_b32 m0, s3
	v_lshl_add_u64 v[248:249], s[28:29], 0, v[162:163]
	ds_read_b128 v[172:175], v180 offset:16384
	ds_read_b128 v[182:185], v180 offset:17408
	ds_read_b128 v[206:209], v180 offset:18432
	ds_read_b128 v[210:213], v180 offset:19456
	ds_read_b128 v[214:217], v180 offset:20480
	ds_read_b128 v[218:221], v180 offset:21504
	ds_read_b128 v[222:225], v180 offset:22528
	ds_read_b128 v[226:229], v180 offset:23552
	global_load_lds_dwordx4 v[248:249], off
	v_lshl_add_u64 v[250:251], s[28:29], 0, v[164:165]
	s_mov_b32 m0, s56
	s_nop 0
	global_load_lds_dwordx4 v[250:251], off
	s_barrier
	s_waitcnt lgkmcnt(0)
	v_mfma_f32_16x16x32_bf16 v[70:73], v[58:61], v[172:175], v[70:73]
	v_mfma_f32_16x16x32_bf16 v[54:57], v[74:77], v[172:175], v[54:57]
	v_mfma_f32_16x16x32_bf16 v[46:49], v[58:61], v[206:209], v[46:49]
	v_mfma_f32_16x16x32_bf16 v[38:41], v[74:77], v[206:209], v[38:41]
	v_mfma_f32_16x16x32_bf16 v[30:33], v[58:61], v[214:217], v[30:33]
	v_mfma_f32_16x16x32_bf16 v[22:25], v[74:77], v[214:217], v[22:25]
	v_mfma_f32_16x16x32_bf16 v[14:17], v[58:61], v[222:225], v[14:17]
	v_mfma_f32_16x16x32_bf16 v[6:9], v[74:77], v[222:225], v[6:9]
	v_mfma_f32_16x16x32_bf16 v[70:73], v[66:69], v[182:185], v[70:73]
	v_mfma_f32_16x16x32_bf16 v[54:57], v[78:81], v[182:185], v[54:57]
	v_mfma_f32_16x16x32_bf16 v[46:49], v[66:69], v[210:213], v[46:49]
	v_mfma_f32_16x16x32_bf16 v[38:41], v[78:81], v[210:213], v[38:41]
	v_mfma_f32_16x16x32_bf16 v[30:33], v[66:69], v[218:221], v[30:33]
	v_mfma_f32_16x16x32_bf16 v[22:25], v[78:81], v[218:221], v[22:25]
	v_mfma_f32_16x16x32_bf16 v[14:17], v[66:69], v[226:229], v[14:17]
	v_mfma_f32_16x16x32_bf16 v[6:9], v[78:81], v[226:229], v[6:9]
	s_barrier
	s_add_u32 s64, s22, 0x40000
	s_addc_u32 s65, s23, 0
	s_add_i32 s63, s66, s37
	v_lshl_add_u64 v[58:59], s[64:65], 0, v[0:1]
	s_mov_b32 m0, s63
	s_nop 0
	global_load_lds_dwordx4 v[58:59], off
	v_lshl_add_u64 v[58:59], s[64:65], 0, v[166:167]
	s_add_i32 m0, s63, 0x2000
	s_nop 0
	global_load_lds_dwordx4 v[58:59], off
	s_waitcnt vmcnt(6)
	s_barrier
	v_mfma_f32_16x16x32_bf16 v[50:53], v[238:241], v[172:175], v[50:53]
	v_mfma_f32_16x16x32_bf16 v[42:45], v[230:233], v[206:209], v[42:45]
	v_mfma_f32_16x16x32_bf16 v[34:37], v[238:241], v[206:209], v[34:37]
	v_mfma_f32_16x16x32_bf16 v[26:29], v[230:233], v[214:217], v[26:29]
	v_mfma_f32_16x16x32_bf16 v[18:21], v[238:241], v[214:217], v[18:21]
	v_mfma_f32_16x16x32_bf16 v[10:13], v[230:233], v[222:225], v[10:13]
	v_mfma_f32_16x16x32_bf16 v[2:5], v[238:241], v[222:225], v[2:5]
	v_mfma_f32_16x16x32_bf16 v[58:61], v[230:233], v[172:175], v[62:65]
	v_mfma_f32_16x16x32_bf16 v[50:53], v[242:245], v[182:185], v[50:53]
	v_mfma_f32_16x16x32_bf16 v[42:45], v[234:237], v[210:213], v[42:45]
	v_mfma_f32_16x16x32_bf16 v[34:37], v[242:245], v[210:213], v[34:37]
	v_mfma_f32_16x16x32_bf16 v[26:29], v[234:237], v[218:221], v[26:29]
	v_mfma_f32_16x16x32_bf16 v[18:21], v[242:245], v[218:221], v[18:21]
	v_mfma_f32_16x16x32_bf16 v[10:13], v[234:237], v[226:229], v[10:13]
	v_mfma_f32_16x16x32_bf16 v[2:5], v[242:245], v[226:229], v[2:5]
	v_mfma_f32_16x16x32_bf16 v[58:61], v[234:237], v[182:185], v[58:61]
	s_barrier
	s_add_i32 s63, 0, 0x18000
	v_add_u32_e32 v78, s63, v178
	ds_read_b128 v[62:65], v78
	ds_read_b128 v[66:69], v78 offset:1024
	ds_read_b128 v[74:77], v78 offset:2048
	ds_read_b128 v[78:81], v78 offset:3072
	s_add_u32 s28, s28, 0x40000
	s_addc_u32 s29, s29, 0
	s_mov_b32 m0, s57
	v_lshl_add_u64 v[230:231], s[28:29], 0, v[162:163]
	ds_read_b128 v[172:175], v180 offset:32768
	ds_read_b128 v[182:185], v180 offset:33792
	ds_read_b128 v[206:209], v180 offset:34816
	ds_read_b128 v[210:213], v180 offset:35840
	ds_read_b128 v[214:217], v180 offset:36864
	ds_read_b128 v[218:221], v180 offset:37888
	ds_read_b128 v[222:225], v180 offset:38912
	ds_read_b128 v[226:229], v180 offset:39936
	global_load_lds_dwordx4 v[230:231], off
	v_lshl_add_u64 v[230:231], s[28:29], 0, v[164:165]
	s_mov_b32 m0, s58
	s_nop 0
	global_load_lds_dwordx4 v[230:231], off
	s_waitcnt lgkmcnt(8)
	s_barrier
	s_waitcnt lgkmcnt(0)
	v_mfma_f32_16x16x32_bf16 v[142:145], v[62:65], v[172:175], v[142:145]
	v_mfma_f32_16x16x32_bf16 v[138:141], v[74:77], v[172:175], v[138:141]
	v_mfma_f32_16x16x32_bf16 v[126:129], v[62:65], v[206:209], v[126:129]
	v_mfma_f32_16x16x32_bf16 v[118:121], v[74:77], v[206:209], v[118:121]
	v_mfma_f32_16x16x32_bf16 v[110:113], v[62:65], v[214:217], v[110:113]
	v_mfma_f32_16x16x32_bf16 v[102:105], v[74:77], v[214:217], v[102:105]
	v_mfma_f32_16x16x32_bf16 v[94:97], v[62:65], v[222:225], v[94:97]
	v_mfma_f32_16x16x32_bf16 v[86:89], v[74:77], v[222:225], v[86:89]
	v_mfma_f32_16x16x32_bf16 v[142:145], v[66:69], v[182:185], v[142:145]
	v_mfma_f32_16x16x32_bf16 v[138:141], v[78:81], v[182:185], v[138:141]
	v_mfma_f32_16x16x32_bf16 v[126:129], v[66:69], v[210:213], v[126:129]
	v_mfma_f32_16x16x32_bf16 v[118:121], v[78:81], v[210:213], v[118:121]
	v_mfma_f32_16x16x32_bf16 v[110:113], v[66:69], v[218:221], v[110:113]
	v_mfma_f32_16x16x32_bf16 v[102:105], v[78:81], v[218:221], v[102:105]
	v_mfma_f32_16x16x32_bf16 v[94:97], v[66:69], v[226:229], v[94:97]
	v_mfma_f32_16x16x32_bf16 v[86:89], v[78:81], v[226:229], v[86:89]
	s_barrier
	s_add_i32 s28, 0, 0x1c000
	s_add_i32 s29, s63, s37
	v_add_u32_e32 v181, s28, v178
	v_lshl_add_u64 v[186:187], v[186:187], 0, s[94:95]
	s_mov_b32 m0, s29
	ds_read_b128 v[230:233], v181
	ds_read_b128 v[234:237], v181 offset:1024
	ds_read_b128 v[238:241], v181 offset:2048
	ds_read_b128 v[242:245], v181 offset:3072
	global_load_lds_dwordx4 v[186:187], off
	v_lshl_add_u64 v[186:187], v[246:247], 0, s[94:95]
	s_add_i32 m0, s29, 0x2000
	s_nop 0
	global_load_lds_dwordx4 v[186:187], off
	s_barrier
	s_waitcnt lgkmcnt(0)
	v_mfma_f32_16x16x32_bf16 v[134:137], v[230:233], v[172:175], v[134:137]
	v_mfma_f32_16x16x32_bf16 v[130:133], v[238:241], v[172:175], v[130:133]
	v_mfma_f32_16x16x32_bf16 v[122:125], v[230:233], v[206:209], v[122:125]
	v_mfma_f32_16x16x32_bf16 v[114:117], v[238:241], v[206:209], v[114:117]
	v_mfma_f32_16x16x32_bf16 v[106:109], v[230:233], v[214:217], v[106:109]
	v_mfma_f32_16x16x32_bf16 v[98:101], v[238:241], v[214:217], v[98:101]
	v_mfma_f32_16x16x32_bf16 v[90:93], v[230:233], v[222:225], v[90:93]
	v_mfma_f32_16x16x32_bf16 v[82:85], v[238:241], v[222:225], v[82:85]
	v_mfma_f32_16x16x32_bf16 v[134:137], v[234:237], v[182:185], v[134:137]
	v_mfma_f32_16x16x32_bf16 v[130:133], v[242:245], v[182:185], v[130:133]
	v_mfma_f32_16x16x32_bf16 v[122:125], v[234:237], v[210:213], v[122:125]
	v_mfma_f32_16x16x32_bf16 v[114:117], v[242:245], v[210:213], v[114:117]
	v_mfma_f32_16x16x32_bf16 v[106:109], v[234:237], v[218:221], v[106:109]
	v_mfma_f32_16x16x32_bf16 v[98:101], v[242:245], v[218:221], v[98:101]
	v_mfma_f32_16x16x32_bf16 v[90:93], v[234:237], v[226:229], v[90:93]
	v_mfma_f32_16x16x32_bf16 v[82:85], v[242:245], v[226:229], v[82:85]
	s_barrier
	s_mov_b32 m0, s59
	v_lshl_add_u64 v[186:187], v[248:249], 0, s[94:95]
	ds_read_b128 v[172:175], v180 offset:49152
	ds_read_b128 v[182:185], v180 offset:50176
	ds_read_b128 v[206:209], v180 offset:51200
	ds_read_b128 v[210:213], v180 offset:52224
	ds_read_b128 v[214:217], v180 offset:53248
	ds_read_b128 v[218:221], v180 offset:54272
	ds_read_b128 v[222:225], v180 offset:55296
	ds_read_b128 v[226:229], v180 offset:56320
	global_load_lds_dwordx4 v[186:187], off
	v_lshl_add_u64 v[186:187], v[250:251], 0, s[94:95]
	s_mov_b32 m0, s60
	s_nop 0
	global_load_lds_dwordx4 v[186:187], off
	s_barrier
	s_waitcnt lgkmcnt(0)
	v_mfma_f32_16x16x32_bf16 v[70:73], v[62:65], v[172:175], v[70:73]
	v_mfma_f32_16x16x32_bf16 v[54:57], v[74:77], v[172:175], v[54:57]
	v_mfma_f32_16x16x32_bf16 v[46:49], v[62:65], v[206:209], v[46:49]
	v_mfma_f32_16x16x32_bf16 v[38:41], v[74:77], v[206:209], v[38:41]
	v_mfma_f32_16x16x32_bf16 v[30:33], v[62:65], v[214:217], v[30:33]
	v_mfma_f32_16x16x32_bf16 v[22:25], v[74:77], v[214:217], v[22:25]
	v_mfma_f32_16x16x32_bf16 v[14:17], v[62:65], v[222:225], v[14:17]
	v_mfma_f32_16x16x32_bf16 v[6:9], v[74:77], v[222:225], v[6:9]
	v_mfma_f32_16x16x32_bf16 v[70:73], v[66:69], v[182:185], v[70:73]
	v_mfma_f32_16x16x32_bf16 v[54:57], v[78:81], v[182:185], v[54:57]
	v_mfma_f32_16x16x32_bf16 v[46:49], v[66:69], v[210:213], v[46:49]
	v_mfma_f32_16x16x32_bf16 v[38:41], v[78:81], v[210:213], v[38:41]
	v_mfma_f32_16x16x32_bf16 v[30:33], v[66:69], v[218:221], v[30:33]
	v_mfma_f32_16x16x32_bf16 v[22:25], v[78:81], v[218:221], v[22:25]
	v_mfma_f32_16x16x32_bf16 v[14:17], v[66:69], v[226:229], v[14:17]
	v_mfma_f32_16x16x32_bf16 v[6:9], v[78:81], v[226:229], v[6:9]
	s_barrier
	s_add_u32 s22, s22, 0x40080
	s_addc_u32 s23, s23, 0
	s_add_i32 s28, s28, s37
	v_lshl_add_u64 v[62:63], s[22:23], 0, v[0:1]
	s_mov_b32 m0, s28
	s_nop 0
	global_load_lds_dwordx4 v[62:63], off
	v_lshl_add_u64 v[62:63], s[22:23], 0, v[166:167]
	s_add_i32 m0, s28, 0x2000
	s_nop 0
	global_load_lds_dwordx4 v[62:63], off
	s_waitcnt vmcnt(6)
	s_barrier
	v_mfma_f32_16x16x32_bf16 v[58:61], v[230:233], v[172:175], v[58:61]
	v_mfma_f32_16x16x32_bf16 v[50:53], v[238:241], v[172:175], v[50:53]
	v_mfma_f32_16x16x32_bf16 v[42:45], v[230:233], v[206:209], v[42:45]
	v_mfma_f32_16x16x32_bf16 v[34:37], v[238:241], v[206:209], v[34:37]
	v_mfma_f32_16x16x32_bf16 v[26:29], v[230:233], v[214:217], v[26:29]
	v_mfma_f32_16x16x32_bf16 v[18:21], v[238:241], v[214:217], v[18:21]
	v_mfma_f32_16x16x32_bf16 v[10:13], v[230:233], v[222:225], v[10:13]
	v_mfma_f32_16x16x32_bf16 v[2:5], v[238:241], v[222:225], v[2:5]
	v_mfma_f32_16x16x32_bf16 v[62:65], v[234:237], v[182:185], v[58:61]
	v_mfma_f32_16x16x32_bf16 v[50:53], v[242:245], v[182:185], v[50:53]
	v_mfma_f32_16x16x32_bf16 v[42:45], v[234:237], v[210:213], v[42:45]
	v_mfma_f32_16x16x32_bf16 v[34:37], v[242:245], v[210:213], v[34:37]
	v_mfma_f32_16x16x32_bf16 v[26:29], v[234:237], v[218:221], v[26:29]
	v_mfma_f32_16x16x32_bf16 v[18:21], v[242:245], v[218:221], v[18:21]
	v_mfma_f32_16x16x32_bf16 v[10:13], v[234:237], v[226:229], v[10:13]
	v_mfma_f32_16x16x32_bf16 v[2:5], v[242:245], v[226:229], v[2:5]
	s_barrier
	s_add_i32 s49, s49, 2
	s_add_u32 s8, s8, 0x100
	s_addc_u32 s9, s9, 0
	s_add_u32 s31, s31, 0x100
	s_addc_u32 s47, s47, 0
	s_cmp_gt_u32 s49, 13
	s_cbranch_scc0 .LBB0_95
	s_setprio 0
	v_lshl_or_b32 v172, s24, 7, v179
	v_ashrrev_i32_e32 v173, 31, v172
	v_lshlrev_b64 v[58:59], 2, v[172:173]
	v_lshl_add_u64 v[60:61], s[40:41], 0, v[58:59]
	v_lshl_add_u64 v[74:75], s[44:45], 0, v[58:59]
	global_load_dwordx4 v[66:69], v[60:61], off offset:16
	global_load_dwordx4 v[78:81], v[60:61], off
	s_nop 0
	global_load_dwordx4 v[58:61], v[74:75], off offset:16
	s_nop 0
	global_load_dwordx4 v[74:77], v[74:75], off
	v_lshl_add_u32 v174, s2, 8, v177
	v_ashrrev_i32_e32 v175, 31, v174
	v_lshl_add_u64 v[172:173], v[172:173], 1, s[20:21]
	v_lshlrev_b64 v[182:183], 11, v[174:175]
	s_mov_b32 s2, 0x50000
	s_mov_b32 s24, s46
	s_mov_b64 s[22:23], s[54:55]
	s_mov_b64 s[8:9], s[50:51]
	s_waitcnt vmcnt(0)
	v_add_f32_e32 v138, v138, v66
	v_add_f32_e32 v126, v126, v78
	v_add_f32_e32 v130, v130, v58
	v_mul_f32_e32 v130, 0xbfb8aa3b, v130
	v_add_f32_e32 v131, v131, v59
	v_add_f32_e32 v122, v122, v74
	v_exp_f32_e32 v130, v130
	v_mul_f32_e32 v131, 0xbfb8aa3b, v131
	v_mul_f32_e32 v122, 0xbfb8aa3b, v122
	v_add_f32_e32 v123, v123, v75
	v_exp_f32_e32 v131, v131
	v_exp_f32_e32 v122, v122
	v_mul_f32_e32 v123, 0xbfb8aa3b, v123
	v_add_f32_e32 v124, v124, v76
	v_exp_f32_e32 v123, v123
	v_mul_f32_e32 v124, 0xbfb8aa3b, v124
	v_add_f32_e32 v125, v125, v77
	v_add_f32_e32 v114, v114, v58
	v_exp_f32_e32 v124, v124
	v_mul_f32_e32 v125, 0xbfb8aa3b, v125
	v_mul_f32_e32 v114, 0xbfb8aa3b, v114
	v_add_f32_e32 v115, v115, v59
	v_add_f32_e32 v106, v106, v74
	v_add_f32_e32 v130, 1.0, v130
	v_exp_f32_e32 v125, v125
	v_exp_f32_e32 v114, v114
	v_mul_f32_e32 v115, 0xbfb8aa3b, v115
	v_mul_f32_e32 v106, 0xbfb8aa3b, v106
	v_add_f32_e32 v107, v107, v75
	v_rcp_f32_e32 v130, v130
	v_add_f32_e32 v131, 1.0, v131
	v_add_f32_e32 v122, 1.0, v122
	v_exp_f32_e32 v115, v115
	v_exp_f32_e32 v106, v106
	v_mul_f32_e32 v107, 0xbfb8aa3b, v107
	v_add_f32_e32 v108, v108, v76
	v_rcp_f32_e32 v131, v131
	v_rcp_f32_e32 v122, v122
	v_add_f32_e32 v123, 1.0, v123
	v_exp_f32_e32 v107, v107
	v_mul_f32_e32 v108, 0xbfb8aa3b, v108
	v_add_f32_e32 v109, v109, v77
	v_add_f32_e32 v98, v98, v58
	v_rcp_f32_e32 v123, v123
	v_add_f32_e32 v124, 1.0, v124
	v_exp_f32_e32 v108, v108
	v_mul_f32_e32 v109, 0xbfb8aa3b, v109
	v_mul_f32_e32 v98, 0xbfb8aa3b, v98
	v_add_f32_e32 v99, v99, v59
	v_add_f32_e32 v90, v90, v74
	v_rcp_f32_e32 v124, v124
	v_add_f32_e32 v125, 1.0, v125
	v_add_f32_e32 v114, 1.0, v114
	v_exp_f32_e32 v109, v109
	v_exp_f32_e32 v98, v98
	v_mul_f32_e32 v99, 0xbfb8aa3b, v99
	v_mul_f32_e32 v90, 0xbfb8aa3b, v90
	v_add_f32_e32 v91, v91, v75
	v_mul_f32_e32 v138, v138, v130
	v_add_f32_e32 v130, v139, v67
	v_rcp_f32_e32 v125, v125
	v_rcp_f32_e32 v114, v114
	v_add_f32_e32 v115, 1.0, v115
	v_add_f32_e32 v106, 1.0, v106
	v_exp_f32_e32 v99, v99
	v_exp_f32_e32 v90, v90
	v_mul_f32_e32 v91, 0xbfb8aa3b, v91
	v_add_f32_e32 v92, v92, v76
	v_mul_f32_e32 v139, v130, v131
	v_add_f32_e32 v131, v132, v60
	v_mul_f32_e32 v122, v126, v122
	v_add_f32_e32 v126, v127, v79
	v_rcp_f32_e32 v115, v115
	v_rcp_f32_e32 v106, v106
	v_add_f32_e32 v107, 1.0, v107
	v_exp_f32_e32 v91, v91
	v_mul_f32_e32 v92, 0xbfb8aa3b, v92
	v_add_f32_e32 v93, v93, v77
	v_add_f32_e32 v82, v82, v58
	v_mul_f32_e32 v131, 0xbfb8aa3b, v131
	v_mul_f32_e32 v123, v126, v123
	v_add_f32_e32 v126, v128, v80
	v_rcp_f32_e32 v107, v107
	v_add_f32_e32 v108, 1.0, v108
	v_exp_f32_e32 v92, v92
	v_mul_f32_e32 v93, 0xbfb8aa3b, v93
	v_mul_f32_e32 v82, 0xbfb8aa3b, v82
	v_add_f32_e32 v83, v83, v59
	v_add_f32_e32 v50, v50, v58
	v_exp_f32_e32 v131, v131
	v_mul_f32_e32 v124, v126, v124
	v_add_f32_e32 v126, v129, v81
	v_add_f32_e32 v118, v118, v66
	v_rcp_f32_e32 v108, v108
	v_add_f32_e32 v109, 1.0, v109
	v_add_f32_e32 v98, 1.0, v98
	v_exp_f32_e32 v93, v93
	v_exp_f32_e32 v82, v82
	v_mul_f32_e32 v83, 0xbfb8aa3b, v83
	v_mul_f32_e32 v50, 0xbfb8aa3b, v50
	v_add_f32_e32 v51, v51, v59
	v_mul_f32_e32 v125, v126, v125
	v_mul_f32_e32 v126, v118, v114
	v_add_f32_e32 v114, v119, v67
	v_add_f32_e32 v110, v110, v78
	v_rcp_f32_e32 v109, v109
	v_rcp_f32_e32 v98, v98
	v_add_f32_e32 v99, 1.0, v99
	v_add_f32_e32 v90, 1.0, v90
	v_exp_f32_e32 v83, v83
	v_exp_f32_e32 v50, v50
	v_mul_f32_e32 v51, 0xbfb8aa3b, v51
	v_add_f32_e32 v34, v34, v58
	v_mul_f32_e32 v127, v114, v115
	v_add_f32_e32 v115, v116, v60
	v_mul_f32_e32 v106, v110, v106
	v_add_f32_e32 v110, v111, v79
	v_rcp_f32_e32 v99, v99
	v_rcp_f32_e32 v90, v90
	v_add_f32_e32 v91, 1.0, v91
	v_exp_f32_e32 v51, v51
	v_mul_f32_e32 v34, 0xbfb8aa3b, v34
	v_add_f32_e32 v35, v35, v59
	v_mul_f32_e32 v115, 0xbfb8aa3b, v115
	v_mul_f32_e32 v107, v110, v107
	v_add_f32_e32 v110, v112, v80
	v_rcp_f32_e32 v91, v91
	v_add_f32_e32 v92, 1.0, v92
	v_exp_f32_e32 v34, v34
	v_mul_f32_e32 v35, 0xbfb8aa3b, v35
	v_add_f32_e32 v18, v18, v58
	v_add_f32_e32 v131, 1.0, v131
	v_exp_f32_e32 v115, v115
	v_mul_f32_e32 v108, v110, v108
	v_add_f32_e32 v110, v113, v81
	v_add_f32_e32 v102, v102, v66
	v_rcp_f32_e32 v92, v92
	v_add_f32_e32 v93, 1.0, v93
	v_add_f32_e32 v82, 1.0, v82
	v_exp_f32_e32 v35, v35
	v_mul_f32_e32 v18, 0xbfb8aa3b, v18
	v_add_f32_e32 v19, v19, v59
	v_rcp_f32_e32 v131, v131
	v_mul_f32_e32 v109, v110, v109
	v_mul_f32_e32 v110, v102, v98
	v_add_f32_e32 v98, v103, v67
	v_add_f32_e32 v94, v94, v78
	v_rcp_f32_e32 v93, v93
	v_rcp_f32_e32 v82, v82
	v_add_f32_e32 v83, 1.0, v83
	v_add_f32_e32 v50, 1.0, v50
	v_exp_f32_e32 v18, v18
	v_mul_f32_e32 v19, 0xbfb8aa3b, v19
	v_add_f32_e32 v2, v2, v58
	v_mul_f32_e32 v111, v98, v99
	v_add_f32_e32 v99, v100, v60
	v_mul_f32_e32 v90, v94, v90
	v_add_f32_e32 v94, v95, v79
	v_rcp_f32_e32 v83, v83
	v_rcp_f32_e32 v50, v50
	v_add_f32_e32 v51, 1.0, v51
	v_exp_f32_e32 v19, v19
	v_mul_f32_e32 v2, 0xbfb8aa3b, v2
	v_add_f32_e32 v3, v3, v59
	v_add_f32_e32 v134, v134, v74
	v_mul_f32_e32 v99, 0xbfb8aa3b, v99
	v_mul_f32_e32 v91, v94, v91
	v_add_f32_e32 v94, v96, v80
	v_rcp_f32_e32 v51, v51
	v_add_f32_e32 v34, 1.0, v34
	v_exp_f32_e32 v2, v2
	v_mul_f32_e32 v3, 0xbfb8aa3b, v3
	v_mul_f32_e32 v134, 0xbfb8aa3b, v134
	v_add_f32_e32 v135, v135, v75
	v_add_f32_e32 v130, v140, v68
	v_add_f32_e32 v115, 1.0, v115
	v_exp_f32_e32 v99, v99
	v_mul_f32_e32 v92, v94, v92
	v_add_f32_e32 v94, v97, v81
	v_add_f32_e32 v86, v86, v66
	v_rcp_f32_e32 v34, v34
	v_add_f32_e32 v35, 1.0, v35
	v_exp_f32_e32 v3, v3
	v_exp_f32_e32 v134, v134
	v_mul_f32_e32 v135, 0xbfb8aa3b, v135
	v_add_f32_e32 v136, v136, v76
	v_mul_f32_e32 v140, v130, v131
	v_add_f32_e32 v131, v133, v61
	v_rcp_f32_e32 v115, v115
	v_mul_f32_e32 v93, v94, v93
	v_mul_f32_e32 v94, v86, v82
	v_add_f32_e32 v82, v87, v67
	v_add_f32_e32 v54, v54, v66
	v_rcp_f32_e32 v35, v35
	v_add_f32_e32 v18, 1.0, v18
	v_exp_f32_e32 v135, v135
	v_mul_f32_e32 v136, 0xbfb8aa3b, v136
	v_add_f32_e32 v137, v137, v77
	v_mul_f32_e32 v131, 0xbfb8aa3b, v131
	v_mul_f32_e32 v95, v82, v83
	v_add_f32_e32 v83, v84, v60
	v_mul_f32_e32 v54, v54, v50
	v_add_f32_e32 v50, v55, v67
	v_rcp_f32_e32 v18, v18
	v_add_f32_e32 v19, 1.0, v19
	v_exp_f32_e32 v136, v136
	v_mul_f32_e32 v137, 0xbfb8aa3b, v137
	v_exp_f32_e32 v131, v131
	v_mul_f32_e32 v83, 0xbfb8aa3b, v83
	v_mul_f32_e32 v55, v50, v51
	v_add_f32_e32 v51, v52, v60
	v_add_f32_e32 v38, v38, v66
	v_rcp_f32_e32 v19, v19
	v_add_f32_e32 v2, 1.0, v2
	v_exp_f32_e32 v137, v137
	v_add_f32_e32 v114, v120, v68
	v_add_f32_e32 v99, 1.0, v99
	v_exp_f32_e32 v83, v83
	v_mul_f32_e32 v51, 0xbfb8aa3b, v51
	v_mul_f32_e32 v38, v38, v34
	v_add_f32_e32 v34, v39, v67
	v_rcp_f32_e32 v2, v2
	v_add_f32_e32 v3, 1.0, v3
	v_add_f32_e32 v134, 1.0, v134
	v_mul_f32_e32 v120, v114, v115
	v_add_f32_e32 v115, v117, v61
	v_rcp_f32_e32 v99, v99
	v_exp_f32_e32 v51, v51
	v_mul_f32_e32 v39, v34, v35
	v_add_f32_e32 v35, v36, v60
	v_add_f32_e32 v22, v22, v66
	v_rcp_f32_e32 v3, v3
	v_rcp_f32_e32 v134, v134
	v_add_f32_e32 v135, 1.0, v135
	v_mul_f32_e32 v115, 0xbfb8aa3b, v115
	v_mul_f32_e32 v35, 0xbfb8aa3b, v35
	v_mul_f32_e32 v22, v22, v18
	v_add_f32_e32 v18, v23, v67
	v_rcp_f32_e32 v135, v135
	v_add_f32_e32 v136, 1.0, v136
	v_add_f32_e32 v131, 1.0, v131
	v_exp_f32_e32 v115, v115
	v_exp_f32_e32 v35, v35
	v_mul_f32_e32 v23, v18, v19
	v_add_f32_e32 v19, v20, v60
	v_add_f32_e32 v6, v6, v66
	v_rcp_f32_e32 v136, v136
	v_add_f32_e32 v137, 1.0, v137
	v_rcp_f32_e32 v131, v131
	v_add_f32_e32 v98, v104, v68
	v_add_f32_e32 v83, 1.0, v83
	v_mul_f32_e32 v19, 0xbfb8aa3b, v19
	v_mul_f32_e32 v6, v6, v2
	v_add_f32_e32 v2, v7, v67
	v_add_f32_e32 v142, v142, v78
	v_rcp_f32_e32 v137, v137
	v_mul_f32_e32 v104, v98, v99
	v_add_f32_e32 v99, v101, v61
	v_rcp_f32_e32 v83, v83
	v_add_f32_e32 v51, 1.0, v51
	v_exp_f32_e32 v19, v19
	v_mul_f32_e32 v7, v2, v3
	v_add_f32_e32 v3, v4, v60
	v_mul_f32_e32 v134, v142, v134
	v_add_f32_e32 v142, v143, v79
	v_mul_f32_e32 v99, 0xbfb8aa3b, v99
	v_rcp_f32_e32 v51, v51
	v_mul_f32_e32 v3, 0xbfb8aa3b, v3
	v_mul_f32_e32 v135, v142, v135
	v_add_f32_e32 v142, v144, v80
	v_add_f32_e32 v130, v141, v69
	v_add_f32_e32 v115, 1.0, v115
	v_exp_f32_e32 v99, v99
	v_add_f32_e32 v62, v62, v74
	v_add_f32_e32 v35, 1.0, v35
	v_exp_f32_e32 v3, v3
	v_mul_f32_e32 v136, v142, v136
	v_add_f32_e32 v142, v145, v81
	v_mul_f32_e32 v141, v130, v131
	v_lshl_add_u64 v[130:131], v[172:173], 0, v[182:183]
	v_cvt_pk_bf16_f32 v132, v134, v135
	v_rcp_f32_e32 v115, v115
	v_add_f32_e32 v82, v88, v68
	v_mul_f32_e32 v62, 0xbfb8aa3b, v62
	v_add_f32_e32 v63, v63, v75
	v_rcp_f32_e32 v35, v35
	v_mul_f32_e32 v137, v142, v137
	v_cvt_pk_bf16_f32 v133, v136, v137
	v_cvt_pk_bf16_f32 v134, v138, v139
	v_cvt_pk_bf16_f32 v135, v140, v141
	global_store_dwordx4 v[130:131], v[132:135], off
	v_mul_f32_e32 v88, v82, v83
	v_add_f32_e32 v83, v85, v61
	v_or_b32_e32 v132, 16, v174
	v_exp_f32_e32 v62, v62
	v_mul_f32_e32 v63, 0xbfb8aa3b, v63
	v_add_f32_e32 v64, v64, v76
	v_add_f32_e32 v50, v56, v68
	v_add_f32_e32 v42, v42, v74
	v_add_f32_e32 v19, 1.0, v19
	v_ashrrev_i32_e32 v133, 31, v132
	v_mul_f32_e32 v83, 0xbfb8aa3b, v83
	v_exp_f32_e32 v63, v63
	v_mul_f32_e32 v64, 0xbfb8aa3b, v64
	v_add_f32_e32 v65, v65, v77
	v_mul_f32_e32 v56, v50, v51
	v_add_f32_e32 v51, v53, v61
	v_mul_f32_e32 v42, 0xbfb8aa3b, v42
	v_add_f32_e32 v43, v43, v75
	v_rcp_f32_e32 v19, v19
	v_lshlrev_b64 v[132:133], 11, v[132:133]
	v_add_f32_e32 v114, v121, v69
	v_add_f32_e32 v99, 1.0, v99
	v_exp_f32_e32 v83, v83
	v_exp_f32_e32 v64, v64
	v_mul_f32_e32 v65, 0xbfb8aa3b, v65
	v_mul_f32_e32 v51, 0xbfb8aa3b, v51
	v_exp_f32_e32 v42, v42
	v_mul_f32_e32 v43, 0xbfb8aa3b, v43
	v_add_f32_e32 v44, v44, v76
	v_add_f32_e32 v34, v40, v68
	v_add_f32_e32 v26, v26, v74
	v_add_f32_e32 v3, 1.0, v3
	v_mul_f32_e32 v117, v114, v115
	v_lshl_add_u64 v[118:119], v[172:173], 0, v[132:133]
	v_cvt_pk_bf16_f32 v114, v122, v123
	v_rcp_f32_e32 v99, v99
	v_exp_f32_e32 v65, v65
	v_exp_f32_e32 v51, v51
	v_exp_f32_e32 v43, v43
	v_mul_f32_e32 v44, 0xbfb8aa3b, v44
	v_add_f32_e32 v45, v45, v77
	v_mul_f32_e32 v40, v34, v35
	v_add_f32_e32 v35, v37, v61
	v_mul_f32_e32 v26, 0xbfb8aa3b, v26
	v_add_f32_e32 v27, v27, v75
	v_rcp_f32_e32 v3, v3
	v_cvt_pk_bf16_f32 v115, v124, v125
	v_cvt_pk_bf16_f32 v116, v126, v127
	v_cvt_pk_bf16_f32 v117, v120, v117
	global_store_dwordx4 v[118:119], v[114:117], off
	v_add_f32_e32 v62, 1.0, v62
	v_exp_f32_e32 v44, v44
	v_or_b32_e32 v114, 32, v174
	v_mul_f32_e32 v45, 0xbfb8aa3b, v45
	v_mul_f32_e32 v35, 0xbfb8aa3b, v35
	v_exp_f32_e32 v26, v26
	v_mul_f32_e32 v27, 0xbfb8aa3b, v27
	v_add_f32_e32 v28, v28, v76
	v_add_f32_e32 v18, v24, v68
	v_add_f32_e32 v10, v10, v74
	v_ashrrev_i32_e32 v115, 31, v114
	v_rcp_f32_e32 v62, v62
	v_add_f32_e32 v63, 1.0, v63
	v_exp_f32_e32 v45, v45
	v_exp_f32_e32 v35, v35
	v_exp_f32_e32 v27, v27
	v_mul_f32_e32 v28, 0xbfb8aa3b, v28
	v_add_f32_e32 v29, v29, v77
	v_mul_f32_e32 v24, v18, v19
	v_add_f32_e32 v19, v21, v61
	v_mul_f32_e32 v10, 0xbfb8aa3b, v10
	v_add_f32_e32 v11, v11, v75
	v_lshlrev_b64 v[114:115], 11, v[114:115]
	v_add_f32_e32 v98, v105, v69
	v_add_f32_e32 v83, 1.0, v83
	v_rcp_f32_e32 v63, v63
	v_add_f32_e32 v64, 1.0, v64
	v_add_f32_e32 v42, 1.0, v42
	v_exp_f32_e32 v28, v28
	v_mul_f32_e32 v29, 0xbfb8aa3b, v29
	v_mul_f32_e32 v19, 0xbfb8aa3b, v19
	v_exp_f32_e32 v10, v10
	v_mul_f32_e32 v11, 0xbfb8aa3b, v11
	v_add_f32_e32 v12, v12, v76
	v_add_f32_e32 v2, v8, v68
	v_mul_f32_e32 v101, v98, v99
	v_lshl_add_u64 v[102:103], v[172:173], 0, v[114:115]
	v_cvt_pk_bf16_f32 v98, v106, v107
	v_rcp_f32_e32 v83, v83
	v_rcp_f32_e32 v64, v64
	v_add_f32_e32 v65, 1.0, v65
	v_add_f32_e32 v51, 1.0, v51
	v_rcp_f32_e32 v42, v42
	v_add_f32_e32 v43, 1.0, v43
	v_exp_f32_e32 v29, v29
	v_exp_f32_e32 v19, v19
	v_exp_f32_e32 v11, v11
	v_mul_f32_e32 v12, 0xbfb8aa3b, v12
	v_add_f32_e32 v13, v13, v77
	v_mul_f32_e32 v8, v2, v3
	v_add_f32_e32 v3, v5, v61
	v_cvt_pk_bf16_f32 v99, v108, v109
	v_cvt_pk_bf16_f32 v100, v110, v111
	v_cvt_pk_bf16_f32 v101, v104, v101
	global_store_dwordx4 v[102:103], v[98:101], off
	v_add_f32_e32 v70, v70, v78
	v_rcp_f32_e32 v65, v65
	v_or_b32_e32 v98, 48, v174
	v_rcp_f32_e32 v51, v51
	v_rcp_f32_e32 v43, v43
	v_add_f32_e32 v44, 1.0, v44
	v_add_f32_e32 v26, 1.0, v26
	v_exp_f32_e32 v12, v12
	v_mul_f32_e32 v13, 0xbfb8aa3b, v13
	v_mul_f32_e32 v3, 0xbfb8aa3b, v3
	v_ashrrev_i32_e32 v99, 31, v98
	v_mul_f32_e32 v62, v70, v62
	v_add_f32_e32 v70, v71, v79
	v_rcp_f32_e32 v44, v44
	v_add_f32_e32 v45, 1.0, v45
	v_add_f32_e32 v35, 1.0, v35
	v_rcp_f32_e32 v26, v26
	v_add_f32_e32 v27, 1.0, v27
	v_exp_f32_e32 v13, v13
	v_exp_f32_e32 v3, v3
	v_lshlrev_b64 v[98:99], 11, v[98:99]
	v_add_f32_e32 v82, v89, v69
	v_mul_f32_e32 v63, v70, v63
	v_add_f32_e32 v70, v72, v80
	v_add_f32_e32 v46, v46, v78
	v_rcp_f32_e32 v45, v45
	v_rcp_f32_e32 v35, v35
	v_rcp_f32_e32 v27, v27
	v_add_f32_e32 v28, 1.0, v28
	v_add_f32_e32 v10, 1.0, v10
	v_mul_f32_e32 v85, v82, v83
	v_lshl_add_u64 v[86:87], v[172:173], 0, v[98:99]
	v_mul_f32_e32 v64, v70, v64
	v_add_f32_e32 v70, v73, v81
	v_add_f32_e32 v50, v57, v69
	v_mul_f32_e32 v42, v46, v42
	v_add_f32_e32 v46, v47, v79
	v_rcp_f32_e32 v28, v28
	v_add_f32_e32 v29, 1.0, v29
	v_add_f32_e32 v19, 1.0, v19
	v_rcp_f32_e32 v10, v10
	v_add_f32_e32 v11, 1.0, v11
	v_cvt_pk_bf16_f32 v82, v90, v91
	v_cvt_pk_bf16_f32 v83, v92, v93
	v_cvt_pk_bf16_f32 v84, v94, v95
	v_cvt_pk_bf16_f32 v85, v88, v85
	global_store_dwordx4 v[86:87], v[82:85], off
	v_mul_f32_e32 v65, v70, v65
	v_mul_f32_e32 v53, v50, v51
	v_cvt_pk_bf16_f32 v50, v62, v63
	v_cvt_pk_bf16_f32 v51, v64, v65
	v_cvt_pk_bf16_f32 v52, v54, v55
	v_add_co_u32_e32 v54, vcc, s67, v130
	v_mul_f32_e32 v43, v46, v43
	v_add_f32_e32 v46, v48, v80
	v_add_f32_e32 v30, v30, v78
	v_rcp_f32_e32 v29, v29
	v_rcp_f32_e32 v19, v19
	v_rcp_f32_e32 v11, v11
	v_add_f32_e32 v12, 1.0, v12
	v_addc_co_u32_e32 v55, vcc, 0, v131, vcc
	v_mul_f32_e32 v44, v46, v44
	v_add_f32_e32 v46, v49, v81
	v_add_f32_e32 v34, v41, v69
	v_mul_f32_e32 v26, v30, v26
	v_add_f32_e32 v30, v31, v79
	v_rcp_f32_e32 v12, v12
	v_add_f32_e32 v13, 1.0, v13
	v_add_f32_e32 v3, 1.0, v3
	v_cvt_pk_bf16_f32 v53, v56, v53
	global_store_dwordx4 v[54:55], v[50:53], off
	v_mul_f32_e32 v45, v46, v45
	v_mul_f32_e32 v37, v34, v35
	v_cvt_pk_bf16_f32 v34, v42, v43
	v_cvt_pk_bf16_f32 v35, v44, v45
	v_cvt_pk_bf16_f32 v36, v38, v39
	v_add_co_u32_e32 v38, vcc, s68, v130
	v_mul_f32_e32 v27, v30, v27
	v_add_f32_e32 v30, v32, v80
	v_add_f32_e32 v14, v14, v78
	v_rcp_f32_e32 v13, v13
	v_rcp_f32_e32 v3, v3
	v_addc_co_u32_e32 v39, vcc, 0, v131, vcc
	v_mul_f32_e32 v28, v30, v28
	v_add_f32_e32 v30, v33, v81
	v_add_f32_e32 v18, v25, v69
	v_mul_f32_e32 v10, v14, v10
	v_add_f32_e32 v14, v15, v79
	v_cvt_pk_bf16_f32 v37, v40, v37
	global_store_dwordx4 v[38:39], v[34:37], off
	v_mul_f32_e32 v29, v30, v29
	v_mul_f32_e32 v21, v18, v19
	v_cvt_pk_bf16_f32 v18, v26, v27
	v_cvt_pk_bf16_f32 v19, v28, v29
	v_cvt_pk_bf16_f32 v20, v22, v23
	v_add_co_u32_e32 v22, vcc, s2, v130
	v_mul_f32_e32 v11, v14, v11
	v_add_f32_e32 v14, v16, v80
	v_addc_co_u32_e32 v23, vcc, 0, v131, vcc
	v_mul_f32_e32 v12, v14, v12
	v_add_f32_e32 v14, v17, v81
	v_add_f32_e32 v2, v9, v69
	v_cvt_pk_bf16_f32 v21, v24, v21
	global_store_dwordx4 v[22:23], v[18:21], off
	v_mul_f32_e32 v13, v14, v13
	v_mul_f32_e32 v5, v2, v3
	v_cvt_pk_bf16_f32 v2, v10, v11
	v_cvt_pk_bf16_f32 v3, v12, v13
	v_cvt_pk_bf16_f32 v4, v6, v7
	v_add_co_u32_e32 v6, vcc, 0x58000, v130
	s_mov_b32 s2, s48
	s_nop 0
	v_addc_co_u32_e32 v7, vcc, 0, v131, vcc
	s_and_b64 vcc, exec, s[38:39]
	v_cvt_pk_bf16_f32 v5, v8, v5
	global_store_dwordx4 v[6:7], v[2:5], off
	s_cbranch_vccz .LBB0_88
	s_waitcnt vmcnt(8)
	s_cmpk_gt_u32 s35, 0xff
	s_cbranch_scc1 .LBB0_99
	s_barrier

.LBB0_259:
	s_ashr_i32 s35, s34, 31
	v_cmp_lt_i64_e32 vcc, s[36:37], v[150:151]
	s_lshl_b64 s[36:37], s[34:35], 19
	s_add_u32 s36, s12, s36
	s_addc_u32 s37, s13, s37
	s_and_b64 s[42:43], vcc, exec
	s_cselect_b32 s35, s37, s1
	s_cselect_b32 s55, s36, s0
	s_ashr_i32 s31, s30, 31
	s_lshl_b64 s[42:43], s[30:31], 19
	s_add_u32 s42, s17, s42
	s_addc_u32 s43, s19, s43
	s_and_b64 s[46:47], vcc, exec
	s_cselect_b32 s31, s43, s23
	s_cselect_b32 s56, s42, s22
	s_add_u32 s0, s0, 0x40080
	s_addc_u32 s1, s1, 0
	s_add_u32 s57, s22, 0x100
	s_addc_u32 s58, s23, 0
	s_mov_b32 s59, -2
	v_mov_b64_e32 v[82:83], 0
	v_mov_b64_e32 v[84:85], 0
	s_nop 1
	v_mfma_f32_32x32x16_bf16 v[2:17], v[82:85], v[82:85], 0
	v_mov_b64_e32 v[114:115], 0
	v_mov_b64_e32 v[116:117], 0
	v_mov_b64_e32 v[118:119], 0
	v_mov_b64_e32 v[120:121], 0
	v_mov_b64_e32 v[122:123], 0
	v_mfma_f32_32x32x16_bf16 v[18:33], v[82:85], v[82:85], 0
	v_mov_b64_e32 v[124:125], 0
	v_mov_b64_e32 v[126:127], 0
	v_mov_b64_e32 v[128:129], 0
	v_mov_b64_e32 v[98:99], 0
	v_mov_b64_e32 v[100:101], 0
	v_mfma_f32_32x32x16_bf16 v[34:49], v[82:85], v[82:85], 0
	v_mov_b64_e32 v[102:103], 0
	v_mov_b64_e32 v[104:105], 0
	v_mov_b64_e32 v[106:107], 0
	v_mov_b64_e32 v[108:109], 0
	v_mov_b64_e32 v[110:111], 0
	v_mfma_f32_32x32x16_bf16 v[50:65], v[82:85], v[82:85], 0
	v_mov_b64_e32 v[112:113], 0
	v_mov_b64_e32 v[86:87], 0
	v_mov_b64_e32 v[88:89], 0
	v_mov_b64_e32 v[90:91], 0
	v_mov_b64_e32 v[92:93], 0
	v_mfma_f32_32x32x16_bf16 v[66:81], v[82:85], v[82:85], 0
	v_mov_b64_e32 v[94:95], 0
	v_mov_b64_e32 v[96:97], 0
	v_readfirstlane_b32 s98, v204
	s_lshr_b32 s98, s98, 8
	s_cmp_eq_u32 s98, 0
	s_cbranch_scc1 .Lkprio_3
	s_setprio 1
.Lkprio_3:
.LBB0_260:
	s_add_u32 s22, s0, 0xfffc0080
	s_addc_u32 s23, s1, -1
	s_add_i32 s60, 0, 0x10000
	v_add_u32_e32 v142, s60, v178
	ds_read_b128 v[130:133], v142
	ds_read_b128 v[134:137], v142 offset:1024
	ds_read_b128 v[138:141], v142 offset:2048
	ds_read_b128 v[142:145], v142 offset:3072
	s_cmp_eq_u32 s59, 12
	s_cselect_b32 s47, s35, s23
	s_cselect_b32 s46, s55, s22
	s_cselect_b32 s23, s31, s58
	s_cselect_b32 s22, s56, s57
	v_lshl_add_u64 v[186:187], s[0:1], 0, v[168:169]
	s_add_i32 m0, s27, 0xc000
	ds_read_b128 v[172:175], v180
	ds_read_b128 v[182:185], v180 offset:1024
	ds_read_b128 v[206:209], v180 offset:2048
	ds_read_b128 v[210:213], v180 offset:3072
	ds_read_b128 v[214:217], v180 offset:4096
	ds_read_b128 v[218:221], v180 offset:5120
	ds_read_b128 v[222:225], v180 offset:6144
	ds_read_b128 v[226:229], v180 offset:7168
	global_load_lds_dwordx4 v[186:187], off
	v_lshl_add_u64 v[186:187], s[0:1], 0, v[170:171]
	s_add_i32 m0, s27, 0xe000
	s_nop 0
	global_load_lds_dwordx4 v[186:187], off
	s_waitcnt lgkmcnt(8)
	s_barrier
	s_waitcnt lgkmcnt(0)
	v_mfma_f32_16x16x32_bf16 v[126:129], v[130:133], v[172:175], v[126:129]
	v_mfma_f32_16x16x32_bf16 v[122:125], v[138:141], v[172:175], v[122:125]
	v_mfma_f32_16x16x32_bf16 v[110:113], v[130:133], v[206:209], v[110:113]
	v_mfma_f32_16x16x32_bf16 v[106:109], v[138:141], v[206:209], v[106:109]
	v_mfma_f32_16x16x32_bf16 v[94:97], v[130:133], v[214:217], v[94:97]
	v_mfma_f32_16x16x32_bf16 v[90:93], v[138:141], v[214:217], v[90:93]
	v_mfma_f32_16x16x32_bf16 v[78:81], v[130:133], v[222:225], v[78:81]
	v_mfma_f32_16x16x32_bf16 v[74:77], v[138:141], v[222:225], v[74:77]
	v_mfma_f32_16x16x32_bf16 v[126:129], v[134:137], v[182:185], v[126:129]
	v_mfma_f32_16x16x32_bf16 v[122:125], v[142:145], v[182:185], v[122:125]
	v_mfma_f32_16x16x32_bf16 v[110:113], v[134:137], v[210:213], v[110:113]
	v_mfma_f32_16x16x32_bf16 v[106:109], v[142:145], v[210:213], v[106:109]
	v_mfma_f32_16x16x32_bf16 v[94:97], v[134:137], v[218:221], v[94:97]
	v_mfma_f32_16x16x32_bf16 v[90:93], v[142:145], v[218:221], v[90:93]
	v_mfma_f32_16x16x32_bf16 v[78:81], v[134:137], v[226:229], v[78:81]
	v_mfma_f32_16x16x32_bf16 v[74:77], v[142:145], v[226:229], v[74:77]
	s_barrier
	s_add_i32 s62, 0, 0x14000
	s_add_i32 s60, s60, s25
	v_add_u32_e32 v181, s62, v178
	v_lshl_add_u64 v[186:187], s[22:23], 0, v[0:1]
	s_mov_b32 m0, s60
	ds_read_b128 v[230:233], v181
	ds_read_b128 v[234:237], v181 offset:1024
	ds_read_b128 v[238:241], v181 offset:2048
	ds_read_b128 v[242:245], v181 offset:3072
	global_load_lds_dwordx4 v[186:187], off
	v_lshl_add_u64 v[246:247], s[22:23], 0, v[162:163]
	s_add_i32 m0, s60, 0x2000
	s_nop 0
	global_load_lds_dwordx4 v[246:247], off
	s_barrier
	s_waitcnt lgkmcnt(0)
	v_mfma_f32_16x16x32_bf16 v[118:121], v[230:233], v[172:175], v[118:121]
	v_mfma_f32_16x16x32_bf16 v[114:117], v[238:241], v[172:175], v[114:117]
	v_mfma_f32_16x16x32_bf16 v[102:105], v[230:233], v[206:209], v[102:105]
	v_mfma_f32_16x16x32_bf16 v[98:101], v[238:241], v[206:209], v[98:101]
	v_mfma_f32_16x16x32_bf16 v[86:89], v[230:233], v[214:217], v[86:89]
	v_mfma_f32_16x16x32_bf16 v[82:85], v[238:241], v[214:217], v[82:85]
	v_mfma_f32_16x16x32_bf16 v[70:73], v[230:233], v[222:225], v[70:73]
	v_mfma_f32_16x16x32_bf16 v[66:69], v[238:241], v[222:225], v[66:69]
	v_mfma_f32_16x16x32_bf16 v[118:121], v[234:237], v[182:185], v[118:121]
	v_mfma_f32_16x16x32_bf16 v[114:117], v[242:245], v[182:185], v[114:117]
	v_mfma_f32_16x16x32_bf16 v[102:105], v[234:237], v[210:213], v[102:105]
	v_mfma_f32_16x16x32_bf16 v[98:101], v[242:245], v[210:213], v[98:101]
	v_mfma_f32_16x16x32_bf16 v[86:89], v[234:237], v[218:221], v[86:89]
	v_mfma_f32_16x16x32_bf16 v[82:85], v[242:245], v[218:221], v[82:85]
	v_mfma_f32_16x16x32_bf16 v[70:73], v[234:237], v[226:229], v[70:73]
	v_mfma_f32_16x16x32_bf16 v[66:69], v[242:245], v[226:229], v[66:69]
	s_barrier
	s_mov_b32 m0, s27
	v_lshl_add_u64 v[248:249], s[46:47], 0, v[166:167]
	ds_read_b128 v[172:175], v180 offset:16384
	ds_read_b128 v[182:185], v180 offset:17408
	ds_read_b128 v[206:209], v180 offset:18432
	ds_read_b128 v[210:213], v180 offset:19456
	ds_read_b128 v[214:217], v180 offset:20480
	ds_read_b128 v[218:221], v180 offset:21504
	ds_read_b128 v[222:225], v180 offset:22528
	ds_read_b128 v[226:229], v180 offset:23552
	global_load_lds_dwordx4 v[248:249], off
	v_lshl_add_u64 v[250:251], s[46:47], 0, v[164:165]
	s_mov_b32 m0, s45
	s_nop 0
	global_load_lds_dwordx4 v[250:251], off
	s_barrier
	s_waitcnt lgkmcnt(0)
	v_mfma_f32_16x16x32_bf16 v[62:65], v[130:133], v[172:175], v[62:65]
	v_mfma_f32_16x16x32_bf16 v[58:61], v[138:141], v[172:175], v[58:61]
	v_mfma_f32_16x16x32_bf16 v[50:53], v[130:133], v[206:209], v[50:53]
	v_mfma_f32_16x16x32_bf16 v[42:45], v[138:141], v[206:209], v[42:45]
	v_mfma_f32_16x16x32_bf16 v[34:37], v[130:133], v[214:217], v[34:37]
	v_mfma_f32_16x16x32_bf16 v[26:29], v[138:141], v[214:217], v[26:29]
	v_mfma_f32_16x16x32_bf16 v[18:21], v[130:133], v[222:225], v[18:21]
	v_mfma_f32_16x16x32_bf16 v[10:13], v[138:141], v[222:225], v[10:13]
	v_mfma_f32_16x16x32_bf16 v[62:65], v[134:137], v[182:185], v[62:65]
	v_mfma_f32_16x16x32_bf16 v[58:61], v[142:145], v[182:185], v[58:61]
	v_mfma_f32_16x16x32_bf16 v[50:53], v[134:137], v[210:213], v[50:53]
	v_mfma_f32_16x16x32_bf16 v[42:45], v[142:145], v[210:213], v[42:45]
	v_mfma_f32_16x16x32_bf16 v[34:37], v[134:137], v[218:221], v[34:37]
	v_mfma_f32_16x16x32_bf16 v[26:29], v[142:145], v[218:221], v[26:29]
	v_mfma_f32_16x16x32_bf16 v[18:21], v[134:137], v[226:229], v[18:21]
	v_mfma_f32_16x16x32_bf16 v[10:13], v[142:145], v[226:229], v[10:13]
	s_barrier
	s_add_u32 s60, s22, 0x40000
	s_addc_u32 s61, s23, 0
	s_add_i32 s62, s62, s25
	v_lshl_add_u64 v[130:131], s[60:61], 0, v[0:1]
	s_mov_b32 m0, s62
	s_nop 0
	global_load_lds_dwordx4 v[130:131], off
	v_lshl_add_u64 v[130:131], s[60:61], 0, v[162:163]
	s_add_i32 m0, s62, 0x2000
	s_nop 0
	global_load_lds_dwordx4 v[130:131], off
	s_waitcnt vmcnt(6)
	s_barrier
	v_mfma_f32_16x16x32_bf16 v[54:57], v[230:233], v[172:175], v[54:57]
	v_mfma_f32_16x16x32_bf16 v[46:49], v[238:241], v[172:175], v[46:49]
	v_mfma_f32_16x16x32_bf16 v[38:41], v[230:233], v[206:209], v[38:41]
	v_mfma_f32_16x16x32_bf16 v[30:33], v[238:241], v[206:209], v[30:33]
	v_mfma_f32_16x16x32_bf16 v[22:25], v[230:233], v[214:217], v[22:25]
	v_mfma_f32_16x16x32_bf16 v[14:17], v[238:241], v[214:217], v[14:17]
	v_mfma_f32_16x16x32_bf16 v[6:9], v[230:233], v[222:225], v[6:9]
	v_mfma_f32_16x16x32_bf16 v[2:5], v[238:241], v[222:225], v[2:5]
	v_mfma_f32_16x16x32_bf16 v[54:57], v[234:237], v[182:185], v[54:57]
	v_mfma_f32_16x16x32_bf16 v[46:49], v[242:245], v[182:185], v[46:49]
	v_mfma_f32_16x16x32_bf16 v[38:41], v[234:237], v[210:213], v[38:41]
	v_mfma_f32_16x16x32_bf16 v[30:33], v[242:245], v[210:213], v[30:33]
	v_mfma_f32_16x16x32_bf16 v[22:25], v[234:237], v[218:221], v[22:25]
	v_mfma_f32_16x16x32_bf16 v[14:17], v[242:245], v[218:221], v[14:17]
	v_mfma_f32_16x16x32_bf16 v[6:9], v[234:237], v[226:229], v[6:9]
	v_mfma_f32_16x16x32_bf16 v[2:5], v[242:245], v[226:229], v[2:5]
	s_barrier
	s_add_i32 s60, 0, 0x18000
	v_add_u32_e32 v142, s60, v178
	ds_read_b128 v[130:133], v142
	ds_read_b128 v[134:137], v142 offset:1024
	ds_read_b128 v[138:141], v142 offset:2048
	ds_read_b128 v[142:145], v142 offset:3072
	s_add_u32 s46, s46, 0x40000
	s_addc_u32 s47, s47, 0
	s_mov_b32 m0, s48
	v_lshl_add_u64 v[230:231], s[46:47], 0, v[166:167]
	ds_read_b128 v[172:175], v180 offset:32768
	ds_read_b128 v[182:185], v180 offset:33792
	ds_read_b128 v[206:209], v180 offset:34816
	ds_read_b128 v[210:213], v180 offset:35840
	ds_read_b128 v[214:217], v180 offset:36864
	ds_read_b128 v[218:221], v180 offset:37888
	ds_read_b128 v[222:225], v180 offset:38912
	ds_read_b128 v[226:229], v180 offset:39936
	global_load_lds_dwordx4 v[230:231], off
	v_lshl_add_u64 v[230:231], s[46:47], 0, v[164:165]
	s_mov_b32 m0, s49
	s_nop 0
	global_load_lds_dwordx4 v[230:231], off
	s_waitcnt lgkmcnt(8)
	s_barrier
	s_waitcnt lgkmcnt(0)
	v_mfma_f32_16x16x32_bf16 v[126:129], v[130:133], v[172:175], v[126:129]
	v_mfma_f32_16x16x32_bf16 v[122:125], v[138:141], v[172:175], v[122:125]
	v_mfma_f32_16x16x32_bf16 v[110:113], v[130:133], v[206:209], v[110:113]
	v_mfma_f32_16x16x32_bf16 v[106:109], v[138:141], v[206:209], v[106:109]
	v_mfma_f32_16x16x32_bf16 v[94:97], v[130:133], v[214:217], v[94:97]
	v_mfma_f32_16x16x32_bf16 v[90:93], v[138:141], v[214:217], v[90:93]
	v_mfma_f32_16x16x32_bf16 v[78:81], v[130:133], v[222:225], v[78:81]
	v_mfma_f32_16x16x32_bf16 v[74:77], v[138:141], v[222:225], v[74:77]
	v_mfma_f32_16x16x32_bf16 v[126:129], v[134:137], v[182:185], v[126:129]
	v_mfma_f32_16x16x32_bf16 v[122:125], v[142:145], v[182:185], v[122:125]
	v_mfma_f32_16x16x32_bf16 v[110:113], v[134:137], v[210:213], v[110:113]
	v_mfma_f32_16x16x32_bf16 v[106:109], v[142:145], v[210:213], v[106:109]
	v_mfma_f32_16x16x32_bf16 v[94:97], v[134:137], v[218:221], v[94:97]
	v_mfma_f32_16x16x32_bf16 v[90:93], v[142:145], v[218:221], v[90:93]
	v_mfma_f32_16x16x32_bf16 v[78:81], v[134:137], v[226:229], v[78:81]
	v_mfma_f32_16x16x32_bf16 v[74:77], v[142:145], v[226:229], v[74:77]
	s_barrier
	s_add_i32 s46, 0, 0x1c000
	s_add_i32 s47, s60, s25
	v_add_u32_e32 v181, s46, v178
	v_lshl_add_u64 v[186:187], v[186:187], 0, s[94:95]
	s_mov_b32 m0, s47
	ds_read_b128 v[230:233], v181
	ds_read_b128 v[234:237], v181 offset:1024
	ds_read_b128 v[238:241], v181 offset:2048
	ds_read_b128 v[242:245], v181 offset:3072
	global_load_lds_dwordx4 v[186:187], off
	v_lshl_add_u64 v[186:187], v[246:247], 0, s[94:95]
	s_add_i32 m0, s47, 0x2000
	s_nop 0
	global_load_lds_dwordx4 v[186:187], off
	s_barrier
	s_waitcnt lgkmcnt(0)
	v_mfma_f32_16x16x32_bf16 v[118:121], v[230:233], v[172:175], v[118:121]
	v_mfma_f32_16x16x32_bf16 v[114:117], v[238:241], v[172:175], v[114:117]
	v_mfma_f32_16x16x32_bf16 v[102:105], v[230:233], v[206:209], v[102:105]
	v_mfma_f32_16x16x32_bf16 v[98:101], v[238:241], v[206:209], v[98:101]
	v_mfma_f32_16x16x32_bf16 v[86:89], v[230:233], v[214:217], v[86:89]
	v_mfma_f32_16x16x32_bf16 v[82:85], v[238:241], v[214:217], v[82:85]
	v_mfma_f32_16x16x32_bf16 v[70:73], v[230:233], v[222:225], v[70:73]
	v_mfma_f32_16x16x32_bf16 v[66:69], v[238:241], v[222:225], v[66:69]
	v_mfma_f32_16x16x32_bf16 v[118:121], v[234:237], v[182:185], v[118:121]
	v_mfma_f32_16x16x32_bf16 v[114:117], v[242:245], v[182:185], v[114:117]
	v_mfma_f32_16x16x32_bf16 v[102:105], v[234:237], v[210:213], v[102:105]
	v_mfma_f32_16x16x32_bf16 v[98:101], v[242:245], v[210:213], v[98:101]
	v_mfma_f32_16x16x32_bf16 v[86:89], v[234:237], v[218:221], v[86:89]
	v_mfma_f32_16x16x32_bf16 v[82:85], v[242:245], v[218:221], v[82:85]
	v_mfma_f32_16x16x32_bf16 v[70:73], v[234:237], v[226:229], v[70:73]
	v_mfma_f32_16x16x32_bf16 v[66:69], v[242:245], v[226:229], v[66:69]
	s_barrier
	s_mov_b32 m0, s51
	v_lshl_add_u64 v[186:187], v[248:249], 0, s[94:95]
	ds_read_b128 v[172:175], v180 offset:49152
	ds_read_b128 v[182:185], v180 offset:50176
	ds_read_b128 v[206:209], v180 offset:51200
	ds_read_b128 v[210:213], v180 offset:52224
	ds_read_b128 v[214:217], v180 offset:53248
	ds_read_b128 v[218:221], v180 offset:54272
	ds_read_b128 v[222:225], v180 offset:55296
	ds_read_b128 v[226:229], v180 offset:56320
	global_load_lds_dwordx4 v[186:187], off
	v_lshl_add_u64 v[186:187], v[250:251], 0, s[94:95]
	s_mov_b32 m0, s52
	s_nop 0
	global_load_lds_dwordx4 v[186:187], off
	s_barrier
	s_waitcnt lgkmcnt(0)
	v_mfma_f32_16x16x32_bf16 v[62:65], v[130:133], v[172:175], v[62:65]
	v_mfma_f32_16x16x32_bf16 v[58:61], v[138:141], v[172:175], v[58:61]
	v_mfma_f32_16x16x32_bf16 v[50:53], v[130:133], v[206:209], v[50:53]
	v_mfma_f32_16x16x32_bf16 v[42:45], v[138:141], v[206:209], v[42:45]
	v_mfma_f32_16x16x32_bf16 v[34:37], v[130:133], v[214:217], v[34:37]
	v_mfma_f32_16x16x32_bf16 v[26:29], v[138:141], v[214:217], v[26:29]
	v_mfma_f32_16x16x32_bf16 v[18:21], v[130:133], v[222:225], v[18:21]
	v_mfma_f32_16x16x32_bf16 v[10:13], v[138:141], v[222:225], v[10:13]
	v_mfma_f32_16x16x32_bf16 v[62:65], v[134:137], v[182:185], v[62:65]
	v_mfma_f32_16x16x32_bf16 v[58:61], v[142:145], v[182:185], v[58:61]
	v_mfma_f32_16x16x32_bf16 v[50:53], v[134:137], v[210:213], v[50:53]
	v_mfma_f32_16x16x32_bf16 v[42:45], v[142:145], v[210:213], v[42:45]
	v_mfma_f32_16x16x32_bf16 v[34:37], v[134:137], v[218:221], v[34:37]
	v_mfma_f32_16x16x32_bf16 v[26:29], v[142:145], v[218:221], v[26:29]
	v_mfma_f32_16x16x32_bf16 v[18:21], v[134:137], v[226:229], v[18:21]
	v_mfma_f32_16x16x32_bf16 v[10:13], v[142:145], v[226:229], v[10:13]
	s_barrier
	s_add_u32 s22, s22, 0x40080
	s_addc_u32 s23, s23, 0
	s_add_i32 s46, s46, s25
	v_lshl_add_u64 v[130:131], s[22:23], 0, v[0:1]
	s_mov_b32 m0, s46
	s_nop 0
	global_load_lds_dwordx4 v[130:131], off
	v_lshl_add_u64 v[130:131], s[22:23], 0, v[162:163]
	s_add_i32 m0, s46, 0x2000
	s_nop 0
	global_load_lds_dwordx4 v[130:131], off
	s_waitcnt vmcnt(6)
	s_barrier
	v_mfma_f32_16x16x32_bf16 v[54:57], v[230:233], v[172:175], v[54:57]
	v_mfma_f32_16x16x32_bf16 v[46:49], v[238:241], v[172:175], v[46:49]
	v_mfma_f32_16x16x32_bf16 v[38:41], v[230:233], v[206:209], v[38:41]
	v_mfma_f32_16x16x32_bf16 v[30:33], v[238:241], v[206:209], v[30:33]
	v_mfma_f32_16x16x32_bf16 v[22:25], v[230:233], v[214:217], v[22:25]
	v_mfma_f32_16x16x32_bf16 v[14:17], v[238:241], v[214:217], v[14:17]
	v_mfma_f32_16x16x32_bf16 v[6:9], v[230:233], v[222:225], v[6:9]
	v_mfma_f32_16x16x32_bf16 v[2:5], v[238:241], v[222:225], v[2:5]
	v_mfma_f32_16x16x32_bf16 v[54:57], v[234:237], v[182:185], v[54:57]
	v_mfma_f32_16x16x32_bf16 v[46:49], v[242:245], v[182:185], v[46:49]
	v_mfma_f32_16x16x32_bf16 v[38:41], v[234:237], v[210:213], v[38:41]
	v_mfma_f32_16x16x32_bf16 v[30:33], v[242:245], v[210:213], v[30:33]
	v_mfma_f32_16x16x32_bf16 v[22:25], v[234:237], v[218:221], v[22:25]
	v_mfma_f32_16x16x32_bf16 v[14:17], v[242:245], v[218:221], v[14:17]
	v_mfma_f32_16x16x32_bf16 v[6:9], v[234:237], v[226:229], v[6:9]
	v_mfma_f32_16x16x32_bf16 v[2:5], v[242:245], v[226:229], v[2:5]
	s_barrier
	s_add_i32 s59, s59, 2
	s_add_u32 s0, s0, 0x100
	s_addc_u32 s1, s1, 0
	s_add_u32 s57, s57, 0x100
	s_addc_u32 s58, s58, 0
	s_cmp_gt_u32 s59, 13
	s_cbranch_scc0 .LBB0_260
	s_setprio 0
	v_lshl_or_b32 v172, s54, 8, v179
	v_ashrrev_i32_e32 v173, 31, v172
	v_cndmask_b32_e64 v131, 0, 1, s[2:3]
	v_lshl_add_u64 v[174:175], v[172:173], 2, s[8:9]
	v_mov_b32_e32 v130, 0
	v_cmp_ne_u32_e64 s[0:1], 1, v131
	s_andn2_b64 vcc, exec, s[2:3]
	v_mov_b32_e32 v134, 0
	v_mov_b32_e32 v135, 0
	v_mov_b32_e32 v136, 0
	v_mov_b32_e32 v137, 0
	s_cbranch_vccnz .LBB0_263
	global_load_dwordx4 v[134:137], v[174:175], off

.LBB0_330:
	s_add_u32 s40, s22, 0x100
	s_addc_u32 s41, s23, 0
	s_mov_b32 s51, -2
	v_mov_b64_e32 v[82:83], 0
	v_mov_b64_e32 v[84:85], 0
	s_nop 1
	v_mfma_f32_32x32x16_bf16 v[2:17], v[82:85], v[82:85], 0
	v_mov_b64_e32 v[114:115], 0
	v_mov_b64_e32 v[116:117], 0
	v_mov_b64_e32 v[118:119], 0
	v_mov_b64_e32 v[120:121], 0
	v_mov_b64_e32 v[122:123], 0
	v_mfma_f32_32x32x16_bf16 v[18:33], v[82:85], v[82:85], 0
	v_mov_b64_e32 v[124:125], 0
	v_mov_b64_e32 v[126:127], 0
	v_mov_b64_e32 v[128:129], 0
	v_mov_b64_e32 v[98:99], 0
	v_mov_b64_e32 v[100:101], 0
	v_mfma_f32_32x32x16_bf16 v[34:49], v[82:85], v[82:85], 0
	v_mov_b64_e32 v[102:103], 0
	v_mov_b64_e32 v[104:105], 0
	v_mov_b64_e32 v[106:107], 0
	v_mov_b64_e32 v[108:109], 0
	v_mov_b64_e32 v[110:111], 0
	v_mfma_f32_32x32x16_bf16 v[50:65], v[82:85], v[82:85], 0
	v_mov_b64_e32 v[112:113], 0
	v_mov_b64_e32 v[86:87], 0
	v_mov_b64_e32 v[88:89], 0
	v_mov_b64_e32 v[90:91], 0
	v_mov_b64_e32 v[92:93], 0
	v_mfma_f32_32x32x16_bf16 v[66:81], v[82:85], v[82:85], 0
	v_mov_b64_e32 v[94:95], 0
	v_mov_b64_e32 v[96:97], 0
	v_readfirstlane_b32 s98, v204
	s_lshr_b32 s98, s98, 8
	s_cmp_eq_u32 s98, 0
	s_cbranch_scc1 .Lkprio_2
	s_setprio 1
.Lkprio_2:
.LBB0_331:
	s_add_u32 s22, s24, 0x100
	s_addc_u32 s23, s25, 0
	s_add_i32 s52, 0, 0x10000
	v_add_u32_e32 v140, s52, v144
	ds_read_b128 v[164:167], v140
	ds_read_b128 v[168:171], v140 offset:1024
	ds_read_b128 v[172:175], v140 offset:2048
	ds_read_b128 v[176:179], v140 offset:3072
	s_cmp_eq_u32 s51, 40
	s_cselect_b32 s29, s3, s23
	s_cselect_b32 s28, s2, s22
	s_cselect_b32 s27, s1, s41
	s_cselect_b32 s26, s0, s40
	v_lshl_add_u64 v[140:141], s[24:25], 0, v[136:137]
	s_add_i32 m0, s35, 0xc000
	ds_read_b128 v[180:183], v162
	ds_read_b128 v[184:187], v162 offset:1024
	ds_read_b128 v[206:209], v162 offset:2048
	ds_read_b128 v[210:213], v162 offset:3072
	ds_read_b128 v[214:217], v162 offset:4096
	ds_read_b128 v[218:221], v162 offset:5120
	ds_read_b128 v[222:225], v162 offset:6144
	ds_read_b128 v[226:229], v162 offset:7168
	global_load_lds_dwordx4 v[140:141], off
	v_lshl_add_u64 v[140:141], s[24:25], 0, v[138:139]
	s_add_i32 m0, s35, 0xe000
	s_nop 0
	global_load_lds_dwordx4 v[140:141], off
	s_waitcnt lgkmcnt(8)
	s_barrier
	s_waitcnt lgkmcnt(0)
	v_mfma_f32_16x16x32_bf16 v[126:129], v[164:167], v[180:183], v[126:129]
	v_mfma_f32_16x16x32_bf16 v[122:125], v[172:175], v[180:183], v[122:125]
	v_mfma_f32_16x16x32_bf16 v[114:117], v[164:167], v[206:209], v[114:117]
	v_mfma_f32_16x16x32_bf16 v[106:109], v[172:175], v[206:209], v[106:109]
	v_mfma_f32_16x16x32_bf16 v[98:101], v[164:167], v[214:217], v[98:101]
	v_mfma_f32_16x16x32_bf16 v[90:93], v[172:175], v[214:217], v[90:93]
	v_mfma_f32_16x16x32_bf16 v[82:85], v[164:167], v[222:225], v[82:85]
	v_mfma_f32_16x16x32_bf16 v[74:77], v[172:175], v[222:225], v[74:77]
	v_mfma_f32_16x16x32_bf16 v[126:129], v[168:171], v[184:187], v[126:129]
	v_mfma_f32_16x16x32_bf16 v[122:125], v[176:179], v[184:187], v[122:125]
	v_mfma_f32_16x16x32_bf16 v[114:117], v[168:171], v[210:213], v[114:117]
	v_mfma_f32_16x16x32_bf16 v[106:109], v[176:179], v[210:213], v[106:109]
	v_mfma_f32_16x16x32_bf16 v[98:101], v[168:171], v[218:221], v[98:101]
	v_mfma_f32_16x16x32_bf16 v[90:93], v[176:179], v[218:221], v[90:93]
	v_mfma_f32_16x16x32_bf16 v[82:85], v[168:171], v[226:229], v[82:85]
	v_mfma_f32_16x16x32_bf16 v[74:77], v[176:179], v[226:229], v[74:77]
	s_barrier
	s_add_i32 s53, 0, 0x14000
	v_add_u32_e32 v140, s53, v144
	s_add_i32 s24, s52, s31
	ds_read_b128 v[230:233], v140
	ds_read_b128 v[234:237], v140 offset:1024
	ds_read_b128 v[238:241], v140 offset:2048
	ds_read_b128 v[242:245], v140 offset:3072
	v_lshl_add_u64 v[140:141], s[26:27], 0, v[0:1]
	s_mov_b32 m0, s24
	v_lshl_add_u64 v[246:247], s[26:27], 0, v[130:131]
	global_load_lds_dwordx4 v[140:141], off
	s_add_i32 m0, s24, 0x2000
	s_nop 0
	global_load_lds_dwordx4 v[246:247], off
	s_barrier
	s_waitcnt lgkmcnt(0)
	v_mfma_f32_16x16x32_bf16 v[118:121], v[230:233], v[180:183], v[118:121]
	v_mfma_f32_16x16x32_bf16 v[110:113], v[238:241], v[180:183], v[110:113]
	v_mfma_f32_16x16x32_bf16 v[102:105], v[230:233], v[206:209], v[102:105]
	v_mfma_f32_16x16x32_bf16 v[94:97], v[238:241], v[206:209], v[94:97]
	v_mfma_f32_16x16x32_bf16 v[86:89], v[230:233], v[214:217], v[86:89]
	v_mfma_f32_16x16x32_bf16 v[78:81], v[238:241], v[214:217], v[78:81]
	v_mfma_f32_16x16x32_bf16 v[70:73], v[230:233], v[222:225], v[70:73]
	v_mfma_f32_16x16x32_bf16 v[66:69], v[238:241], v[222:225], v[66:69]
	v_mfma_f32_16x16x32_bf16 v[118:121], v[234:237], v[184:187], v[118:121]
	v_mfma_f32_16x16x32_bf16 v[110:113], v[242:245], v[184:187], v[110:113]
	v_mfma_f32_16x16x32_bf16 v[102:105], v[234:237], v[210:213], v[102:105]
	v_mfma_f32_16x16x32_bf16 v[94:97], v[242:245], v[210:213], v[94:97]
	v_mfma_f32_16x16x32_bf16 v[86:89], v[234:237], v[218:221], v[86:89]
	v_mfma_f32_16x16x32_bf16 v[78:81], v[242:245], v[218:221], v[78:81]
	v_mfma_f32_16x16x32_bf16 v[70:73], v[234:237], v[226:229], v[70:73]
	v_mfma_f32_16x16x32_bf16 v[66:69], v[242:245], v[226:229], v[66:69]
	s_barrier
	s_mov_b32 m0, s35
	v_lshl_add_u64 v[248:249], s[28:29], 0, v[134:135]
	ds_read_b128 v[180:183], v162 offset:16384
	ds_read_b128 v[184:187], v162 offset:17408
	ds_read_b128 v[206:209], v162 offset:18432
	ds_read_b128 v[210:213], v162 offset:19456
	ds_read_b128 v[214:217], v162 offset:20480
	ds_read_b128 v[218:221], v162 offset:21504
	ds_read_b128 v[222:225], v162 offset:22528
	ds_read_b128 v[226:229], v162 offset:23552
	global_load_lds_dwordx4 v[248:249], off
	v_lshl_add_u64 v[250:251], s[28:29], 0, v[132:133]
	s_mov_b32 m0, s36
	s_nop 0
	global_load_lds_dwordx4 v[250:251], off
	s_barrier
	s_waitcnt lgkmcnt(0)
	v_mfma_f32_16x16x32_bf16 v[62:65], v[164:167], v[180:183], v[62:65]
	v_mfma_f32_16x16x32_bf16 v[58:61], v[172:175], v[180:183], v[58:61]
	v_mfma_f32_16x16x32_bf16 v[50:53], v[164:167], v[206:209], v[50:53]
	v_mfma_f32_16x16x32_bf16 v[42:45], v[172:175], v[206:209], v[42:45]
	v_mfma_f32_16x16x32_bf16 v[34:37], v[164:167], v[214:217], v[34:37]
	v_mfma_f32_16x16x32_bf16 v[26:29], v[172:175], v[214:217], v[26:29]
	v_mfma_f32_16x16x32_bf16 v[18:21], v[164:167], v[222:225], v[18:21]
	v_mfma_f32_16x16x32_bf16 v[10:13], v[172:175], v[222:225], v[10:13]
	v_mfma_f32_16x16x32_bf16 v[62:65], v[168:171], v[184:187], v[62:65]
	v_mfma_f32_16x16x32_bf16 v[58:61], v[176:179], v[184:187], v[58:61]
	v_mfma_f32_16x16x32_bf16 v[50:53], v[168:171], v[210:213], v[50:53]
	v_mfma_f32_16x16x32_bf16 v[42:45], v[176:179], v[210:213], v[42:45]
	v_mfma_f32_16x16x32_bf16 v[34:37], v[168:171], v[218:221], v[34:37]
	v_mfma_f32_16x16x32_bf16 v[26:29], v[176:179], v[218:221], v[26:29]
	v_mfma_f32_16x16x32_bf16 v[18:21], v[168:171], v[226:229], v[18:21]
	v_mfma_f32_16x16x32_bf16 v[10:13], v[176:179], v[226:229], v[10:13]
	s_barrier
	s_add_u32 s24, s26, 0xb0000
	s_addc_u32 s25, s27, 0
	s_add_i32 s52, s53, s31
	v_lshl_add_u64 v[164:165], s[24:25], 0, v[0:1]
	s_mov_b32 m0, s52
	s_nop 0
	global_load_lds_dwordx4 v[164:165], off
	v_lshl_add_u64 v[164:165], s[24:25], 0, v[130:131]
	s_add_i32 m0, s52, 0x2000
	s_nop 0
	global_load_lds_dwordx4 v[164:165], off
	s_waitcnt vmcnt(6)
	s_barrier
	v_mfma_f32_16x16x32_bf16 v[54:57], v[230:233], v[180:183], v[54:57]
	v_mfma_f32_16x16x32_bf16 v[46:49], v[238:241], v[180:183], v[46:49]
	v_mfma_f32_16x16x32_bf16 v[38:41], v[230:233], v[206:209], v[38:41]
	v_mfma_f32_16x16x32_bf16 v[30:33], v[238:241], v[206:209], v[30:33]
	v_mfma_f32_16x16x32_bf16 v[22:25], v[230:233], v[214:217], v[22:25]
	v_mfma_f32_16x16x32_bf16 v[14:17], v[238:241], v[214:217], v[14:17]
	v_mfma_f32_16x16x32_bf16 v[6:9], v[230:233], v[222:225], v[6:9]
	v_mfma_f32_16x16x32_bf16 v[2:5], v[238:241], v[222:225], v[2:5]
	v_mfma_f32_16x16x32_bf16 v[54:57], v[234:237], v[184:187], v[54:57]
	v_mfma_f32_16x16x32_bf16 v[46:49], v[242:245], v[184:187], v[46:49]
	v_mfma_f32_16x16x32_bf16 v[38:41], v[234:237], v[210:213], v[38:41]
	v_mfma_f32_16x16x32_bf16 v[30:33], v[242:245], v[210:213], v[30:33]
	v_mfma_f32_16x16x32_bf16 v[22:25], v[234:237], v[218:221], v[22:25]
	v_mfma_f32_16x16x32_bf16 v[14:17], v[242:245], v[218:221], v[14:17]
	v_mfma_f32_16x16x32_bf16 v[6:9], v[234:237], v[226:229], v[6:9]
	v_mfma_f32_16x16x32_bf16 v[2:5], v[242:245], v[226:229], v[2:5]
	s_barrier
	s_add_i32 s52, 0, 0x18000
	v_add_u32_e32 v163, s52, v144
	ds_read_b128 v[164:167], v163
	ds_read_b128 v[168:171], v163 offset:1024
	ds_read_b128 v[172:175], v163 offset:2048
	ds_read_b128 v[176:179], v163 offset:3072
	s_add_u32 s24, s28, 0xb0000
	s_addc_u32 s25, s29, 0
	s_mov_b32 m0, s37
	v_lshl_add_u64 v[230:231], s[24:25], 0, v[134:135]
	ds_read_b128 v[180:183], v162 offset:32768
	ds_read_b128 v[184:187], v162 offset:33792
	ds_read_b128 v[206:209], v162 offset:34816
	ds_read_b128 v[210:213], v162 offset:35840
	ds_read_b128 v[214:217], v162 offset:36864
	ds_read_b128 v[218:221], v162 offset:37888
	ds_read_b128 v[222:225], v162 offset:38912
	ds_read_b128 v[226:229], v162 offset:39936
	global_load_lds_dwordx4 v[230:231], off
	v_lshl_add_u64 v[230:231], s[24:25], 0, v[132:133]
	s_mov_b32 m0, s42
	s_nop 0
	global_load_lds_dwordx4 v[230:231], off
	s_waitcnt lgkmcnt(8)
	s_barrier
	s_waitcnt lgkmcnt(0)
	v_mfma_f32_16x16x32_bf16 v[126:129], v[164:167], v[180:183], v[126:129]
	v_mfma_f32_16x16x32_bf16 v[122:125], v[172:175], v[180:183], v[122:125]
	v_mfma_f32_16x16x32_bf16 v[114:117], v[164:167], v[206:209], v[114:117]
	v_mfma_f32_16x16x32_bf16 v[106:109], v[172:175], v[206:209], v[106:109]
	v_mfma_f32_16x16x32_bf16 v[98:101], v[164:167], v[214:217], v[98:101]
	v_mfma_f32_16x16x32_bf16 v[90:93], v[172:175], v[214:217], v[90:93]
	v_mfma_f32_16x16x32_bf16 v[82:85], v[164:167], v[222:225], v[82:85]
	v_mfma_f32_16x16x32_bf16 v[74:77], v[172:175], v[222:225], v[74:77]
	v_mfma_f32_16x16x32_bf16 v[126:129], v[168:171], v[184:187], v[126:129]
	v_mfma_f32_16x16x32_bf16 v[122:125], v[176:179], v[184:187], v[122:125]
	v_mfma_f32_16x16x32_bf16 v[114:117], v[168:171], v[210:213], v[114:117]
	v_mfma_f32_16x16x32_bf16 v[106:109], v[176:179], v[210:213], v[106:109]
	v_mfma_f32_16x16x32_bf16 v[98:101], v[168:171], v[218:221], v[98:101]
	v_mfma_f32_16x16x32_bf16 v[90:93], v[176:179], v[218:221], v[90:93]
	v_mfma_f32_16x16x32_bf16 v[82:85], v[168:171], v[226:229], v[82:85]
	v_mfma_f32_16x16x32_bf16 v[74:77], v[176:179], v[226:229], v[74:77]
	s_barrier
	s_add_i32 s28, 0, 0x1c000
	s_add_i32 s24, s52, s31
	v_add_u32_e32 v163, s28, v144
	v_lshl_add_u64 v[140:141], v[140:141], 0, s[94:95]
	s_mov_b32 m0, s24
	ds_read_b128 v[230:233], v163
	ds_read_b128 v[234:237], v163 offset:1024
	ds_read_b128 v[238:241], v163 offset:2048
	ds_read_b128 v[242:245], v163 offset:3072
	global_load_lds_dwordx4 v[140:141], off
	v_lshl_add_u64 v[140:141], v[246:247], 0, s[94:95]
	s_add_i32 m0, s24, 0x2000
	s_nop 0
	global_load_lds_dwordx4 v[140:141], off
	s_barrier
	s_waitcnt lgkmcnt(0)
	v_mfma_f32_16x16x32_bf16 v[118:121], v[230:233], v[180:183], v[118:121]
	v_mfma_f32_16x16x32_bf16 v[110:113], v[238:241], v[180:183], v[110:113]
	v_mfma_f32_16x16x32_bf16 v[102:105], v[230:233], v[206:209], v[102:105]
	v_mfma_f32_16x16x32_bf16 v[94:97], v[238:241], v[206:209], v[94:97]
	v_mfma_f32_16x16x32_bf16 v[86:89], v[230:233], v[214:217], v[86:89]
	v_mfma_f32_16x16x32_bf16 v[78:81], v[238:241], v[214:217], v[78:81]
	v_mfma_f32_16x16x32_bf16 v[70:73], v[230:233], v[222:225], v[70:73]
	v_mfma_f32_16x16x32_bf16 v[66:69], v[238:241], v[222:225], v[66:69]
	v_mfma_f32_16x16x32_bf16 v[118:121], v[234:237], v[184:187], v[118:121]
	v_mfma_f32_16x16x32_bf16 v[110:113], v[242:245], v[184:187], v[110:113]
	v_mfma_f32_16x16x32_bf16 v[102:105], v[234:237], v[210:213], v[102:105]
	v_mfma_f32_16x16x32_bf16 v[94:97], v[242:245], v[210:213], v[94:97]
	v_mfma_f32_16x16x32_bf16 v[86:89], v[234:237], v[218:221], v[86:89]
	v_mfma_f32_16x16x32_bf16 v[78:81], v[242:245], v[218:221], v[78:81]
	v_mfma_f32_16x16x32_bf16 v[70:73], v[234:237], v[226:229], v[70:73]
	v_mfma_f32_16x16x32_bf16 v[66:69], v[242:245], v[226:229], v[66:69]
	s_barrier
	s_mov_b32 m0, s44
	v_lshl_add_u64 v[140:141], v[248:249], 0, s[94:95]
	ds_read_b128 v[180:183], v162 offset:49152
	ds_read_b128 v[184:187], v162 offset:50176
	ds_read_b128 v[206:209], v162 offset:51200
	ds_read_b128 v[210:213], v162 offset:52224
	ds_read_b128 v[214:217], v162 offset:53248
	ds_read_b128 v[218:221], v162 offset:54272
	ds_read_b128 v[222:225], v162 offset:55296
	ds_read_b128 v[226:229], v162 offset:56320
	global_load_lds_dwordx4 v[140:141], off
	v_lshl_add_u64 v[140:141], v[250:251], 0, s[94:95]
	s_mov_b32 m0, s45
	s_nop 0
	global_load_lds_dwordx4 v[140:141], off
	s_barrier
	s_waitcnt lgkmcnt(0)
	v_mfma_f32_16x16x32_bf16 v[62:65], v[164:167], v[180:183], v[62:65]
	v_mfma_f32_16x16x32_bf16 v[58:61], v[172:175], v[180:183], v[58:61]
	v_mfma_f32_16x16x32_bf16 v[50:53], v[164:167], v[206:209], v[50:53]
	v_mfma_f32_16x16x32_bf16 v[42:45], v[172:175], v[206:209], v[42:45]
	v_mfma_f32_16x16x32_bf16 v[34:37], v[164:167], v[214:217], v[34:37]
	v_mfma_f32_16x16x32_bf16 v[26:29], v[172:175], v[214:217], v[26:29]
	v_mfma_f32_16x16x32_bf16 v[18:21], v[164:167], v[222:225], v[18:21]
	v_mfma_f32_16x16x32_bf16 v[10:13], v[172:175], v[222:225], v[10:13]
	v_mfma_f32_16x16x32_bf16 v[62:65], v[168:171], v[184:187], v[62:65]
	v_mfma_f32_16x16x32_bf16 v[58:61], v[176:179], v[184:187], v[58:61]
	v_mfma_f32_16x16x32_bf16 v[50:53], v[168:171], v[210:213], v[50:53]
	v_mfma_f32_16x16x32_bf16 v[42:45], v[176:179], v[210:213], v[42:45]
	v_mfma_f32_16x16x32_bf16 v[34:37], v[168:171], v[218:221], v[34:37]
	v_mfma_f32_16x16x32_bf16 v[26:29], v[176:179], v[218:221], v[26:29]
	v_mfma_f32_16x16x32_bf16 v[18:21], v[168:171], v[226:229], v[18:21]
	v_mfma_f32_16x16x32_bf16 v[10:13], v[176:179], v[226:229], v[10:13]
	s_barrier
	s_add_u32 s24, s26, 0xb0080
	s_addc_u32 s25, s27, 0
	s_add_i32 s26, s28, s31
	v_lshl_add_u64 v[140:141], s[24:25], 0, v[0:1]
	s_mov_b32 m0, s26
	s_nop 0
	global_load_lds_dwordx4 v[140:141], off
	v_lshl_add_u64 v[140:141], s[24:25], 0, v[130:131]
	s_add_i32 m0, s26, 0x2000
	s_nop 0
	global_load_lds_dwordx4 v[140:141], off
	s_waitcnt vmcnt(6)
	s_barrier
	v_mfma_f32_16x16x32_bf16 v[54:57], v[230:233], v[180:183], v[54:57]
	v_mfma_f32_16x16x32_bf16 v[46:49], v[238:241], v[180:183], v[46:49]
	v_mfma_f32_16x16x32_bf16 v[38:41], v[230:233], v[206:209], v[38:41]
	v_mfma_f32_16x16x32_bf16 v[30:33], v[238:241], v[206:209], v[30:33]
	v_mfma_f32_16x16x32_bf16 v[22:25], v[230:233], v[214:217], v[22:25]
	v_mfma_f32_16x16x32_bf16 v[14:17], v[238:241], v[214:217], v[14:17]
	v_mfma_f32_16x16x32_bf16 v[6:9], v[230:233], v[222:225], v[6:9]
	v_mfma_f32_16x16x32_bf16 v[2:5], v[238:241], v[222:225], v[2:5]
	v_mfma_f32_16x16x32_bf16 v[54:57], v[234:237], v[184:187], v[54:57]
	v_mfma_f32_16x16x32_bf16 v[46:49], v[242:245], v[184:187], v[46:49]
	v_mfma_f32_16x16x32_bf16 v[38:41], v[234:237], v[210:213], v[38:41]
	v_mfma_f32_16x16x32_bf16 v[30:33], v[242:245], v[210:213], v[30:33]
	v_mfma_f32_16x16x32_bf16 v[22:25], v[234:237], v[218:221], v[22:25]
	v_mfma_f32_16x16x32_bf16 v[14:17], v[242:245], v[218:221], v[14:17]
	v_mfma_f32_16x16x32_bf16 v[6:9], v[234:237], v[226:229], v[6:9]
	v_mfma_f32_16x16x32_bf16 v[2:5], v[242:245], v[226:229], v[2:5]
	s_barrier
	s_add_i32 s51, s51, 2
	s_add_u32 s40, s40, 0x100
	s_addc_u32 s41, s41, 0
	s_cmp_gt_u32 s51, 41
	s_mov_b64 s[24:25], s[22:23]
	s_cbranch_scc0 .LBB0_331
	s_setprio 0
	v_lshl_or_b32 v140, s50, 8, v145
	v_lshl_add_u32 v164, s49, 8, v143
	v_ashrrev_i32_e32 v141, 31, v140
	v_ashrrev_i32_e32 v165, 31, v164
	v_lshl_add_u64 v[166:167], v[140:141], 1, s[20:21]
	v_lshlrev_b64 v[140:141], 11, v[164:165]
	v_lshl_add_u64 v[140:141], v[166:167], 0, v[140:141]
	v_pk_add_f32 v[128:129], v[128:129], 0 op_sel_hi:[1,0]
	v_pk_add_f32 v[126:127], v[126:127], 0 op_sel_hi:[1,0]
	v_pk_add_f32 v[168:169], v[124:125], 0 op_sel_hi:[1,0]
	v_pk_add_f32 v[124:125], v[122:123], 0 op_sel_hi:[1,0]
	v_cvt_pk_bf16_f32 v122, v126, v127
	v_cvt_pk_bf16_f32 v123, v128, v129
	v_pk_add_f32 v[118:119], v[118:119], 0 op_sel_hi:[1,0]
	v_cvt_pk_bf16_f32 v124, v124, v125
	v_cvt_pk_bf16_f32 v125, v168, v169
	global_store_dwordx4 v[140:141], v[122:125], off
	v_pk_add_f32 v[120:121], v[120:121], 0 op_sel_hi:[1,0]
	v_pk_add_f32 v[114:115], v[114:115], 0 op_sel_hi:[1,0]
	v_pk_add_f32 v[122:123], v[112:113], 0 op_sel_hi:[1,0]
	v_pk_add_f32 v[112:113], v[110:111], 0 op_sel_hi:[1,0]
	v_cvt_pk_bf16_f32 v110, v118, v119
	v_cvt_pk_bf16_f32 v111, v120, v121
	v_pk_add_f32 v[102:103], v[102:103], 0 op_sel_hi:[1,0]
	v_cvt_pk_bf16_f32 v112, v112, v113
	v_cvt_pk_bf16_f32 v113, v122, v123
	global_store_dwordx4 v[140:141], v[110:113], off offset:256
	v_pk_add_f32 v[104:105], v[104:105], 0 op_sel_hi:[1,0]
	v_pk_add_f32 v[98:99], v[98:99], 0 op_sel_hi:[1,0]
	v_or_b32_e32 v110, 16, v164
	v_ashrrev_i32_e32 v111, 31, v110
	v_lshlrev_b64 v[110:111], 11, v[110:111]
	v_lshl_add_u64 v[110:111], v[166:167], 0, v[110:111]
	v_pk_add_f32 v[112:113], v[116:117], 0 op_sel_hi:[1,0]
	v_pk_add_f32 v[116:117], v[108:109], 0 op_sel_hi:[1,0]
	v_pk_add_f32 v[108:109], v[106:107], 0 op_sel_hi:[1,0]
	v_cvt_pk_bf16_f32 v106, v114, v115
	v_cvt_pk_bf16_f32 v107, v112, v113
	v_pk_add_f32 v[86:87], v[86:87], 0 op_sel_hi:[1,0]
	v_cvt_pk_bf16_f32 v108, v108, v109
	v_cvt_pk_bf16_f32 v109, v116, v117
	global_store_dwordx4 v[110:111], v[106:109], off
	v_pk_add_f32 v[88:89], v[88:89], 0 op_sel_hi:[1,0]
	v_pk_add_f32 v[82:83], v[82:83], 0 op_sel_hi:[1,0]
	v_pk_add_f32 v[106:107], v[96:97], 0 op_sel_hi:[1,0]
	v_pk_add_f32 v[96:97], v[94:95], 0 op_sel_hi:[1,0]
	v_cvt_pk_bf16_f32 v94, v102, v103
	v_cvt_pk_bf16_f32 v95, v104, v105
	v_pk_add_f32 v[72:73], v[72:73], 0 op_sel_hi:[1,0]
	v_cvt_pk_bf16_f32 v96, v96, v97
	v_cvt_pk_bf16_f32 v97, v106, v107
	global_store_dwordx4 v[110:111], v[94:97], off offset:256
	v_pk_add_f32 v[70:71], v[70:71], 0 op_sel_hi:[1,0]
	v_pk_add_f32 v[62:63], v[62:63], 0 op_sel_hi:[1,0]
	v_or_b32_e32 v94, 32, v164
	v_ashrrev_i32_e32 v95, 31, v94
	v_lshlrev_b64 v[94:95], 11, v[94:95]
	v_lshl_add_u64 v[94:95], v[166:167], 0, v[94:95]
	v_pk_add_f32 v[96:97], v[100:101], 0 op_sel_hi:[1,0]
	v_pk_add_f32 v[100:101], v[92:93], 0 op_sel_hi:[1,0]
	v_pk_add_f32 v[92:93], v[90:91], 0 op_sel_hi:[1,0]
	v_cvt_pk_bf16_f32 v90, v98, v99
	v_cvt_pk_bf16_f32 v91, v96, v97
	v_pk_add_f32 v[64:65], v[64:65], 0 op_sel_hi:[1,0]
	v_cvt_pk_bf16_f32 v92, v92, v93
	v_cvt_pk_bf16_f32 v93, v100, v101
	global_store_dwordx4 v[94:95], v[90:93], off
	s_mov_b64 s[22:23], 0x40000
	v_pk_add_f32 v[56:57], v[56:57], 0 op_sel_hi:[1,0]
	v_pk_add_f32 v[90:91], v[80:81], 0 op_sel_hi:[1,0]
	v_pk_add_f32 v[80:81], v[78:79], 0 op_sel_hi:[1,0]
	v_cvt_pk_bf16_f32 v78, v86, v87
	v_cvt_pk_bf16_f32 v79, v88, v89
	v_pk_add_f32 v[54:55], v[54:55], 0 op_sel_hi:[1,0]
	v_cvt_pk_bf16_f32 v80, v80, v81
	v_cvt_pk_bf16_f32 v81, v90, v91
	global_store_dwordx4 v[94:95], v[78:81], off offset:256
	v_pk_add_f32 v[50:51], v[50:51], 0 op_sel_hi:[1,0]
	v_pk_add_f32 v[40:41], v[40:41], 0 op_sel_hi:[1,0]
	v_or_b32_e32 v78, 48, v164
	v_ashrrev_i32_e32 v79, 31, v78
	v_lshlrev_b64 v[78:79], 11, v[78:79]
	v_lshl_add_u64 v[78:79], v[166:167], 0, v[78:79]
	v_pk_add_f32 v[80:81], v[84:85], 0 op_sel_hi:[1,0]
	v_pk_add_f32 v[84:85], v[76:77], 0 op_sel_hi:[1,0]
	v_pk_add_f32 v[76:77], v[74:75], 0 op_sel_hi:[1,0]
	v_cvt_pk_bf16_f32 v74, v82, v83
	v_cvt_pk_bf16_f32 v75, v80, v81
	v_pk_add_f32 v[38:39], v[38:39], 0 op_sel_hi:[1,0]
	v_cvt_pk_bf16_f32 v76, v76, v77
	v_cvt_pk_bf16_f32 v77, v84, v85
	global_store_dwordx4 v[78:79], v[74:77], off
	v_pk_add_f32 v[34:35], v[34:35], 0 op_sel_hi:[1,0]
	v_pk_add_f32 v[24:25], v[24:25], 0 op_sel_hi:[1,0]
	v_pk_add_f32 v[74:75], v[68:69], 0 op_sel_hi:[1,0]
	v_pk_add_f32 v[68:69], v[66:67], 0 op_sel_hi:[1,0]
	v_cvt_pk_bf16_f32 v66, v70, v71
	v_cvt_pk_bf16_f32 v67, v72, v73
	v_pk_add_f32 v[22:23], v[22:23], 0 op_sel_hi:[1,0]
	v_cvt_pk_bf16_f32 v68, v68, v69
	v_cvt_pk_bf16_f32 v69, v74, v75
	global_store_dwordx4 v[78:79], v[66:69], off offset:256
	v_pk_add_f32 v[18:19], v[18:19], 0 op_sel_hi:[1,0]
	s_mov_b32 s50, s47
	v_pk_add_f32 v[68:69], v[60:61], 0 op_sel_hi:[1,0]
	v_pk_add_f32 v[60:61], v[58:59], 0 op_sel_hi:[1,0]
	v_cvt_pk_bf16_f32 v58, v62, v63
	v_add_co_u32_e32 v62, vcc, s67, v140
	v_cvt_pk_bf16_f32 v59, v64, v65
	v_cvt_pk_bf16_f32 v60, v60, v61
	v_cvt_pk_bf16_f32 v61, v68, v69
	v_lshl_add_u64 v[66:67], v[140:141], 0, s[22:23]
	s_nop 0
	v_addc_co_u32_e32 v63, vcc, 0, v141, vcc
	global_store_dwordx4 v[62:63], v[58:61], off
	s_mov_b64 s[22:23], 0x48000
	s_mov_b32 s49, s48
	v_pk_add_f32 v[58:59], v[48:49], 0 op_sel_hi:[1,0]
	v_pk_add_f32 v[48:49], v[46:47], 0 op_sel_hi:[1,0]
	v_cvt_pk_bf16_f32 v46, v54, v55
	v_cvt_pk_bf16_f32 v47, v56, v57
	s_mov_b64 s[24:25], s[2:3]
	v_cvt_pk_bf16_f32 v48, v48, v49
	v_cvt_pk_bf16_f32 v49, v58, v59
	global_store_dwordx4 v[66:67], v[46:49], off offset:256
	v_pk_add_f32 v[8:9], v[8:9], 0 op_sel_hi:[1,0]
	v_pk_add_f32 v[6:7], v[6:7], 0 op_sel_hi:[1,0]
	v_pk_add_f32 v[48:49], v[52:53], 0 op_sel_hi:[1,0]
	v_pk_add_f32 v[52:53], v[44:45], 0 op_sel_hi:[1,0]
	v_pk_add_f32 v[44:45], v[42:43], 0 op_sel_hi:[1,0]
	v_cvt_pk_bf16_f32 v42, v50, v51
	v_cvt_pk_bf16_f32 v43, v48, v49
	v_add_co_u32_e32 v48, vcc, s68, v140
	v_cvt_pk_bf16_f32 v44, v44, v45
	v_cvt_pk_bf16_f32 v45, v52, v53
	v_lshl_add_u64 v[46:47], v[140:141], 0, s[22:23]
	s_nop 0
	v_addc_co_u32_e32 v49, vcc, 0, v141, vcc
	global_store_dwordx4 v[48:49], v[42:45], off
	s_mov_b64 s[22:23], 0x50000
	s_nop 0
	v_pk_add_f32 v[42:43], v[32:33], 0 op_sel_hi:[1,0]
	v_pk_add_f32 v[32:33], v[30:31], 0 op_sel_hi:[1,0]
	v_cvt_pk_bf16_f32 v30, v38, v39
	v_cvt_pk_bf16_f32 v31, v40, v41
	s_nop 0
	v_cvt_pk_bf16_f32 v32, v32, v33
	v_cvt_pk_bf16_f32 v33, v42, v43
	global_store_dwordx4 v[46:47], v[30:33], off offset:256
	s_nop 1
	v_lshl_add_u64 v[30:31], v[140:141], 0, s[22:23]
	v_pk_add_f32 v[32:33], v[36:37], 0 op_sel_hi:[1,0]
	s_mov_b32 s22, 0x50000
	v_pk_add_f32 v[36:37], v[28:29], 0 op_sel_hi:[1,0]
	v_pk_add_f32 v[28:29], v[26:27], 0 op_sel_hi:[1,0]
	v_cvt_pk_bf16_f32 v26, v34, v35
	v_cvt_pk_bf16_f32 v27, v32, v33
	v_add_co_u32_e32 v32, vcc, s22, v140
	v_cvt_pk_bf16_f32 v28, v28, v29
	v_cvt_pk_bf16_f32 v29, v36, v37
	s_mov_b64 s[22:23], 0x58000
	s_nop 0
	v_addc_co_u32_e32 v33, vcc, 0, v141, vcc
	global_store_dwordx4 v[32:33], v[26:29], off
	s_nop 1
	v_pk_add_f32 v[26:27], v[16:17], 0 op_sel_hi:[1,0]
	v_pk_add_f32 v[16:17], v[14:15], 0 op_sel_hi:[1,0]
	v_cvt_pk_bf16_f32 v14, v22, v23
	v_cvt_pk_bf16_f32 v15, v24, v25
	s_nop 0
	v_cvt_pk_bf16_f32 v16, v16, v17
	v_cvt_pk_bf16_f32 v17, v26, v27
	global_store_dwordx4 v[30:31], v[14:17], off offset:256
	s_nop 1
	v_lshl_add_u64 v[14:15], v[140:141], 0, s[22:23]
	v_pk_add_f32 v[16:17], v[20:21], 0 op_sel_hi:[1,0]
	s_mov_b32 s22, 0x58000
	v_pk_add_f32 v[20:21], v[12:13], 0 op_sel_hi:[1,0]
	v_pk_add_f32 v[12:13], v[10:11], 0 op_sel_hi:[1,0]
	v_cvt_pk_bf16_f32 v10, v18, v19
	v_cvt_pk_bf16_f32 v11, v16, v17
	v_add_co_u32_e32 v16, vcc, s22, v140
	v_cvt_pk_bf16_f32 v12, v12, v13
	v_cvt_pk_bf16_f32 v13, v20, v21
	s_mov_b64 s[22:23], s[0:1]
	s_nop 0
	v_addc_co_u32_e32 v17, vcc, 0, v141, vcc
	global_store_dwordx4 v[16:17], v[10:13], off
	s_and_b64 vcc, exec, s[38:39]
	s_nop 0
	v_pk_add_f32 v[10:11], v[4:5], 0 op_sel_hi:[1,0]
	v_pk_add_f32 v[4:5], v[2:3], 0 op_sel_hi:[1,0]
	v_cvt_pk_bf16_f32 v2, v6, v7
	v_cvt_pk_bf16_f32 v3, v8, v9
	s_nop 0
	v_cvt_pk_bf16_f32 v4, v4, v5
	v_cvt_pk_bf16_f32 v5, v10, v11
	global_store_dwordx4 v[14:15], v[2:5], off offset:256
	s_cbranch_vccz .LBB0_320
	s_waitcnt vmcnt(16)
	s_cmpk_gt_u32 s30, 0xff
	s_cbranch_scc1 .LBB0_335
	s_barrier

.LBB0_359:
	s_ashr_i32 s35, s34, 31
	v_cmp_lt_i64_e32 vcc, s[36:37], v[156:157]
	s_lshl_b64 s[36:37], s[34:35], 19
	s_add_u32 s36, s12, s36
	s_addc_u32 s37, s13, s37
	s_and_b64 s[40:41], vcc, exec
	s_cselect_b32 s1, s37, s45
	s_cselect_b32 s3, s36, s44
	s_ashr_i32 s31, s30, 31
	s_lshl_b64 s[40:41], s[30:31], 19
	s_add_u32 s40, s48, s40
	s_addc_u32 s41, s49, s41
	s_and_b64 s[46:47], vcc, exec
	s_cselect_b32 s31, s41, s43
	s_cselect_b32 s35, s40, s42
	s_add_u32 s60, s42, 0x100
	s_addc_u32 s61, s43, 0
	s_add_u32 s42, s44, 0x40080
	s_addc_u32 s43, s45, 0
	s_mov_b32 s62, -2
	v_mov_b64_e32 v[98:99], 0
	v_mov_b64_e32 v[100:101], 0
	s_nop 1
	v_mfma_f32_32x32x16_bf16 v[2:17], v[98:101], v[98:101], 0
	v_mov_b64_e32 v[130:131], 0
	v_mov_b64_e32 v[132:133], 0
	v_mov_b64_e32 v[134:135], 0
	v_mov_b64_e32 v[136:137], 0
	v_mov_b64_e32 v[138:139], 0
	v_mfma_f32_32x32x16_bf16 v[18:33], v[98:101], v[98:101], 0
	v_mov_b64_e32 v[140:141], 0
	v_mov_b64_e32 v[142:143], 0
	v_mov_b64_e32 v[144:145], 0
	v_mov_b64_e32 v[114:115], 0
	v_mov_b64_e32 v[116:117], 0
	v_mfma_f32_32x32x16_bf16 v[34:49], v[98:101], v[98:101], 0
	v_mov_b64_e32 v[118:119], 0
	v_mov_b64_e32 v[120:121], 0
	v_mov_b64_e32 v[122:123], 0
	v_mov_b64_e32 v[124:125], 0
	v_mov_b64_e32 v[126:127], 0
	v_mfma_f32_32x32x16_bf16 v[50:65], v[98:101], v[98:101], 0
	v_mov_b64_e32 v[128:129], 0
	v_mov_b64_e32 v[102:103], 0
	v_mov_b64_e32 v[104:105], 0
	v_mov_b64_e32 v[106:107], 0
	v_mov_b64_e32 v[108:109], 0
	v_mfma_f32_32x32x16_bf16 v[66:81], v[98:101], v[98:101], 0
	v_mov_b64_e32 v[110:111], 0
	v_mov_b64_e32 v[112:113], 0
	v_readfirstlane_b32 s98, v204
	s_lshr_b32 s98, s98, 8
	s_cmp_eq_u32 s98, 0
	s_cbranch_scc1 .Lkprio_1
	s_setprio 1
.Lkprio_1:
.LBB0_360:
	s_add_u32 s44, s42, 0xfffc0080
	s_addc_u32 s45, s43, -1
	s_add_i32 s63, 0, 0x10000
	v_add_u32_e32 v0, s63, v206
	ds_read_b128 v[82:85], v0
	ds_read_b128 v[86:89], v0 offset:1024
	ds_read_b128 v[90:93], v0 offset:2048
	ds_read_b128 v[94:97], v0 offset:3072
	s_cmp_eq_u32 s62, 12
	s_cselect_b32 s47, s1, s45
	s_cselect_b32 s46, s3, s44
	s_cselect_b32 s45, s31, s61
	s_cselect_b32 s44, s35, s60
	v_lshl_add_u64 v[230:231], s[42:43], 0, v[174:175]
	s_add_i32 m0, s51, 0xc000
	ds_read_b128 v[176:179], v208
	ds_read_b128 v[180:183], v208 offset:1024
	ds_read_b128 v[184:187], v208 offset:2048
	ds_read_b128 v[210:213], v208 offset:3072
	ds_read_b128 v[214:217], v208 offset:4096
	ds_read_b128 v[218:221], v208 offset:5120
	ds_read_b128 v[222:225], v208 offset:6144
	ds_read_b128 v[226:229], v208 offset:7168
	global_load_lds_dwordx4 v[230:231], off
	v_lshl_add_u64 v[230:231], s[42:43], 0, v[172:173]
	s_add_i32 m0, s51, 0xe000
	s_nop 0
	global_load_lds_dwordx4 v[230:231], off
	s_waitcnt lgkmcnt(8)
	s_barrier
	s_waitcnt lgkmcnt(0)
	v_mfma_f32_16x16x32_bf16 v[142:145], v[82:85], v[176:179], v[142:145]
	v_mfma_f32_16x16x32_bf16 v[138:141], v[90:93], v[176:179], v[138:141]
	v_mfma_f32_16x16x32_bf16 v[126:129], v[82:85], v[184:187], v[126:129]
	v_mfma_f32_16x16x32_bf16 v[122:125], v[90:93], v[184:187], v[122:125]
	v_mfma_f32_16x16x32_bf16 v[110:113], v[82:85], v[214:217], v[110:113]
	v_mfma_f32_16x16x32_bf16 v[106:109], v[90:93], v[214:217], v[106:109]
	v_mfma_f32_16x16x32_bf16 v[78:81], v[82:85], v[222:225], v[78:81]
	v_mfma_f32_16x16x32_bf16 v[74:77], v[90:93], v[222:225], v[74:77]
	v_mfma_f32_16x16x32_bf16 v[142:145], v[86:89], v[180:183], v[142:145]
	v_mfma_f32_16x16x32_bf16 v[138:141], v[94:97], v[180:183], v[138:141]
	v_mfma_f32_16x16x32_bf16 v[126:129], v[86:89], v[210:213], v[126:129]
	v_mfma_f32_16x16x32_bf16 v[122:125], v[94:97], v[210:213], v[122:125]
	v_mfma_f32_16x16x32_bf16 v[110:113], v[86:89], v[218:221], v[110:113]
	v_mfma_f32_16x16x32_bf16 v[106:109], v[94:97], v[218:221], v[106:109]
	v_mfma_f32_16x16x32_bf16 v[78:81], v[86:89], v[226:229], v[78:81]
	v_mfma_f32_16x16x32_bf16 v[74:77], v[94:97], v[226:229], v[74:77]
	s_barrier
	s_add_i32 s66, 0, 0x14000
	s_add_i32 s63, s63, s50
	v_add_u32_e32 v0, s66, v206
	v_lshl_add_u64 v[246:247], s[44:45], 0, v[164:165]
	s_mov_b32 m0, s63
	ds_read_b128 v[230:233], v0
	ds_read_b128 v[234:237], v0 offset:1024
	ds_read_b128 v[238:241], v0 offset:2048
	ds_read_b128 v[242:245], v0 offset:3072
	global_load_lds_dwordx4 v[246:247], off
	v_lshl_add_u64 v[248:249], s[44:45], 0, v[168:169]
	s_add_i32 m0, s63, 0x2000
	s_nop 0
	global_load_lds_dwordx4 v[248:249], off
	s_barrier
	s_waitcnt lgkmcnt(0)
	v_mfma_f32_16x16x32_bf16 v[134:137], v[230:233], v[176:179], v[134:137]
	v_mfma_f32_16x16x32_bf16 v[130:133], v[238:241], v[176:179], v[130:133]
	v_mfma_f32_16x16x32_bf16 v[118:121], v[230:233], v[184:187], v[118:121]
	v_mfma_f32_16x16x32_bf16 v[114:117], v[238:241], v[184:187], v[114:117]
	v_mfma_f32_16x16x32_bf16 v[102:105], v[230:233], v[214:217], v[102:105]
	v_mfma_f32_16x16x32_bf16 v[98:101], v[238:241], v[214:217], v[98:101]
	v_mfma_f32_16x16x32_bf16 v[70:73], v[230:233], v[222:225], v[70:73]
	v_mfma_f32_16x16x32_bf16 v[66:69], v[238:241], v[222:225], v[66:69]
	v_mfma_f32_16x16x32_bf16 v[134:137], v[234:237], v[180:183], v[134:137]
	v_mfma_f32_16x16x32_bf16 v[130:133], v[242:245], v[180:183], v[130:133]
	v_mfma_f32_16x16x32_bf16 v[118:121], v[234:237], v[210:213], v[118:121]
	v_mfma_f32_16x16x32_bf16 v[114:117], v[242:245], v[210:213], v[114:117]
	v_mfma_f32_16x16x32_bf16 v[102:105], v[234:237], v[218:221], v[102:105]
	v_mfma_f32_16x16x32_bf16 v[98:101], v[242:245], v[218:221], v[98:101]
	v_mfma_f32_16x16x32_bf16 v[70:73], v[234:237], v[226:229], v[70:73]
	v_mfma_f32_16x16x32_bf16 v[66:69], v[242:245], v[226:229], v[66:69]
	s_barrier
	s_mov_b32 m0, s51
	v_lshl_add_u64 v[250:251], s[46:47], 0, v[162:163]
	ds_read_b128 v[176:179], v208 offset:16384
	ds_read_b128 v[180:183], v208 offset:17408
	ds_read_b128 v[184:187], v208 offset:18432
	ds_read_b128 v[210:213], v208 offset:19456
	ds_read_b128 v[214:217], v208 offset:20480
	ds_read_b128 v[218:221], v208 offset:21504
	ds_read_b128 v[222:225], v208 offset:22528
	ds_read_b128 v[226:229], v208 offset:23552
	global_load_lds_dwordx4 v[250:251], off
	v_lshl_add_u64 v[252:253], s[46:47], 0, v[166:167]
	s_mov_b32 m0, s52
	s_nop 0
	global_load_lds_dwordx4 v[252:253], off
	s_barrier
	s_waitcnt lgkmcnt(0)
	v_mfma_f32_16x16x32_bf16 v[62:65], v[82:85], v[176:179], v[62:65]
	v_mfma_f32_16x16x32_bf16 v[58:61], v[90:93], v[176:179], v[58:61]
	v_mfma_f32_16x16x32_bf16 v[46:49], v[82:85], v[184:187], v[46:49]
	v_mfma_f32_16x16x32_bf16 v[42:45], v[90:93], v[184:187], v[42:45]
	v_mfma_f32_16x16x32_bf16 v[30:33], v[82:85], v[214:217], v[30:33]
	v_mfma_f32_16x16x32_bf16 v[26:29], v[90:93], v[214:217], v[26:29]
	v_mfma_f32_16x16x32_bf16 v[14:17], v[82:85], v[222:225], v[14:17]
	v_mfma_f32_16x16x32_bf16 v[10:13], v[90:93], v[222:225], v[10:13]
	v_mfma_f32_16x16x32_bf16 v[62:65], v[86:89], v[180:183], v[62:65]
	v_mfma_f32_16x16x32_bf16 v[58:61], v[94:97], v[180:183], v[58:61]
	v_mfma_f32_16x16x32_bf16 v[46:49], v[86:89], v[210:213], v[46:49]
	v_mfma_f32_16x16x32_bf16 v[42:45], v[94:97], v[210:213], v[42:45]
	v_mfma_f32_16x16x32_bf16 v[30:33], v[86:89], v[218:221], v[30:33]
	v_mfma_f32_16x16x32_bf16 v[26:29], v[94:97], v[218:221], v[26:29]
	v_mfma_f32_16x16x32_bf16 v[14:17], v[86:89], v[226:229], v[14:17]
	v_mfma_f32_16x16x32_bf16 v[10:13], v[94:97], v[226:229], v[10:13]
	s_barrier
	s_add_u32 s64, s44, 0x40000
	s_addc_u32 s65, s45, 0
	s_add_i32 s63, s66, s50
	v_lshl_add_u64 v[82:83], s[64:65], 0, v[164:165]
	s_mov_b32 m0, s63
	s_nop 0
	global_load_lds_dwordx4 v[82:83], off
	v_lshl_add_u64 v[82:83], s[64:65], 0, v[168:169]
	s_add_i32 m0, s63, 0x2000
	s_nop 0
	global_load_lds_dwordx4 v[82:83], off
	s_waitcnt vmcnt(6)
	s_barrier
	v_mfma_f32_16x16x32_bf16 v[54:57], v[230:233], v[176:179], v[54:57]
	v_mfma_f32_16x16x32_bf16 v[50:53], v[238:241], v[176:179], v[50:53]
	v_mfma_f32_16x16x32_bf16 v[38:41], v[230:233], v[184:187], v[38:41]
	v_mfma_f32_16x16x32_bf16 v[34:37], v[238:241], v[184:187], v[34:37]
	v_mfma_f32_16x16x32_bf16 v[22:25], v[230:233], v[214:217], v[22:25]
	v_mfma_f32_16x16x32_bf16 v[18:21], v[238:241], v[214:217], v[18:21]
	v_mfma_f32_16x16x32_bf16 v[6:9], v[230:233], v[222:225], v[6:9]
	v_mfma_f32_16x16x32_bf16 v[2:5], v[238:241], v[222:225], v[2:5]
	v_mfma_f32_16x16x32_bf16 v[54:57], v[234:237], v[180:183], v[54:57]
	v_mfma_f32_16x16x32_bf16 v[50:53], v[242:245], v[180:183], v[50:53]
	v_mfma_f32_16x16x32_bf16 v[38:41], v[234:237], v[210:213], v[38:41]
	v_mfma_f32_16x16x32_bf16 v[34:37], v[242:245], v[210:213], v[34:37]
	v_mfma_f32_16x16x32_bf16 v[22:25], v[234:237], v[218:221], v[22:25]
	v_mfma_f32_16x16x32_bf16 v[18:21], v[242:245], v[218:221], v[18:21]
	v_mfma_f32_16x16x32_bf16 v[6:9], v[234:237], v[226:229], v[6:9]
	v_mfma_f32_16x16x32_bf16 v[2:5], v[242:245], v[226:229], v[2:5]
	s_barrier
	s_add_i32 s63, 0, 0x18000
	v_add_u32_e32 v0, s63, v206
	ds_read_b128 v[82:85], v0
	ds_read_b128 v[86:89], v0 offset:1024
	ds_read_b128 v[90:93], v0 offset:2048
	ds_read_b128 v[94:97], v0 offset:3072
	s_add_u32 s46, s46, 0x40000
	s_addc_u32 s47, s47, 0
	s_mov_b32 m0, s53
	v_lshl_add_u64 v[230:231], s[46:47], 0, v[162:163]
	ds_read_b128 v[176:179], v208 offset:32768
	ds_read_b128 v[180:183], v208 offset:33792
	ds_read_b128 v[184:187], v208 offset:34816
	ds_read_b128 v[210:213], v208 offset:35840
	ds_read_b128 v[214:217], v208 offset:36864
	ds_read_b128 v[218:221], v208 offset:37888
	ds_read_b128 v[222:225], v208 offset:38912
	ds_read_b128 v[226:229], v208 offset:39936
	global_load_lds_dwordx4 v[230:231], off
	v_lshl_add_u64 v[230:231], s[46:47], 0, v[166:167]
	s_mov_b32 m0, s54
	s_nop 0
	global_load_lds_dwordx4 v[230:231], off
	s_waitcnt lgkmcnt(8)
	s_barrier
	s_waitcnt lgkmcnt(0)
	v_mfma_f32_16x16x32_bf16 v[142:145], v[82:85], v[176:179], v[142:145]
	v_mfma_f32_16x16x32_bf16 v[138:141], v[90:93], v[176:179], v[138:141]
	v_mfma_f32_16x16x32_bf16 v[126:129], v[82:85], v[184:187], v[126:129]
	v_mfma_f32_16x16x32_bf16 v[122:125], v[90:93], v[184:187], v[122:125]
	v_mfma_f32_16x16x32_bf16 v[110:113], v[82:85], v[214:217], v[110:113]
	v_mfma_f32_16x16x32_bf16 v[106:109], v[90:93], v[214:217], v[106:109]
	v_mfma_f32_16x16x32_bf16 v[78:81], v[82:85], v[222:225], v[78:81]
	v_mfma_f32_16x16x32_bf16 v[74:77], v[90:93], v[222:225], v[74:77]
	v_mfma_f32_16x16x32_bf16 v[142:145], v[86:89], v[180:183], v[142:145]
	v_mfma_f32_16x16x32_bf16 v[138:141], v[94:97], v[180:183], v[138:141]
	v_mfma_f32_16x16x32_bf16 v[126:129], v[86:89], v[210:213], v[126:129]
	v_mfma_f32_16x16x32_bf16 v[122:125], v[94:97], v[210:213], v[122:125]
	v_mfma_f32_16x16x32_bf16 v[110:113], v[86:89], v[218:221], v[110:113]
	v_mfma_f32_16x16x32_bf16 v[106:109], v[94:97], v[218:221], v[106:109]
	v_mfma_f32_16x16x32_bf16 v[78:81], v[86:89], v[226:229], v[78:81]
	v_mfma_f32_16x16x32_bf16 v[74:77], v[94:97], v[226:229], v[74:77]
	s_barrier
	s_add_i32 s46, 0, 0x1c000
	s_add_i32 s47, s63, s50
	v_add_u32_e32 v0, s46, v206
	v_lshl_add_u64 v[246:247], v[246:247], 0, s[94:95]
	s_mov_b32 m0, s47
	ds_read_b128 v[230:233], v0
	ds_read_b128 v[234:237], v0 offset:1024
	ds_read_b128 v[238:241], v0 offset:2048
	ds_read_b128 v[242:245], v0 offset:3072
	global_load_lds_dwordx4 v[246:247], off
	v_lshl_add_u64 v[246:247], v[248:249], 0, s[94:95]
	s_add_i32 m0, s47, 0x2000
	s_nop 0
	global_load_lds_dwordx4 v[246:247], off
	s_barrier
	s_waitcnt lgkmcnt(0)
	v_mfma_f32_16x16x32_bf16 v[134:137], v[230:233], v[176:179], v[134:137]
	v_mfma_f32_16x16x32_bf16 v[130:133], v[238:241], v[176:179], v[130:133]
	v_mfma_f32_16x16x32_bf16 v[118:121], v[230:233], v[184:187], v[118:121]
	v_mfma_f32_16x16x32_bf16 v[114:117], v[238:241], v[184:187], v[114:117]
	v_mfma_f32_16x16x32_bf16 v[102:105], v[230:233], v[214:217], v[102:105]
	v_mfma_f32_16x16x32_bf16 v[98:101], v[238:241], v[214:217], v[98:101]
	v_mfma_f32_16x16x32_bf16 v[70:73], v[230:233], v[222:225], v[70:73]
	v_mfma_f32_16x16x32_bf16 v[66:69], v[238:241], v[222:225], v[66:69]
	v_mfma_f32_16x16x32_bf16 v[134:137], v[234:237], v[180:183], v[134:137]
	v_mfma_f32_16x16x32_bf16 v[130:133], v[242:245], v[180:183], v[130:133]
	v_mfma_f32_16x16x32_bf16 v[118:121], v[234:237], v[210:213], v[118:121]
	v_mfma_f32_16x16x32_bf16 v[114:117], v[242:245], v[210:213], v[114:117]
	v_mfma_f32_16x16x32_bf16 v[102:105], v[234:237], v[218:221], v[102:105]
	v_mfma_f32_16x16x32_bf16 v[98:101], v[242:245], v[218:221], v[98:101]
	v_mfma_f32_16x16x32_bf16 v[70:73], v[234:237], v[226:229], v[70:73]
	v_mfma_f32_16x16x32_bf16 v[66:69], v[242:245], v[226:229], v[66:69]
	s_barrier
	s_mov_b32 m0, s56
	v_lshl_add_u64 v[246:247], v[250:251], 0, s[94:95]
	ds_read_b128 v[176:179], v208 offset:49152
	ds_read_b128 v[180:183], v208 offset:50176
	ds_read_b128 v[184:187], v208 offset:51200
	ds_read_b128 v[210:213], v208 offset:52224
	ds_read_b128 v[214:217], v208 offset:53248
	ds_read_b128 v[218:221], v208 offset:54272
	ds_read_b128 v[222:225], v208 offset:55296
	ds_read_b128 v[226:229], v208 offset:56320
	global_load_lds_dwordx4 v[246:247], off
	v_lshl_add_u64 v[246:247], v[252:253], 0, s[94:95]
	s_mov_b32 m0, s57
	s_nop 0
	global_load_lds_dwordx4 v[246:247], off
	s_barrier
	s_waitcnt lgkmcnt(0)
	v_mfma_f32_16x16x32_bf16 v[62:65], v[82:85], v[176:179], v[62:65]
	v_mfma_f32_16x16x32_bf16 v[58:61], v[90:93], v[176:179], v[58:61]
	v_mfma_f32_16x16x32_bf16 v[46:49], v[82:85], v[184:187], v[46:49]
	v_mfma_f32_16x16x32_bf16 v[42:45], v[90:93], v[184:187], v[42:45]
	v_mfma_f32_16x16x32_bf16 v[30:33], v[82:85], v[214:217], v[30:33]
	v_mfma_f32_16x16x32_bf16 v[26:29], v[90:93], v[214:217], v[26:29]
	v_mfma_f32_16x16x32_bf16 v[14:17], v[82:85], v[222:225], v[14:17]
	v_mfma_f32_16x16x32_bf16 v[10:13], v[90:93], v[222:225], v[10:13]
	v_mfma_f32_16x16x32_bf16 v[62:65], v[86:89], v[180:183], v[62:65]
	v_mfma_f32_16x16x32_bf16 v[58:61], v[94:97], v[180:183], v[58:61]
	v_mfma_f32_16x16x32_bf16 v[46:49], v[86:89], v[210:213], v[46:49]
	v_mfma_f32_16x16x32_bf16 v[42:45], v[94:97], v[210:213], v[42:45]
	v_mfma_f32_16x16x32_bf16 v[30:33], v[86:89], v[218:221], v[30:33]
	v_mfma_f32_16x16x32_bf16 v[26:29], v[94:97], v[218:221], v[26:29]
	v_mfma_f32_16x16x32_bf16 v[14:17], v[86:89], v[226:229], v[14:17]
	v_mfma_f32_16x16x32_bf16 v[10:13], v[94:97], v[226:229], v[10:13]
	s_barrier
	s_add_u32 s44, s44, 0x40080
	s_addc_u32 s45, s45, 0
	s_add_i32 s46, s46, s50
	v_lshl_add_u64 v[82:83], s[44:45], 0, v[164:165]
	s_mov_b32 m0, s46
	s_nop 0
	global_load_lds_dwordx4 v[82:83], off
	v_lshl_add_u64 v[82:83], s[44:45], 0, v[168:169]
	s_add_i32 m0, s46, 0x2000
	s_nop 0
	global_load_lds_dwordx4 v[82:83], off
	s_waitcnt vmcnt(6)
	s_barrier
	v_mfma_f32_16x16x32_bf16 v[54:57], v[230:233], v[176:179], v[54:57]
	v_mfma_f32_16x16x32_bf16 v[50:53], v[238:241], v[176:179], v[50:53]
	v_mfma_f32_16x16x32_bf16 v[38:41], v[230:233], v[184:187], v[38:41]
	v_mfma_f32_16x16x32_bf16 v[34:37], v[238:241], v[184:187], v[34:37]
	v_mfma_f32_16x16x32_bf16 v[22:25], v[230:233], v[214:217], v[22:25]
	v_mfma_f32_16x16x32_bf16 v[18:21], v[238:241], v[214:217], v[18:21]
	v_mfma_f32_16x16x32_bf16 v[6:9], v[230:233], v[222:225], v[6:9]
	v_mfma_f32_16x16x32_bf16 v[2:5], v[238:241], v[222:225], v[2:5]
	v_mfma_f32_16x16x32_bf16 v[54:57], v[234:237], v[180:183], v[54:57]
	v_mfma_f32_16x16x32_bf16 v[50:53], v[242:245], v[180:183], v[50:53]
	v_mfma_f32_16x16x32_bf16 v[38:41], v[234:237], v[210:213], v[38:41]
	v_mfma_f32_16x16x32_bf16 v[34:37], v[242:245], v[210:213], v[34:37]
	v_mfma_f32_16x16x32_bf16 v[22:25], v[234:237], v[218:221], v[22:25]
	v_mfma_f32_16x16x32_bf16 v[18:21], v[242:245], v[218:221], v[18:21]
	v_mfma_f32_16x16x32_bf16 v[6:9], v[234:237], v[226:229], v[6:9]
	v_mfma_f32_16x16x32_bf16 v[2:5], v[242:245], v[226:229], v[2:5]
	s_barrier
	s_add_i32 s62, s62, 2
	s_add_u32 s60, s60, 0x100
	s_addc_u32 s61, s61, 0
	s_add_u32 s42, s42, 0x100
	s_addc_u32 s43, s43, 0
	s_cmp_gt_u32 s62, 13
	s_cbranch_scc0 .LBB0_360
	s_setprio 0
	v_lshl_or_b32 v180, s0, 8, v207
	v_ashrrev_i32_e32 v181, 31, v180
	v_mov_b32_e32 v86, 0
	v_cndmask_b32_e64 v0, 0, 1, s[26:27]
	v_lshl_add_u64 v[176:177], v[180:181], 2, s[22:23]
	v_cmp_ne_u32_e64 s[0:1], 1, v0
	s_andn2_b64 vcc, exec, s[26:27]
	v_mov_b32_e32 v94, 0
	v_mov_b32_e32 v95, v86
	v_mov_b32_e32 v96, 0
	v_mov_b32_e32 v97, 0
	s_cbranch_vccnz .LBB0_363
	global_load_dwordx4 v[94:97], v[176:177], off

.LBB0_585:
	s_ashr_i32 s9, s8, 31
	v_cmp_lt_i64_e32 vcc, s[16:17], v[160:161]
	s_lshl_b64 s[16:17], s[8:9], 19
	s_add_u32 s16, s12, s16
	s_addc_u32 s17, s13, s17
	s_and_b64 s[18:19], vcc, exec
	s_cselect_b32 s9, s17, s21
	s_cselect_b32 s43, s16, s20
	s_ashr_i32 s1, s0, 31
	s_lshl_b64 s[18:19], s[0:1], 19
	s_add_u32 s18, s27, s18
	s_addc_u32 s19, s28, s19
	s_and_b64 s[24:25], vcc, exec
	s_cselect_b32 s1, s19, s23
	s_cselect_b32 s44, s18, s22
	s_add_u32 s20, s20, 0x40080
	s_addc_u32 s21, s21, 0
	s_add_u32 s45, s22, 0x100
	s_addc_u32 s46, s23, 0
	s_mov_b32 s47, -2
	v_mov_b64_e32 v[82:83], 0
	v_mov_b64_e32 v[84:85], 0
	s_nop 1
	v_mfma_f32_32x32x16_bf16 v[2:17], v[82:85], v[82:85], 0
	v_mov_b64_e32 v[114:115], 0
	v_mov_b64_e32 v[116:117], 0
	v_mov_b64_e32 v[118:119], 0
	v_mov_b64_e32 v[120:121], 0
	v_mov_b64_e32 v[122:123], 0
	v_mfma_f32_32x32x16_bf16 v[18:33], v[82:85], v[82:85], 0
	v_mov_b64_e32 v[124:125], 0
	v_mov_b64_e32 v[126:127], 0
	v_mov_b64_e32 v[128:129], 0
	v_mov_b64_e32 v[98:99], 0
	v_mov_b64_e32 v[100:101], 0
	v_mfma_f32_32x32x16_bf16 v[34:49], v[82:85], v[82:85], 0
	v_mov_b64_e32 v[102:103], 0
	v_mov_b64_e32 v[104:105], 0
	v_mov_b64_e32 v[106:107], 0
	v_mov_b64_e32 v[108:109], 0
	v_mov_b64_e32 v[110:111], 0
	v_mfma_f32_32x32x16_bf16 v[50:65], v[82:85], v[82:85], 0
	v_mov_b64_e32 v[112:113], 0
	v_mov_b64_e32 v[86:87], 0
	v_mov_b64_e32 v[88:89], 0
	v_mov_b64_e32 v[90:91], 0
	v_mov_b64_e32 v[92:93], 0
	v_mfma_f32_32x32x16_bf16 v[66:81], v[82:85], v[82:85], 0
	v_mov_b64_e32 v[94:95], 0
	v_mov_b64_e32 v[96:97], 0
	v_readfirstlane_b32 s98, v204
	s_lshr_b32 s98, s98, 8
	s_cmp_eq_u32 s98, 0
	s_cbranch_scc1 .Lkprio_0
	s_setprio 1
.Lkprio_0:
.LBB0_586:
	s_add_u32 s22, s20, 0xfffc0080
	s_addc_u32 s23, s21, -1
	s_add_i32 s48, 0, 0x10000
	v_add_u32_e32 v140, s48, v143
	ds_read_b128 v[162:165], v140
	ds_read_b128 v[166:169], v140 offset:1024
	ds_read_b128 v[170:173], v140 offset:2048
	ds_read_b128 v[174:177], v140 offset:3072
	s_cmp_eq_u32 s47, 12
	s_cselect_b32 s25, s9, s23
	s_cselect_b32 s24, s43, s22
	s_cselect_b32 s23, s1, s46
	s_cselect_b32 s22, s44, s45
	v_lshl_add_u64 v[140:141], s[20:21], 0, v[136:137]
	s_add_i32 m0, s3, 0xc000
	ds_read_b128 v[178:181], v145
	ds_read_b128 v[182:185], v145 offset:1024
	ds_read_b128 v[206:209], v145 offset:2048
	ds_read_b128 v[210:213], v145 offset:3072
	ds_read_b128 v[214:217], v145 offset:4096
	ds_read_b128 v[218:221], v145 offset:5120
	ds_read_b128 v[222:225], v145 offset:6144
	ds_read_b128 v[226:229], v145 offset:7168
	global_load_lds_dwordx4 v[140:141], off
	v_lshl_add_u64 v[140:141], s[20:21], 0, v[138:139]
	s_add_i32 m0, s3, 0xe000
	s_nop 0
	global_load_lds_dwordx4 v[140:141], off
	s_waitcnt lgkmcnt(8)
	s_barrier
	s_waitcnt lgkmcnt(0)
	v_mfma_f32_16x16x32_bf16 v[122:125], v[162:165], v[178:181], v[122:125]
	v_mfma_f32_16x16x32_bf16 v[114:117], v[170:173], v[178:181], v[114:117]
	v_mfma_f32_16x16x32_bf16 v[106:109], v[162:165], v[206:209], v[106:109]
	v_mfma_f32_16x16x32_bf16 v[98:101], v[170:173], v[206:209], v[98:101]
	v_mfma_f32_16x16x32_bf16 v[90:93], v[162:165], v[214:217], v[90:93]
	v_mfma_f32_16x16x32_bf16 v[82:85], v[170:173], v[214:217], v[82:85]
	v_mfma_f32_16x16x32_bf16 v[74:77], v[162:165], v[222:225], v[74:77]
	v_mfma_f32_16x16x32_bf16 v[66:69], v[170:173], v[222:225], v[66:69]
	v_mfma_f32_16x16x32_bf16 v[122:125], v[166:169], v[182:185], v[122:125]
	v_mfma_f32_16x16x32_bf16 v[114:117], v[174:177], v[182:185], v[114:117]
	v_mfma_f32_16x16x32_bf16 v[106:109], v[166:169], v[210:213], v[106:109]
	v_mfma_f32_16x16x32_bf16 v[98:101], v[174:177], v[210:213], v[98:101]
	v_mfma_f32_16x16x32_bf16 v[90:93], v[166:169], v[218:221], v[90:93]
	v_mfma_f32_16x16x32_bf16 v[82:85], v[174:177], v[218:221], v[82:85]
	v_mfma_f32_16x16x32_bf16 v[74:77], v[166:169], v[226:229], v[74:77]
	v_mfma_f32_16x16x32_bf16 v[66:69], v[174:177], v[226:229], v[66:69]
	s_barrier
	s_add_i32 s50, 0, 0x14000
	v_add_u32_e32 v140, s50, v143
	s_add_i32 s48, s48, s29
	ds_read_b128 v[230:233], v140
	ds_read_b128 v[234:237], v140 offset:1024
	ds_read_b128 v[238:241], v140 offset:2048
	ds_read_b128 v[242:245], v140 offset:3072
	v_lshl_add_u64 v[140:141], s[22:23], 0, v[0:1]
	s_mov_b32 m0, s48
	v_lshl_add_u64 v[186:187], s[22:23], 0, v[130:131]
	global_load_lds_dwordx4 v[140:141], off
	s_add_i32 m0, s48, 0x2000
	s_nop 0
	global_load_lds_dwordx4 v[186:187], off
	s_barrier
	s_waitcnt lgkmcnt(0)
	v_mfma_f32_16x16x32_bf16 v[126:129], v[230:233], v[178:181], v[126:129]
	v_mfma_f32_16x16x32_bf16 v[118:121], v[238:241], v[178:181], v[118:121]
	v_mfma_f32_16x16x32_bf16 v[110:113], v[230:233], v[206:209], v[110:113]
	v_mfma_f32_16x16x32_bf16 v[102:105], v[238:241], v[206:209], v[102:105]
	v_mfma_f32_16x16x32_bf16 v[94:97], v[230:233], v[214:217], v[94:97]
	v_mfma_f32_16x16x32_bf16 v[86:89], v[238:241], v[214:217], v[86:89]
	v_mfma_f32_16x16x32_bf16 v[78:81], v[230:233], v[222:225], v[78:81]
	v_mfma_f32_16x16x32_bf16 v[70:73], v[238:241], v[222:225], v[70:73]
	v_mfma_f32_16x16x32_bf16 v[126:129], v[234:237], v[182:185], v[126:129]
	v_mfma_f32_16x16x32_bf16 v[118:121], v[242:245], v[182:185], v[118:121]
	v_mfma_f32_16x16x32_bf16 v[110:113], v[234:237], v[210:213], v[110:113]
	v_mfma_f32_16x16x32_bf16 v[102:105], v[242:245], v[210:213], v[102:105]
	v_mfma_f32_16x16x32_bf16 v[94:97], v[234:237], v[218:221], v[94:97]
	v_mfma_f32_16x16x32_bf16 v[86:89], v[242:245], v[218:221], v[86:89]
	v_mfma_f32_16x16x32_bf16 v[78:81], v[234:237], v[226:229], v[78:81]
	v_mfma_f32_16x16x32_bf16 v[70:73], v[242:245], v[226:229], v[70:73]
	s_barrier
	s_mov_b32 m0, s3
	v_lshl_add_u64 v[246:247], s[24:25], 0, v[134:135]
	ds_read_b128 v[178:181], v145 offset:16384
	ds_read_b128 v[182:185], v145 offset:17408
	ds_read_b128 v[206:209], v145 offset:18432
	ds_read_b128 v[210:213], v145 offset:19456
	ds_read_b128 v[214:217], v145 offset:20480
	ds_read_b128 v[218:221], v145 offset:21504
	ds_read_b128 v[222:225], v145 offset:22528
	ds_read_b128 v[226:229], v145 offset:23552
	global_load_lds_dwordx4 v[246:247], off
	v_lshl_add_u64 v[248:249], s[24:25], 0, v[132:133]
	s_mov_b32 m0, s31
	s_nop 0
	global_load_lds_dwordx4 v[248:249], off
	s_barrier
	s_waitcnt lgkmcnt(0)
	v_mfma_f32_16x16x32_bf16 v[58:61], v[162:165], v[178:181], v[58:61]
	v_mfma_f32_16x16x32_bf16 v[50:53], v[170:173], v[178:181], v[50:53]
	v_mfma_f32_16x16x32_bf16 v[42:45], v[162:165], v[206:209], v[42:45]
	v_mfma_f32_16x16x32_bf16 v[34:37], v[170:173], v[206:209], v[34:37]
	v_mfma_f32_16x16x32_bf16 v[26:29], v[162:165], v[214:217], v[26:29]
	v_mfma_f32_16x16x32_bf16 v[18:21], v[170:173], v[214:217], v[18:21]
	v_mfma_f32_16x16x32_bf16 v[10:13], v[162:165], v[222:225], v[10:13]
	v_mfma_f32_16x16x32_bf16 v[6:9], v[170:173], v[222:225], v[6:9]
	v_mfma_f32_16x16x32_bf16 v[58:61], v[166:169], v[182:185], v[58:61]
	v_mfma_f32_16x16x32_bf16 v[50:53], v[174:177], v[182:185], v[50:53]
	v_mfma_f32_16x16x32_bf16 v[42:45], v[166:169], v[210:213], v[42:45]
	v_mfma_f32_16x16x32_bf16 v[34:37], v[174:177], v[210:213], v[34:37]
	v_mfma_f32_16x16x32_bf16 v[26:29], v[166:169], v[218:221], v[26:29]
	v_mfma_f32_16x16x32_bf16 v[18:21], v[174:177], v[218:221], v[18:21]
	v_mfma_f32_16x16x32_bf16 v[10:13], v[166:169], v[226:229], v[10:13]
	v_mfma_f32_16x16x32_bf16 v[6:9], v[174:177], v[226:229], v[6:9]
	s_barrier
	s_add_u32 s48, s22, 0x40000
	s_addc_u32 s49, s23, 0
	s_add_i32 s50, s50, s29
	v_lshl_add_u64 v[162:163], s[48:49], 0, v[0:1]
	s_mov_b32 m0, s50
	s_nop 0
	global_load_lds_dwordx4 v[162:163], off
	v_lshl_add_u64 v[162:163], s[48:49], 0, v[130:131]
	s_add_i32 m0, s50, 0x2000
	s_nop 0
	global_load_lds_dwordx4 v[162:163], off
	s_waitcnt vmcnt(6)
	s_barrier
	v_mfma_f32_16x16x32_bf16 v[62:65], v[230:233], v[178:181], v[62:65]
	v_mfma_f32_16x16x32_bf16 v[54:57], v[238:241], v[178:181], v[54:57]
	v_mfma_f32_16x16x32_bf16 v[46:49], v[230:233], v[206:209], v[46:49]
	v_mfma_f32_16x16x32_bf16 v[38:41], v[238:241], v[206:209], v[38:41]
	v_mfma_f32_16x16x32_bf16 v[30:33], v[230:233], v[214:217], v[30:33]
	v_mfma_f32_16x16x32_bf16 v[22:25], v[238:241], v[214:217], v[22:25]
	v_mfma_f32_16x16x32_bf16 v[14:17], v[230:233], v[222:225], v[14:17]
	v_mfma_f32_16x16x32_bf16 v[2:5], v[238:241], v[222:225], v[2:5]
	v_mfma_f32_16x16x32_bf16 v[62:65], v[234:237], v[182:185], v[62:65]
	v_mfma_f32_16x16x32_bf16 v[54:57], v[242:245], v[182:185], v[54:57]
	v_mfma_f32_16x16x32_bf16 v[46:49], v[234:237], v[210:213], v[46:49]
	v_mfma_f32_16x16x32_bf16 v[38:41], v[242:245], v[210:213], v[38:41]
	v_mfma_f32_16x16x32_bf16 v[30:33], v[234:237], v[218:221], v[30:33]
	v_mfma_f32_16x16x32_bf16 v[22:25], v[242:245], v[218:221], v[22:25]
	v_mfma_f32_16x16x32_bf16 v[14:17], v[234:237], v[226:229], v[14:17]
	v_mfma_f32_16x16x32_bf16 v[2:5], v[242:245], v[226:229], v[2:5]
	s_barrier
	s_add_i32 s48, 0, 0x18000
	v_add_u32_e32 v174, s48, v143
	ds_read_b128 v[162:165], v174
	ds_read_b128 v[166:169], v174 offset:1024
	ds_read_b128 v[170:173], v174 offset:2048
	ds_read_b128 v[174:177], v174 offset:3072
	s_add_u32 s24, s24, 0x40000
	s_addc_u32 s25, s25, 0
	s_mov_b32 m0, s34
	v_lshl_add_u64 v[230:231], s[24:25], 0, v[134:135]
	ds_read_b128 v[178:181], v145 offset:32768
	ds_read_b128 v[182:185], v145 offset:33792
	ds_read_b128 v[206:209], v145 offset:34816
	ds_read_b128 v[210:213], v145 offset:35840
	ds_read_b128 v[214:217], v145 offset:36864
	ds_read_b128 v[218:221], v145 offset:37888
	ds_read_b128 v[222:225], v145 offset:38912
	ds_read_b128 v[226:229], v145 offset:39936
	global_load_lds_dwordx4 v[230:231], off
	v_lshl_add_u64 v[230:231], s[24:25], 0, v[132:133]
	s_mov_b32 m0, s35
	s_nop 0
	global_load_lds_dwordx4 v[230:231], off
	s_waitcnt lgkmcnt(8)
	s_barrier
	s_waitcnt lgkmcnt(0)
	v_mfma_f32_16x16x32_bf16 v[122:125], v[162:165], v[178:181], v[122:125]
	v_mfma_f32_16x16x32_bf16 v[114:117], v[170:173], v[178:181], v[114:117]
	v_mfma_f32_16x16x32_bf16 v[106:109], v[162:165], v[206:209], v[106:109]
	v_mfma_f32_16x16x32_bf16 v[98:101], v[170:173], v[206:209], v[98:101]
	v_mfma_f32_16x16x32_bf16 v[90:93], v[162:165], v[214:217], v[90:93]
	v_mfma_f32_16x16x32_bf16 v[82:85], v[170:173], v[214:217], v[82:85]
	v_mfma_f32_16x16x32_bf16 v[74:77], v[162:165], v[222:225], v[74:77]
	v_mfma_f32_16x16x32_bf16 v[66:69], v[170:173], v[222:225], v[66:69]
	v_mfma_f32_16x16x32_bf16 v[122:125], v[166:169], v[182:185], v[122:125]
	v_mfma_f32_16x16x32_bf16 v[114:117], v[174:177], v[182:185], v[114:117]
	v_mfma_f32_16x16x32_bf16 v[106:109], v[166:169], v[210:213], v[106:109]
	v_mfma_f32_16x16x32_bf16 v[98:101], v[174:177], v[210:213], v[98:101]
	v_mfma_f32_16x16x32_bf16 v[90:93], v[166:169], v[218:221], v[90:93]
	v_mfma_f32_16x16x32_bf16 v[82:85], v[174:177], v[218:221], v[82:85]
	v_mfma_f32_16x16x32_bf16 v[74:77], v[166:169], v[226:229], v[74:77]
	v_mfma_f32_16x16x32_bf16 v[66:69], v[174:177], v[226:229], v[66:69]
	s_barrier
	s_add_i32 s24, 0, 0x1c000
	s_add_i32 s25, s48, s29
	v_add_u32_e32 v205, s24, v143
	v_lshl_add_u64 v[140:141], v[140:141], 0, s[94:95]
	s_mov_b32 m0, s25
	ds_read_b128 v[230:233], v205
	ds_read_b128 v[234:237], v205 offset:1024
	ds_read_b128 v[238:241], v205 offset:2048
	ds_read_b128 v[242:245], v205 offset:3072
	global_load_lds_dwordx4 v[140:141], off
	v_lshl_add_u64 v[140:141], v[186:187], 0, s[94:95]
	s_add_i32 m0, s25, 0x2000
	s_nop 0
	global_load_lds_dwordx4 v[140:141], off
	s_barrier
	s_waitcnt lgkmcnt(0)
	v_mfma_f32_16x16x32_bf16 v[126:129], v[230:233], v[178:181], v[126:129]
	v_mfma_f32_16x16x32_bf16 v[118:121], v[238:241], v[178:181], v[118:121]
	v_mfma_f32_16x16x32_bf16 v[110:113], v[230:233], v[206:209], v[110:113]
	v_mfma_f32_16x16x32_bf16 v[102:105], v[238:241], v[206:209], v[102:105]
	v_mfma_f32_16x16x32_bf16 v[94:97], v[230:233], v[214:217], v[94:97]
	v_mfma_f32_16x16x32_bf16 v[86:89], v[238:241], v[214:217], v[86:89]
	v_mfma_f32_16x16x32_bf16 v[78:81], v[230:233], v[222:225], v[78:81]
	v_mfma_f32_16x16x32_bf16 v[70:73], v[238:241], v[222:225], v[70:73]
	v_mfma_f32_16x16x32_bf16 v[126:129], v[234:237], v[182:185], v[126:129]
	v_mfma_f32_16x16x32_bf16 v[118:121], v[242:245], v[182:185], v[118:121]
	v_mfma_f32_16x16x32_bf16 v[110:113], v[234:237], v[210:213], v[110:113]
	v_mfma_f32_16x16x32_bf16 v[102:105], v[242:245], v[210:213], v[102:105]
	v_mfma_f32_16x16x32_bf16 v[94:97], v[234:237], v[218:221], v[94:97]
	v_mfma_f32_16x16x32_bf16 v[86:89], v[242:245], v[218:221], v[86:89]
	v_mfma_f32_16x16x32_bf16 v[78:81], v[234:237], v[226:229], v[78:81]
	v_mfma_f32_16x16x32_bf16 v[70:73], v[242:245], v[226:229], v[70:73]
	s_barrier
	s_mov_b32 m0, s37
	v_lshl_add_u64 v[140:141], v[246:247], 0, s[94:95]
	ds_read_b128 v[178:181], v145 offset:49152
	ds_read_b128 v[182:185], v145 offset:50176
	ds_read_b128 v[206:209], v145 offset:51200
	ds_read_b128 v[210:213], v145 offset:52224
	ds_read_b128 v[214:217], v145 offset:53248
	ds_read_b128 v[218:221], v145 offset:54272
	ds_read_b128 v[222:225], v145 offset:55296
	ds_read_b128 v[226:229], v145 offset:56320
	global_load_lds_dwordx4 v[140:141], off
	v_lshl_add_u64 v[140:141], v[248:249], 0, s[94:95]
	s_mov_b32 m0, s40
	s_nop 0
	global_load_lds_dwordx4 v[140:141], off
	s_barrier
	s_waitcnt lgkmcnt(0)
	v_mfma_f32_16x16x32_bf16 v[58:61], v[162:165], v[178:181], v[58:61]
	v_mfma_f32_16x16x32_bf16 v[50:53], v[170:173], v[178:181], v[50:53]
	v_mfma_f32_16x16x32_bf16 v[42:45], v[162:165], v[206:209], v[42:45]
	v_mfma_f32_16x16x32_bf16 v[34:37], v[170:173], v[206:209], v[34:37]
	v_mfma_f32_16x16x32_bf16 v[26:29], v[162:165], v[214:217], v[26:29]
	v_mfma_f32_16x16x32_bf16 v[18:21], v[170:173], v[214:217], v[18:21]
	v_mfma_f32_16x16x32_bf16 v[10:13], v[162:165], v[222:225], v[10:13]
	v_mfma_f32_16x16x32_bf16 v[6:9], v[170:173], v[222:225], v[6:9]
	v_mfma_f32_16x16x32_bf16 v[58:61], v[166:169], v[182:185], v[58:61]
	v_mfma_f32_16x16x32_bf16 v[50:53], v[174:177], v[182:185], v[50:53]
	v_mfma_f32_16x16x32_bf16 v[42:45], v[166:169], v[210:213], v[42:45]
	v_mfma_f32_16x16x32_bf16 v[34:37], v[174:177], v[210:213], v[34:37]
	v_mfma_f32_16x16x32_bf16 v[26:29], v[166:169], v[218:221], v[26:29]
	v_mfma_f32_16x16x32_bf16 v[18:21], v[174:177], v[218:221], v[18:21]
	v_mfma_f32_16x16x32_bf16 v[10:13], v[166:169], v[226:229], v[10:13]
	v_mfma_f32_16x16x32_bf16 v[6:9], v[174:177], v[226:229], v[6:9]
	s_barrier
	s_add_u32 s22, s22, 0x40080
	s_addc_u32 s23, s23, 0
	s_add_i32 s24, s24, s29
	v_lshl_add_u64 v[140:141], s[22:23], 0, v[0:1]
	s_mov_b32 m0, s24
	s_nop 0
	global_load_lds_dwordx4 v[140:141], off
	v_lshl_add_u64 v[140:141], s[22:23], 0, v[130:131]
	s_add_i32 m0, s24, 0x2000
	s_nop 0
	global_load_lds_dwordx4 v[140:141], off
	s_waitcnt vmcnt(6)
	s_barrier
	v_mfma_f32_16x16x32_bf16 v[62:65], v[230:233], v[178:181], v[62:65]
	v_mfma_f32_16x16x32_bf16 v[54:57], v[238:241], v[178:181], v[54:57]
	v_mfma_f32_16x16x32_bf16 v[46:49], v[230:233], v[206:209], v[46:49]
	v_mfma_f32_16x16x32_bf16 v[38:41], v[238:241], v[206:209], v[38:41]
	v_mfma_f32_16x16x32_bf16 v[30:33], v[230:233], v[214:217], v[30:33]
	v_mfma_f32_16x16x32_bf16 v[22:25], v[238:241], v[214:217], v[22:25]
	v_mfma_f32_16x16x32_bf16 v[14:17], v[230:233], v[222:225], v[14:17]
	v_mfma_f32_16x16x32_bf16 v[2:5], v[238:241], v[222:225], v[2:5]
	v_mfma_f32_16x16x32_bf16 v[62:65], v[234:237], v[182:185], v[62:65]
	v_mfma_f32_16x16x32_bf16 v[54:57], v[242:245], v[182:185], v[54:57]
	v_mfma_f32_16x16x32_bf16 v[46:49], v[234:237], v[210:213], v[46:49]
	v_mfma_f32_16x16x32_bf16 v[38:41], v[242:245], v[210:213], v[38:41]
	v_mfma_f32_16x16x32_bf16 v[30:33], v[234:237], v[218:221], v[30:33]
	v_mfma_f32_16x16x32_bf16 v[22:25], v[242:245], v[218:221], v[22:25]
	v_mfma_f32_16x16x32_bf16 v[14:17], v[234:237], v[226:229], v[14:17]
	v_mfma_f32_16x16x32_bf16 v[2:5], v[242:245], v[226:229], v[2:5]
	s_barrier
	s_add_i32 s47, s47, 2
	s_add_u32 s20, s20, 0x100
	s_addc_u32 s21, s21, 0
	s_add_u32 s45, s45, 0x100
	s_addc_u32 s46, s46, 0
	s_cmp_gt_u32 s47, 13
	s_cbranch_scc0 .LBB0_586
	s_setprio 0
	v_pk_mul_f32 v[164:165], v[122:123], s[4:5] op_sel_hi:[1,0]
	v_pk_mul_f32 v[122:123], v[122:123], v[126:127]
	v_pk_mul_f32 v[126:127], v[114:115], s[4:5] op_sel_hi:[1,0]
	v_pk_mul_f32 v[114:115], v[114:115], v[118:119]
	v_exp_f32_e32 v126, v126
	v_exp_f32_e32 v127, v127
	v_pk_mul_f32 v[128:129], v[124:125], v[128:129]
	v_pk_mul_f32 v[124:125], v[124:125], s[4:5] op_sel_hi:[1,0]
	v_exp_f32_e32 v164, v164
	v_pk_add_f32 v[126:127], v[126:127], 1.0 op_sel_hi:[1,0]
	v_exp_f32_e32 v165, v165
	v_rcp_f32_e32 v126, v126
	v_rcp_f32_e32 v127, v127
	v_exp_f32_e32 v124, v124
	v_exp_f32_e32 v125, v125
	v_pk_add_f32 v[164:165], v[164:165], 1.0 op_sel_hi:[1,0]
	v_pk_mul_f32 v[118:119], v[126:127], v[114:115]
	v_pk_mul_f32 v[114:115], v[116:117], s[4:5] op_sel_hi:[1,0]
	v_pk_add_f32 v[124:125], v[124:125], 1.0 op_sel_hi:[1,0]
	v_exp_f32_e32 v114, v114
	v_exp_f32_e32 v115, v115
	v_rcp_f32_e32 v164, v164
	v_rcp_f32_e32 v165, v165
	v_rcp_f32_e32 v124, v124
	v_pk_add_f32 v[114:115], v[114:115], 1.0 op_sel_hi:[1,0]
	v_rcp_f32_e32 v125, v125
	v_rcp_f32_e32 v114, v114
	v_rcp_f32_e32 v115, v115
	v_lshl_or_b32 v140, s42, 7, v144
	v_ashrrev_i32_e32 v141, 31, v140
	v_lshl_add_u32 v162, s2, 8, v142
	v_lshl_add_u64 v[140:141], v[140:141], 1, s[14:15]
	v_pk_mul_f32 v[120:121], v[116:117], v[120:121]
	v_pk_mul_f32 v[122:123], v[164:165], v[122:123]
	v_pk_mul_f32 v[124:125], v[124:125], v[128:129]
	v_pk_mul_f32 v[120:121], v[114:115], v[120:121]
	v_mad_i64_i32 v[126:127], s[20:21], v162, s91, v[140:141]
	v_cvt_pk_bf16_f32 v114, v122, v123
	v_cvt_pk_bf16_f32 v115, v124, v125
	v_cvt_pk_bf16_f32 v116, v118, v119
	v_cvt_pk_bf16_f32 v117, v120, v121
	global_store_dwordx4 v[126:127], v[114:117], off
	v_pk_mul_f32 v[112:113], v[108:109], v[112:113]
	v_pk_mul_f32 v[108:109], v[108:109], s[4:5] op_sel_hi:[1,0]
	v_pk_mul_f32 v[114:115], v[106:107], s[4:5] op_sel_hi:[1,0]
	v_pk_mul_f32 v[106:107], v[106:107], v[110:111]
	v_pk_mul_f32 v[110:111], v[98:99], s[4:5] op_sel_hi:[1,0]
	v_pk_mul_f32 v[98:99], v[98:99], v[102:103]
	v_exp_f32_e32 v110, v110
	v_exp_f32_e32 v111, v111
	v_exp_f32_e32 v114, v114
	v_exp_f32_e32 v115, v115
	v_exp_f32_e32 v108, v108
	v_pk_add_f32 v[110:111], v[110:111], 1.0 op_sel_hi:[1,0]
	v_exp_f32_e32 v109, v109
	v_rcp_f32_e32 v110, v110
	v_rcp_f32_e32 v111, v111
	v_pk_add_f32 v[114:115], v[114:115], 1.0 op_sel_hi:[1,0]
	v_pk_add_f32 v[108:109], v[108:109], 1.0 op_sel_hi:[1,0]
	v_rcp_f32_e32 v114, v114
	v_pk_mul_f32 v[102:103], v[110:111], v[98:99]
	v_pk_mul_f32 v[98:99], v[100:101], s[4:5] op_sel_hi:[1,0]
	v_rcp_f32_e32 v115, v115
	v_exp_f32_e32 v98, v98
	v_exp_f32_e32 v99, v99
	v_rcp_f32_e32 v108, v108
	v_rcp_f32_e32 v109, v109
	v_or_b32_e32 v116, 16, v162
	v_pk_add_f32 v[98:99], v[98:99], 1.0 op_sel_hi:[1,0]
	v_pk_mul_f32 v[104:105], v[100:101], v[104:105]
	v_rcp_f32_e32 v98, v98
	v_rcp_f32_e32 v99, v99
	v_pk_mul_f32 v[106:107], v[114:115], v[106:107]
	v_pk_mul_f32 v[108:109], v[108:109], v[112:113]
	v_mad_i64_i32 v[110:111], s[20:21], v116, s91, v[140:141]
	v_pk_mul_f32 v[104:105], v[98:99], v[104:105]
	v_cvt_pk_bf16_f32 v98, v106, v107
	v_cvt_pk_bf16_f32 v99, v108, v109
	v_cvt_pk_bf16_f32 v100, v102, v103
	v_pk_mul_f32 v[96:97], v[92:93], v[96:97]
	v_cvt_pk_bf16_f32 v101, v104, v105
	global_store_dwordx4 v[110:111], v[98:101], off
	v_pk_mul_f32 v[92:93], v[92:93], s[4:5] op_sel_hi:[1,0]
	v_pk_mul_f32 v[88:89], v[84:85], v[88:89]
	v_pk_mul_f32 v[98:99], v[90:91], s[4:5] op_sel_hi:[1,0]
	v_pk_mul_f32 v[90:91], v[90:91], v[94:95]
	v_pk_mul_f32 v[94:95], v[82:83], s[4:5] op_sel_hi:[1,0]
	v_pk_mul_f32 v[82:83], v[82:83], v[86:87]
	v_exp_f32_e32 v94, v94
	v_exp_f32_e32 v95, v95
	v_exp_f32_e32 v98, v98
	v_exp_f32_e32 v99, v99
	v_exp_f32_e32 v92, v92
	v_pk_add_f32 v[94:95], v[94:95], 1.0 op_sel_hi:[1,0]
	v_exp_f32_e32 v93, v93
	v_rcp_f32_e32 v94, v94
	v_rcp_f32_e32 v95, v95
	v_pk_add_f32 v[98:99], v[98:99], 1.0 op_sel_hi:[1,0]
	v_pk_add_f32 v[92:93], v[92:93], 1.0 op_sel_hi:[1,0]
	v_rcp_f32_e32 v98, v98
	v_pk_mul_f32 v[86:87], v[94:95], v[82:83]
	v_pk_mul_f32 v[82:83], v[84:85], s[4:5] op_sel_hi:[1,0]
	v_rcp_f32_e32 v99, v99
	v_exp_f32_e32 v82, v82
	v_exp_f32_e32 v83, v83
	v_rcp_f32_e32 v92, v92
	v_rcp_f32_e32 v93, v93
	v_or_b32_e32 v100, 32, v162
	v_pk_add_f32 v[82:83], v[82:83], 1.0 op_sel_hi:[1,0]
	v_pk_mul_f32 v[90:91], v[98:99], v[90:91]
	v_rcp_f32_e32 v82, v82
	v_rcp_f32_e32 v83, v83
	v_pk_mul_f32 v[92:93], v[92:93], v[96:97]
	v_mad_i64_i32 v[94:95], s[20:21], v100, s91, v[140:141]
	v_pk_mul_f32 v[88:89], v[82:83], v[88:89]
	v_cvt_pk_bf16_f32 v82, v90, v91
	v_cvt_pk_bf16_f32 v83, v92, v93
	v_cvt_pk_bf16_f32 v84, v86, v87
	v_pk_mul_f32 v[80:81], v[76:77], v[80:81]
	v_cvt_pk_bf16_f32 v85, v88, v89
	global_store_dwordx4 v[94:95], v[82:85], off
	v_pk_mul_f32 v[76:77], v[76:77], s[4:5] op_sel_hi:[1,0]
	v_pk_mul_f32 v[72:73], v[68:69], v[72:73]
	v_pk_mul_f32 v[82:83], v[74:75], s[4:5] op_sel_hi:[1,0]
	v_pk_mul_f32 v[74:75], v[74:75], v[78:79]
	v_pk_mul_f32 v[78:79], v[66:67], s[4:5] op_sel_hi:[1,0]
	v_pk_mul_f32 v[66:67], v[66:67], v[70:71]
	v_exp_f32_e32 v78, v78
	v_exp_f32_e32 v79, v79
	v_exp_f32_e32 v82, v82
	v_exp_f32_e32 v83, v83
	v_exp_f32_e32 v76, v76
	v_pk_add_f32 v[78:79], v[78:79], 1.0 op_sel_hi:[1,0]
	v_exp_f32_e32 v77, v77
	v_rcp_f32_e32 v78, v78
	v_rcp_f32_e32 v79, v79
	v_pk_add_f32 v[82:83], v[82:83], 1.0 op_sel_hi:[1,0]
	v_pk_add_f32 v[76:77], v[76:77], 1.0 op_sel_hi:[1,0]
	v_rcp_f32_e32 v82, v82
	v_pk_mul_f32 v[70:71], v[78:79], v[66:67]
	v_pk_mul_f32 v[66:67], v[68:69], s[4:5] op_sel_hi:[1,0]
	v_rcp_f32_e32 v83, v83
	v_exp_f32_e32 v66, v66
	v_exp_f32_e32 v67, v67
	v_rcp_f32_e32 v76, v76
	v_rcp_f32_e32 v77, v77
	v_or_b32_e32 v84, 48, v162
	v_pk_add_f32 v[66:67], v[66:67], 1.0 op_sel_hi:[1,0]
	v_pk_mul_f32 v[74:75], v[82:83], v[74:75]
	v_rcp_f32_e32 v66, v66
	v_rcp_f32_e32 v67, v67
	v_pk_mul_f32 v[76:77], v[76:77], v[80:81]
	v_mad_i64_i32 v[78:79], s[20:21], v84, s91, v[140:141]
	v_pk_mul_f32 v[72:73], v[66:67], v[72:73]
	v_cvt_pk_bf16_f32 v66, v74, v75
	v_cvt_pk_bf16_f32 v67, v76, v77
	v_cvt_pk_bf16_f32 v68, v70, v71
	v_pk_mul_f32 v[64:65], v[60:61], v[64:65]
	v_cvt_pk_bf16_f32 v69, v72, v73
	global_store_dwordx4 v[78:79], v[66:69], off
	v_pk_mul_f32 v[60:61], v[60:61], s[4:5] op_sel_hi:[1,0]
	v_pk_mul_f32 v[56:57], v[52:53], v[56:57]
	v_pk_mul_f32 v[66:67], v[58:59], s[4:5] op_sel_hi:[1,0]
	v_pk_mul_f32 v[58:59], v[58:59], v[62:63]
	v_pk_mul_f32 v[62:63], v[50:51], s[4:5] op_sel_hi:[1,0]
	v_pk_mul_f32 v[50:51], v[50:51], v[54:55]
	v_exp_f32_e32 v62, v62
	v_exp_f32_e32 v63, v63
	v_exp_f32_e32 v66, v66
	v_exp_f32_e32 v67, v67
	v_exp_f32_e32 v60, v60
	v_pk_add_f32 v[62:63], v[62:63], 1.0 op_sel_hi:[1,0]
	v_exp_f32_e32 v61, v61
	v_rcp_f32_e32 v62, v62
	v_rcp_f32_e32 v63, v63
	v_pk_add_f32 v[66:67], v[66:67], 1.0 op_sel_hi:[1,0]
	v_pk_add_f32 v[60:61], v[60:61], 1.0 op_sel_hi:[1,0]
	v_rcp_f32_e32 v66, v66
	v_pk_mul_f32 v[54:55], v[62:63], v[50:51]
	v_pk_mul_f32 v[50:51], v[52:53], s[4:5] op_sel_hi:[1,0]
	v_rcp_f32_e32 v67, v67
	v_exp_f32_e32 v50, v50
	v_exp_f32_e32 v51, v51
	v_rcp_f32_e32 v60, v60
	v_rcp_f32_e32 v61, v61
	v_add_u32_e32 v68, 0x80, v162
	v_pk_add_f32 v[50:51], v[50:51], 1.0 op_sel_hi:[1,0]
	v_pk_mul_f32 v[58:59], v[66:67], v[58:59]
	v_rcp_f32_e32 v50, v50
	v_rcp_f32_e32 v51, v51
	v_pk_mul_f32 v[60:61], v[60:61], v[64:65]
	v_mad_i64_i32 v[62:63], s[20:21], v68, s91, v[140:141]
	v_pk_mul_f32 v[56:57], v[50:51], v[56:57]
	v_cvt_pk_bf16_f32 v50, v58, v59
	v_cvt_pk_bf16_f32 v51, v60, v61
	v_cvt_pk_bf16_f32 v52, v54, v55
	v_pk_mul_f32 v[48:49], v[44:45], v[48:49]
	v_cvt_pk_bf16_f32 v53, v56, v57
	global_store_dwordx4 v[62:63], v[50:53], off
	v_pk_mul_f32 v[44:45], v[44:45], s[4:5] op_sel_hi:[1,0]
	v_pk_mul_f32 v[40:41], v[36:37], v[40:41]
	v_pk_mul_f32 v[50:51], v[42:43], s[4:5] op_sel_hi:[1,0]
	v_pk_mul_f32 v[42:43], v[42:43], v[46:47]
	v_pk_mul_f32 v[46:47], v[34:35], s[4:5] op_sel_hi:[1,0]
	v_pk_mul_f32 v[34:35], v[34:35], v[38:39]
	v_exp_f32_e32 v46, v46
	v_exp_f32_e32 v47, v47
	v_exp_f32_e32 v50, v50
	v_exp_f32_e32 v51, v51
	v_exp_f32_e32 v44, v44
	v_pk_add_f32 v[46:47], v[46:47], 1.0 op_sel_hi:[1,0]
	v_exp_f32_e32 v45, v45
	v_rcp_f32_e32 v46, v46
	v_rcp_f32_e32 v47, v47
	v_pk_add_f32 v[50:51], v[50:51], 1.0 op_sel_hi:[1,0]
	v_pk_add_f32 v[44:45], v[44:45], 1.0 op_sel_hi:[1,0]
	v_rcp_f32_e32 v50, v50
	v_pk_mul_f32 v[38:39], v[46:47], v[34:35]
	v_pk_mul_f32 v[34:35], v[36:37], s[4:5] op_sel_hi:[1,0]
	v_rcp_f32_e32 v51, v51
	v_exp_f32_e32 v34, v34
	v_exp_f32_e32 v35, v35
	v_rcp_f32_e32 v44, v44
	v_rcp_f32_e32 v45, v45
	v_add_u32_e32 v52, 0x90, v162
	v_pk_add_f32 v[34:35], v[34:35], 1.0 op_sel_hi:[1,0]
	v_pk_mul_f32 v[42:43], v[50:51], v[42:43]
	v_rcp_f32_e32 v34, v34
	v_rcp_f32_e32 v35, v35
	v_pk_mul_f32 v[44:45], v[44:45], v[48:49]
	v_mad_i64_i32 v[46:47], s[20:21], v52, s91, v[140:141]
	v_pk_mul_f32 v[40:41], v[34:35], v[40:41]
	v_cvt_pk_bf16_f32 v34, v42, v43
	v_cvt_pk_bf16_f32 v35, v44, v45
	v_cvt_pk_bf16_f32 v36, v38, v39
	v_pk_mul_f32 v[32:33], v[28:29], v[32:33]
	v_cvt_pk_bf16_f32 v37, v40, v41
	global_store_dwordx4 v[46:47], v[34:37], off
	v_pk_mul_f32 v[28:29], v[28:29], s[4:5] op_sel_hi:[1,0]
	v_pk_mul_f32 v[24:25], v[20:21], v[24:25]
	v_pk_mul_f32 v[34:35], v[26:27], s[4:5] op_sel_hi:[1,0]
	v_pk_mul_f32 v[26:27], v[26:27], v[30:31]
	v_pk_mul_f32 v[30:31], v[18:19], s[4:5] op_sel_hi:[1,0]
	v_pk_mul_f32 v[18:19], v[18:19], v[22:23]
	v_exp_f32_e32 v30, v30
	v_exp_f32_e32 v31, v31
	v_exp_f32_e32 v34, v34
	v_exp_f32_e32 v35, v35
	v_exp_f32_e32 v28, v28
	v_pk_add_f32 v[30:31], v[30:31], 1.0 op_sel_hi:[1,0]
	v_exp_f32_e32 v29, v29
	v_rcp_f32_e32 v30, v30
	v_rcp_f32_e32 v31, v31
	v_pk_add_f32 v[34:35], v[34:35], 1.0 op_sel_hi:[1,0]
	v_pk_add_f32 v[28:29], v[28:29], 1.0 op_sel_hi:[1,0]
	v_rcp_f32_e32 v34, v34
	v_pk_mul_f32 v[22:23], v[30:31], v[18:19]
	v_pk_mul_f32 v[18:19], v[20:21], s[4:5] op_sel_hi:[1,0]
	v_rcp_f32_e32 v35, v35
	v_exp_f32_e32 v18, v18
	v_exp_f32_e32 v19, v19
	v_rcp_f32_e32 v28, v28
	v_rcp_f32_e32 v29, v29
	v_add_u32_e32 v36, 0xa0, v162
	v_pk_add_f32 v[18:19], v[18:19], 1.0 op_sel_hi:[1,0]
	v_pk_mul_f32 v[26:27], v[34:35], v[26:27]
	v_rcp_f32_e32 v18, v18
	v_rcp_f32_e32 v19, v19
	v_pk_mul_f32 v[28:29], v[28:29], v[32:33]
	v_mad_i64_i32 v[30:31], s[20:21], v36, s91, v[140:141]
	v_pk_mul_f32 v[24:25], v[18:19], v[24:25]
	v_cvt_pk_bf16_f32 v18, v26, v27
	v_cvt_pk_bf16_f32 v19, v28, v29
	v_cvt_pk_bf16_f32 v20, v22, v23
	v_pk_mul_f32 v[2:3], v[6:7], v[2:3]
	v_cvt_pk_bf16_f32 v21, v24, v25
	global_store_dwordx4 v[30:31], v[18:21], off
	v_pk_mul_f32 v[16:17], v[12:13], v[16:17]
	v_pk_mul_f32 v[12:13], v[12:13], s[4:5] op_sel_hi:[1,0]
	v_pk_mul_f32 v[18:19], v[10:11], s[4:5] op_sel_hi:[1,0]
	v_pk_mul_f32 v[10:11], v[10:11], v[14:15]
	v_pk_mul_f32 v[14:15], v[6:7], s[4:5] op_sel_hi:[1,0]
	v_exp_f32_e32 v18, v18
	v_exp_f32_e32 v14, v14
	v_exp_f32_e32 v15, v15
	v_exp_f32_e32 v19, v19
	v_exp_f32_e32 v12, v12
	v_exp_f32_e32 v13, v13
	v_pk_add_f32 v[14:15], v[14:15], 1.0 op_sel_hi:[1,0]
	v_pk_add_f32 v[18:19], v[18:19], 1.0 op_sel_hi:[1,0]
	v_rcp_f32_e32 v14, v14
	v_rcp_f32_e32 v15, v15
	v_pk_add_f32 v[12:13], v[12:13], 1.0 op_sel_hi:[1,0]
	v_rcp_f32_e32 v18, v18
	v_rcp_f32_e32 v19, v19
	v_pk_mul_f32 v[6:7], v[14:15], v[2:3]
	v_pk_mul_f32 v[2:3], v[8:9], s[4:5] op_sel_hi:[1,0]
	v_rcp_f32_e32 v12, v12
	v_exp_f32_e32 v2, v2
	v_exp_f32_e32 v3, v3
	v_rcp_f32_e32 v13, v13
	v_add_u32_e32 v20, 0xb0, v162
	v_mad_i64_i32 v[14:15], s[20:21], v20, s91, v[140:141]
	v_pk_add_f32 v[2:3], v[2:3], 1.0 op_sel_hi:[1,0]
	v_pk_mul_f32 v[4:5], v[8:9], v[4:5]
	v_rcp_f32_e32 v2, v2
	v_rcp_f32_e32 v3, v3
	s_and_b64 vcc, exec, s[38:39]
	s_mov_b32 s42, s0
	s_mov_b32 s2, s8
	s_mov_b64 s[22:23], s[18:19]
	s_mov_b64 s[20:21], s[16:17]
	v_pk_mul_f32 v[10:11], v[18:19], v[10:11]
	v_pk_mul_f32 v[12:13], v[12:13], v[16:17]
	v_pk_mul_f32 v[8:9], v[2:3], v[4:5]
	v_cvt_pk_bf16_f32 v2, v10, v11
	v_cvt_pk_bf16_f32 v3, v12, v13
	v_cvt_pk_bf16_f32 v4, v6, v7
	s_nop 0
	v_cvt_pk_bf16_f32 v5, v8, v9
	global_store_dwordx4 v[14:15], v[2:5], off
	s_cbranch_vccz .LBB0_579
	s_waitcnt vmcnt(0)
	s_cmpk_gt_u32 s26, 0xff
	s_cbranch_scc1 .LBB0_590
	s_barrier
